# rsq+Newton replaces IEEE 1/sqrt expansion in P1/P3/P8 epilogues too; redundant max canonicalization after permlane removed in attention loops
# speedup vs baseline: 1.0160x; 1.0056x over previous
.LBB0_180:
	s_lshl_b32 s8, s8, 8
	s_add_i32 s8, s8, s72
	v_or_b32_e32 v176, s8, v147
	v_ashrrev_i32_e32 v177, 31, v176
	v_lshlrev_b64 v[128:129], 6, v[176:177]
	v_lshl_add_u64 v[130:131], s[26:27], 0, v[128:129]
	global_load_dword v130, v[130:131], off
	s_cmp_gt_i32 s92, 2
	s_cselect_b64 s[10:11], -1, 0
	s_cmp_eq_u32 s92, 2
	s_cselect_b64 s[20:21], -1, 0
	s_bfe_u32 s30, s8, 0x70006
	s_mov_b64 s[34:35], -1
	s_waitcnt vmcnt(0)
	v_fmamk_f32 v130, v130, 0x3a800000, v204
	s_and_b64 s[8:9], exec, s[10:11]
	v_rsq_f32_e32 v135, v130
	v_mul_f32_e32 v134, 0.5, v130
	v_mul_f32_e32 v130, v135, v135
	v_fma_f32 v134, -v134, v130, 0.5
	v_fma_f32 v130, v135, v134, v135
	v_pk_mul_f32 v[188:189], v[126:127], v[130:131] op_sel_hi:[1,0]
	v_pk_mul_f32 v[196:197], v[124:125], v[130:131] op_sel_hi:[1,0]
	v_pk_mul_f32 v[186:187], v[122:123], v[130:131] op_sel_hi:[1,0]
	v_pk_mul_f32 v[194:195], v[120:121], v[130:131] op_sel_hi:[1,0]
	v_pk_mul_f32 v[180:181], v[118:119], v[130:131] op_sel_hi:[1,0]
	v_pk_mul_f32 v[184:185], v[116:117], v[130:131] op_sel_hi:[1,0]
	v_pk_mul_f32 v[178:179], v[114:115], v[130:131] op_sel_hi:[1,0]
	v_pk_mul_f32 v[182:183], v[112:113], v[130:131] op_sel_hi:[1,0]
	s_mov_b64 vcc, s[8:9]
	s_cbranch_vccz .LBB0_198
	v_lshlrev_b64 v[112:113], 4, v[176:177]
	s_cmp_lt_i32 s92, 4
	s_mov_b64 s[8:9], -1
	s_cbranch_scc1 .LBB0_193
	v_lshlrev_b64 v[114:115], 9, v[176:177]
	s_cmp_lg_u32 s92, 4
	v_lshl_add_u64 v[114:115], v[148:149], 0, v[114:115]
	s_cbranch_scc0 .LBB0_188
	v_cvt_pk_bf16_f32 v116, v196, v197
	v_cvt_pk_bf16_f32 v117, v188, v189
	v_cvt_pk_bf16_f32 v118, v194, v195
	v_cvt_pk_bf16_f32 v119, v186, v187
	global_store_dwordx4 v[114:115], v[116:119], off offset:256
	s_nop 1
	v_mul_f32_e32 v116, v197, v197
	v_mul_f32_e32 v117, v189, v189
	v_fmac_f32_e32 v116, v196, v196
	v_fmac_f32_e32 v117, v188, v188
	v_add_f32_e32 v116, v116, v117
	v_mul_f32_e32 v117, v195, v195
	v_fmac_f32_e32 v117, v194, v194
	v_add_f32_e32 v116, v117, v116
	v_mul_f32_e32 v117, v187, v187
	v_fmac_f32_e32 v117, v186, v186
	v_and_b32_e32 v118, 64, v206
	v_add_f32_e32 v117, v117, v116
	v_xor_b32_e32 v116, 16, v206
	v_add_u32_e32 v118, 64, v118
	v_cmp_lt_i32_e32 vcc, v116, v118
	s_nop 1
	v_cndmask_b32_e32 v116, v206, v116, vcc
	v_lshlrev_b32_e32 v116, 2, v116
	ds_bpermute_b32 v119, v116, v117
	s_waitcnt lgkmcnt(0)
	v_add_f32_e32 v117, v117, v119
	v_xor_b32_e32 v119, 32, v206
	v_cmp_lt_i32_e32 vcc, v119, v118
	s_nop 1
	v_cndmask_b32_e32 v118, v206, v119, vcc
	v_lshlrev_b32_e32 v118, 2, v118
	ds_bpermute_b32 v118, v118, v117
	s_and_saveexec_b64 s[8:9], s[0:1]
	s_cbranch_execz .LBB0_185
	v_lshl_add_u64 v[120:121], v[112:113], 2, s[88:89]
	s_waitcnt lgkmcnt(0)
	v_add_f32_e32 v117, v117, v118
	global_store_dword v[120:121], v117, off offset:16
	global_store_dword v[120:121], v145, off offset:32
	global_store_dword v[120:121], v145, off offset:48

.LBB0_203:
	v_or_b32_e32 v120, 16, v176
	v_ashrrev_i32_e32 v121, 31, v120
	v_lshlrev_b64 v[112:113], 6, v[120:121]
	s_waitcnt lgkmcnt(0)
	v_lshl_add_u64 v[114:115], s[26:27], 0, v[112:113]
	global_load_dword v114, v[114:115], off
	v_cndmask_b32_e64 v116, 0, 1, s[10:11]
	s_waitcnt vmcnt(0)
	v_fmamk_f32 v114, v114, 0x3a800000, v204
	v_cmp_ne_u32_e64 s[8:9], 1, v116
	v_rsq_f32_e32 v116, v114
	v_mul_f32_e32 v122, 0.5, v114
	v_mul_f32_e32 v114, v116, v116
	v_fma_f32 v122, -v122, v114, 0.5
	v_fma_f32 v114, v116, v122, v116
	s_andn2_b64 vcc, exec, s[10:11]
	v_pk_mul_f32 v[132:133], v[110:111], v[114:115] op_sel_hi:[1,0]
	v_pk_mul_f32 v[178:179], v[108:109], v[114:115] op_sel_hi:[1,0]
	v_pk_mul_f32 v[130:131], v[106:107], v[114:115] op_sel_hi:[1,0]
	v_pk_mul_f32 v[134:135], v[104:105], v[114:115] op_sel_hi:[1,0]
	v_pk_mul_f32 v[124:125], v[102:103], v[114:115] op_sel_hi:[1,0]
	v_pk_mul_f32 v[128:129], v[100:101], v[114:115] op_sel_hi:[1,0]
	v_pk_mul_f32 v[122:123], v[98:99], v[114:115] op_sel_hi:[1,0]
	v_pk_mul_f32 v[126:127], v[96:97], v[114:115] op_sel_hi:[1,0]
	s_mov_b64 s[10:11], -1
	s_cbranch_vccnz .LBB0_221
	v_lshlrev_b64 v[96:97], 4, v[120:121]
	s_cmp_lt_i32 s92, 4
	s_cbranch_scc1 .LBB0_216
	v_lshlrev_b64 v[98:99], 9, v[120:121]
	s_cmp_lg_u32 s92, 4
	v_lshl_add_u64 v[98:99], v[148:149], 0, v[98:99]
	s_cbranch_scc0 .LBB0_211
	v_cvt_pk_bf16_f32 v100, v178, v179
	v_cvt_pk_bf16_f32 v101, v132, v133
	v_cvt_pk_bf16_f32 v102, v134, v135
	v_cvt_pk_bf16_f32 v103, v130, v131
	global_store_dwordx4 v[98:99], v[100:103], off offset:256
	s_nop 1
	v_mul_f32_e32 v100, v179, v179
	v_mul_f32_e32 v101, v133, v133
	v_fmac_f32_e32 v100, v178, v178
	v_fmac_f32_e32 v101, v132, v132
	v_add_f32_e32 v100, v100, v101
	v_mul_f32_e32 v101, v135, v135
	v_fmac_f32_e32 v101, v134, v134
	v_add_f32_e32 v100, v101, v100
	v_mul_f32_e32 v101, v131, v131
	v_fmac_f32_e32 v101, v130, v130
	v_and_b32_e32 v102, 64, v206
	v_add_f32_e32 v101, v101, v100
	v_xor_b32_e32 v100, 16, v206
	v_add_u32_e32 v102, 64, v102
	v_cmp_lt_i32_e32 vcc, v100, v102
	s_nop 1
	v_cndmask_b32_e32 v100, v206, v100, vcc
	v_lshlrev_b32_e32 v100, 2, v100
	ds_bpermute_b32 v103, v100, v101
	s_waitcnt lgkmcnt(0)
	v_add_f32_e32 v101, v101, v103
	v_xor_b32_e32 v103, 32, v206
	v_cmp_lt_i32_e32 vcc, v103, v102
	s_nop 1
	v_cndmask_b32_e32 v102, v206, v103, vcc
	v_lshlrev_b32_e32 v102, 2, v102
	ds_bpermute_b32 v102, v102, v101
	s_and_saveexec_b64 s[10:11], s[0:1]
	s_cbranch_execz .LBB0_208
	v_lshl_add_u64 v[104:105], v[96:97], 2, s[88:89]
	s_waitcnt lgkmcnt(0)
	v_add_f32_e32 v101, v101, v102
	global_store_dword v[104:105], v101, off offset:16
	global_store_dword v[104:105], v145, off offset:32
	global_store_dword v[104:105], v145, off offset:48

.LBB0_226:
	v_or_b32_e32 v104, 32, v176
	v_ashrrev_i32_e32 v105, 31, v104
	v_lshlrev_b64 v[96:97], 6, v[104:105]
	s_waitcnt lgkmcnt(0)
	v_lshl_add_u64 v[98:99], s[26:27], 0, v[96:97]
	global_load_dword v98, v[98:99], off
	s_waitcnt vmcnt(0)
	v_fmamk_f32 v98, v98, 0x3a800000, v204
	s_mov_b64 s[14:15], -1
	v_rsq_f32_e32 v103, v98
	v_mul_f32_e32 v102, 0.5, v98
	v_mul_f32_e32 v98, v103, v103
	v_fma_f32 v102, -v102, v98, 0.5
	v_fma_f32 v98, v103, v102, v103
	s_and_b64 vcc, exec, s[8:9]
	v_pk_mul_f32 v[116:117], v[94:95], v[98:99] op_sel_hi:[1,0]
	v_pk_mul_f32 v[120:121], v[92:93], v[98:99] op_sel_hi:[1,0]
	v_pk_mul_f32 v[114:115], v[90:91], v[98:99] op_sel_hi:[1,0]
	v_pk_mul_f32 v[118:119], v[88:89], v[98:99] op_sel_hi:[1,0]
	v_pk_mul_f32 v[108:109], v[86:87], v[98:99] op_sel_hi:[1,0]
	v_pk_mul_f32 v[112:113], v[84:85], v[98:99] op_sel_hi:[1,0]
	v_pk_mul_f32 v[106:107], v[82:83], v[98:99] op_sel_hi:[1,0]
	v_pk_mul_f32 v[110:111], v[80:81], v[98:99] op_sel_hi:[1,0]
	s_cbranch_vccnz .LBB0_244
	v_lshlrev_b64 v[80:81], 4, v[104:105]
	s_cmp_lt_i32 s92, 4
	s_cbranch_scc1 .LBB0_239
	v_lshlrev_b64 v[82:83], 9, v[104:105]
	s_cmp_lg_u32 s92, 4
	v_lshl_add_u64 v[82:83], v[148:149], 0, v[82:83]
	s_cbranch_scc0 .LBB0_234
	v_cvt_pk_bf16_f32 v84, v120, v121
	v_cvt_pk_bf16_f32 v85, v116, v117
	v_cvt_pk_bf16_f32 v86, v118, v119
	v_cvt_pk_bf16_f32 v87, v114, v115
	global_store_dwordx4 v[82:83], v[84:87], off offset:256
	s_nop 1
	v_mul_f32_e32 v84, v121, v121
	v_mul_f32_e32 v85, v117, v117
	v_fmac_f32_e32 v84, v120, v120
	v_fmac_f32_e32 v85, v116, v116
	v_add_f32_e32 v84, v84, v85
	v_mul_f32_e32 v85, v119, v119
	v_fmac_f32_e32 v85, v118, v118
	v_add_f32_e32 v84, v85, v84
	v_mul_f32_e32 v85, v115, v115
	v_fmac_f32_e32 v85, v114, v114
	v_and_b32_e32 v86, 64, v206
	v_add_f32_e32 v85, v85, v84
	v_xor_b32_e32 v84, 16, v206
	v_add_u32_e32 v86, 64, v86
	v_cmp_lt_i32_e32 vcc, v84, v86
	s_nop 1
	v_cndmask_b32_e32 v84, v206, v84, vcc
	v_lshlrev_b32_e32 v84, 2, v84
	ds_bpermute_b32 v87, v84, v85
	s_waitcnt lgkmcnt(0)
	v_add_f32_e32 v85, v85, v87
	v_xor_b32_e32 v87, 32, v206
	v_cmp_lt_i32_e32 vcc, v87, v86
	s_nop 1
	v_cndmask_b32_e32 v86, v206, v87, vcc
	v_lshlrev_b32_e32 v86, 2, v86
	ds_bpermute_b32 v86, v86, v85
	s_and_saveexec_b64 s[14:15], s[0:1]
	s_cbranch_execz .LBB0_231
	v_lshl_add_u64 v[88:89], v[80:81], 2, s[88:89]
	s_waitcnt lgkmcnt(0)
	v_add_f32_e32 v85, v85, v86
	global_store_dword v[88:89], v85, off offset:16
	global_store_dword v[88:89], v145, off offset:32
	global_store_dword v[88:89], v145, off offset:48

.LBB0_249:
	s_nop 1
	v_or_b32_e32 v80, 48, v176
	v_ashrrev_i32_e32 v81, 31, v80
	s_waitcnt lgkmcnt(0)
	v_lshlrev_b64 v[86:87], 6, v[80:81]
	v_lshl_add_u64 v[82:83], s[26:27], 0, v[86:87]
	global_load_dword v82, v[82:83], off
	s_waitcnt vmcnt(0)
	v_fmamk_f32 v82, v82, 0x3a800000, v204
	s_mov_b64 s[14:15], -1
	v_rsq_f32_e32 v89, v82
	v_mul_f32_e32 v88, 0.5, v82
	v_mul_f32_e32 v82, v89, v89
	v_fma_f32 v88, -v88, v82, 0.5
	v_fma_f32 v82, v89, v88, v89
	s_and_b64 vcc, exec, s[8:9]
	v_pk_mul_f32 v[78:79], v[78:79], v[82:83] op_sel_hi:[1,0]
	v_pk_mul_f32 v[76:77], v[76:77], v[82:83] op_sel_hi:[1,0]
	v_pk_mul_f32 v[74:75], v[74:75], v[82:83] op_sel_hi:[1,0]
	v_pk_mul_f32 v[72:73], v[72:73], v[82:83] op_sel_hi:[1,0]
	v_pk_mul_f32 v[70:71], v[70:71], v[82:83] op_sel_hi:[1,0]
	v_pk_mul_f32 v[68:69], v[68:69], v[82:83] op_sel_hi:[1,0]
	v_pk_mul_f32 v[66:67], v[66:67], v[82:83] op_sel_hi:[1,0]
	v_pk_mul_f32 v[64:65], v[64:65], v[82:83] op_sel_hi:[1,0]
	s_cbranch_vccnz .LBB0_267
	v_lshlrev_b64 v[82:83], 4, v[80:81]
	s_cmp_lt_i32 s92, 4
	s_cbranch_scc1 .LBB0_262
	v_lshlrev_b64 v[84:85], 9, v[80:81]
	s_cmp_lg_u32 s92, 4
	v_lshl_add_u64 v[84:85], v[148:149], 0, v[84:85]
	s_cbranch_scc0 .LBB0_257
	v_cvt_pk_bf16_f32 v88, v76, v77
	v_cvt_pk_bf16_f32 v89, v78, v79
	v_cvt_pk_bf16_f32 v90, v72, v73
	v_cvt_pk_bf16_f32 v91, v74, v75
	global_store_dwordx4 v[84:85], v[88:91], off offset:256
	s_nop 1
	v_mul_f32_e32 v88, v77, v77
	v_mul_f32_e32 v89, v79, v79
	v_fmac_f32_e32 v88, v76, v76
	v_fmac_f32_e32 v89, v78, v78
	v_add_f32_e32 v88, v88, v89
	v_mul_f32_e32 v89, v73, v73
	v_fmac_f32_e32 v89, v72, v72
	v_add_f32_e32 v88, v89, v88
	v_mul_f32_e32 v89, v75, v75
	v_fmac_f32_e32 v89, v74, v74
	v_and_b32_e32 v90, 64, v206
	v_add_f32_e32 v89, v89, v88
	v_xor_b32_e32 v88, 16, v206
	v_add_u32_e32 v90, 64, v90
	v_cmp_lt_i32_e32 vcc, v88, v90
	s_nop 1
	v_cndmask_b32_e32 v88, v206, v88, vcc
	v_lshlrev_b32_e32 v88, 2, v88
	ds_bpermute_b32 v91, v88, v89
	s_waitcnt lgkmcnt(0)
	v_add_f32_e32 v89, v89, v91
	v_xor_b32_e32 v91, 32, v206
	v_cmp_lt_i32_e32 vcc, v91, v90
	s_nop 1
	v_cndmask_b32_e32 v90, v206, v91, vcc
	v_lshlrev_b32_e32 v90, 2, v90
	ds_bpermute_b32 v90, v90, v89
	s_and_saveexec_b64 s[14:15], s[0:1]
	s_cbranch_execz .LBB0_254
	v_lshl_add_u64 v[92:93], v[82:83], 2, s[88:89]
	s_waitcnt lgkmcnt(0)
	v_add_f32_e32 v89, v89, v90
	global_store_dword v[92:93], v89, off offset:16
	global_store_dword v[92:93], v145, off offset:32
	global_store_dword v[92:93], v145, off offset:48

.LBB0_267:
	s_and_b64 vcc, exec, s[14:15]
	s_cbranch_vccz .LBB0_272
	s_and_b64 vcc, exec, s[10:11]
	s_mov_b64 s[14:15], -1
	s_cbranch_vccnz .LBB0_270
	v_mul_f32_e32 v82, v77, v77
	v_mul_f32_e32 v83, v79, v79
	v_fmac_f32_e32 v82, v76, v76
	v_fmac_f32_e32 v83, v78, v78
	v_add_f32_e32 v82, v82, v83
	v_mul_f32_e32 v83, v73, v73
	v_fmac_f32_e32 v83, v72, v72
	v_add_f32_e32 v82, v83, v82
	v_mul_f32_e32 v83, v75, v75
	v_fmac_f32_e32 v83, v74, v74
	v_add_f32_e32 v94, v83, v82
	v_mul_f32_e32 v82, v69, v69
	v_mul_f32_e32 v83, v71, v71
	s_and_b64 s[14:15], s[20:21], exec
	v_fmac_f32_e32 v82, v68, v68
	v_fmac_f32_e32 v83, v70, v70
	s_cselect_b32 s35, s45, s43
	s_cselect_b32 s34, s44, s42
	v_lshlrev_b32_e32 v108, 2, v146
	v_add_f32_e32 v86, v82, v83
	s_waitcnt lgkmcnt(0)
	global_load_dwordx4 v[82:85], v108, s[34:35]
	v_mul_f32_e32 v87, v65, v65
	v_fmac_f32_e32 v87, v64, v64
	v_lshl_or_b32 v102, s30, 6, v202
	v_add_f32_e32 v90, v87, v86
	v_mul_f32_e32 v91, v67, v67
	global_load_dwordx4 v[86:89], v102, s[38:39]
	v_fmac_f32_e32 v91, v66, v66
	v_add_f32_e32 v95, v91, v90
	global_load_dwordx4 v[90:93], v102, s[36:37]
	v_and_b32_e32 v96, 64, v206
	v_add_f32_e32 v94, v94, v95
	v_xor_b32_e32 v95, 16, v206
	v_add_u32_e32 v96, 64, v96
	v_cmp_lt_i32_e32 vcc, v95, v96
	s_cselect_b32 s30, 8, 10
	s_cselect_b32 s75, 0, s91
	v_cndmask_b32_e32 v95, v206, v95, vcc
	v_lshlrev_b32_e32 v95, 2, v95
	ds_bpermute_b32 v95, v95, v94
	s_cselect_b32 s74, s23, s19
	v_lshlrev_b32_e32 v144, 1, v146
	s_waitcnt lgkmcnt(0)
	v_add_f32_e32 v106, v94, v95
	v_xor_b32_e32 v94, 32, v206
	v_cmp_lt_i32_e32 vcc, v94, v96
	s_nop 1
	v_cndmask_b32_e32 v94, v206, v94, vcc
	v_lshlrev_b32_e32 v109, 2, v94
	global_load_dwordx4 v[94:97], v108, s[34:35] offset:16
	global_load_dwordx4 v[98:101], v102, s[36:37] offset:16
	s_nop 0
	global_load_dwordx4 v[102:105], v102, s[38:39] offset:16
	ds_bpermute_b32 v107, v109, v106
	s_waitcnt lgkmcnt(0)
	v_add_f32_e32 v106, v106, v107
	v_fmamk_f32 v106, v106, 0x3c800000, v204
	s_cselect_b32 s15, s3, s31
	s_cselect_b32 s14, s33, s29
	v_rsq_f32_e32 v113, v106
	v_mul_f32_e32 v112, 0.5, v106
	v_mul_f32_e32 v110, v113, v113
	v_fma_f32 v112, -v112, v110, 0.5
	v_fma_f32 v110, v113, v112, v113
	v_mul_f32_e32 v112, v76, v110
	s_waitcnt vmcnt(5)
	v_mul_f32_e32 v82, v82, v112
	ds_bpermute_b32 v112, v109, v82
	v_mul_f32_e32 v113, v77, v110
	v_mul_f32_e32 v83, v83, v113
	ds_bpermute_b32 v113, v109, v83
	v_cndmask_b32_e64 v111, v207, 1.0, s[20:21]
	s_waitcnt vmcnt(4) lgkmcnt(1)
	v_mul_f32_e32 v86, v86, v112
	v_cndmask_b32_e64 v86, v86, -v86, s[12:13]
	s_waitcnt vmcnt(3)
	v_fmac_f32_e32 v86, v90, v82
	v_mul_f32_e32 v82, v111, v86
	s_waitcnt lgkmcnt(0)
	v_mul_f32_e32 v86, v87, v113
	v_cndmask_b32_e64 v86, v86, -v86, s[12:13]
	v_fmac_f32_e32 v86, v91, v83
	v_mul_f32_e32 v83, v78, v110
	v_mul_f32_e32 v83, v84, v83
	ds_bpermute_b32 v84, v109, v83
	v_mul_f32_e32 v87, v79, v110
	v_mul_f32_e32 v85, v85, v87
	ds_bpermute_b32 v87, v109, v85
	v_mul_f32_e32 v90, v75, v110
	s_waitcnt lgkmcnt(1)
	v_mul_f32_e32 v84, v88, v84
	v_cndmask_b32_e64 v84, v84, -v84, s[12:13]
	v_fmac_f32_e32 v84, v92, v83
	v_mul_f32_e32 v83, v111, v84
	s_waitcnt lgkmcnt(0)
	v_mul_f32_e32 v84, v89, v87
	v_cndmask_b32_e64 v84, v84, -v84, s[12:13]
	v_fmac_f32_e32 v84, v93, v85
	v_mul_f32_e32 v85, v72, v110
	s_waitcnt vmcnt(2)
	v_mul_f32_e32 v85, v85, v94
	ds_bpermute_b32 v87, v109, v85
	v_mul_f32_e32 v88, v73, v110
	v_mul_f32_e32 v88, v88, v95
	ds_bpermute_b32 v89, v109, v88
	v_mul_f32_e32 v90, v90, v97
	s_waitcnt vmcnt(0) lgkmcnt(1)
	v_mul_f32_e32 v87, v102, v87
	v_cndmask_b32_e64 v87, v87, -v87, s[12:13]
	v_fmac_f32_e32 v87, v98, v85
	v_mul_f32_e32 v85, v111, v87
	s_waitcnt lgkmcnt(0)
	v_mul_f32_e32 v87, v103, v89
	v_cndmask_b32_e64 v87, v87, -v87, s[12:13]
	v_fmac_f32_e32 v87, v99, v88
	v_mul_f32_e32 v88, v74, v110
	v_mul_f32_e32 v88, v88, v96
	ds_bpermute_b32 v89, v109, v88
	ds_bpermute_b32 v91, v109, v90
	v_lshlrev_b64 v[106:107], s30, v[80:81]
	v_lshl_add_u64 v[106:107], s[14:15], 0, v[106:107]
	v_lshl_add_u64 v[106:107], s[74:75], 1, v[106:107]
	s_waitcnt lgkmcnt(1)
	v_mul_f32_e32 v89, v104, v89
	v_cndmask_b32_e64 v89, v89, -v89, s[12:13]
	v_fmac_f32_e32 v89, v100, v88
	v_mul_f32_e32 v88, v111, v89
	s_waitcnt lgkmcnt(0)
	v_mul_f32_e32 v89, v105, v91
	v_cndmask_b32_e64 v89, v89, -v89, s[12:13]
	v_lshl_add_u64 v[106:107], v[106:107], 0, v[144:145]
	v_mul_f32_e32 v84, v111, v84
	v_fmac_f32_e32 v89, v101, v90
	v_mul_f32_e32 v86, v111, v86
	v_mul_f32_e32 v87, v111, v87
	v_mul_f32_e32 v89, v111, v89
	v_cvt_pk_bf16_f32 v82, v82, v86
	v_cvt_pk_bf16_f32 v83, v83, v84
	v_cvt_pk_bf16_f32 v84, v85, v87
	v_cvt_pk_bf16_f32 v85, v88, v89
	global_store_dwordx4 v[106:107], v[82:85], off
	global_load_dwordx4 v[82:85], v108, s[34:35] offset:128
	s_nop 0
	global_load_dwordx4 v[86:89], v[166:167], off
	global_load_dwordx4 v[90:93], v[164:165], off
	global_load_dwordx4 v[94:97], v108, s[34:35] offset:144
	global_load_dwordx4 v[98:101], v[166:167], off offset:16
	global_load_dwordx4 v[102:105], v[164:165], off offset:16
	v_mul_f32_e32 v114, v71, v110
	v_mul_f32_e32 v108, v68, v110
	v_mul_f32_e32 v113, v70, v110
	v_mul_f32_e32 v112, v69, v110
	s_mov_b64 s[14:15], 0
	s_waitcnt vmcnt(5)
	v_mul_f32_e32 v85, v114, v85
	v_mul_f32_e32 v82, v108, v82
	ds_bpermute_b32 v114, v109, v85
	v_mul_f32_e32 v84, v113, v84
	ds_bpermute_b32 v108, v109, v82
	ds_bpermute_b32 v113, v109, v84
	v_mul_f32_e32 v83, v112, v83
	ds_bpermute_b32 v112, v109, v83
	s_waitcnt vmcnt(4) lgkmcnt(3)
	v_mul_f32_e32 v89, v89, v114
	s_waitcnt lgkmcnt(2)
	v_mul_f32_e32 v86, v86, v108
	v_cndmask_b32_e64 v89, v89, -v89, s[12:13]
	s_waitcnt lgkmcnt(1)
	v_mul_f32_e32 v88, v88, v113
	v_cndmask_b32_e64 v86, v86, -v86, s[12:13]
	s_waitcnt vmcnt(3)
	v_fmac_f32_e32 v89, v93, v85
	v_mul_f32_e32 v85, v64, v110
	v_cndmask_b32_e64 v88, v88, -v88, s[12:13]
	v_fmac_f32_e32 v86, v90, v82
	s_waitcnt vmcnt(2)
	v_mul_f32_e32 v85, v85, v94
	s_waitcnt lgkmcnt(0)
	v_mul_f32_e32 v87, v87, v112
	v_fmac_f32_e32 v88, v92, v84
	v_mul_f32_e32 v82, v111, v86
	ds_bpermute_b32 v86, v109, v85
	v_cndmask_b32_e64 v87, v87, -v87, s[12:13]
	v_mul_f32_e32 v84, v111, v88
	v_mul_f32_e32 v88, v65, v110
	v_fmac_f32_e32 v87, v91, v83
	v_mul_f32_e32 v88, v88, v95
	v_mul_f32_e32 v83, v111, v87
	v_mul_f32_e32 v87, v111, v89
	ds_bpermute_b32 v89, v109, v88
	s_waitcnt vmcnt(1) lgkmcnt(1)
	v_mul_f32_e32 v86, v98, v86
	v_cndmask_b32_e64 v86, v86, -v86, s[12:13]
	s_waitcnt vmcnt(0)
	v_fmac_f32_e32 v86, v102, v85
	v_mul_f32_e32 v85, v111, v86
	s_waitcnt lgkmcnt(0)
	v_mul_f32_e32 v86, v99, v89
	v_cndmask_b32_e64 v86, v86, -v86, s[12:13]
	v_fmac_f32_e32 v86, v103, v88
	v_mul_f32_e32 v88, v66, v110
	v_mul_f32_e32 v88, v88, v96
	ds_bpermute_b32 v89, v109, v88
	v_mul_f32_e32 v90, v67, v110
	v_mul_f32_e32 v90, v90, v97
	ds_bpermute_b32 v91, v109, v90
	v_mul_f32_e32 v86, v111, v86
	s_waitcnt lgkmcnt(1)
	v_mul_f32_e32 v89, v100, v89
	v_cndmask_b32_e64 v89, v89, -v89, s[12:13]
	v_fmac_f32_e32 v89, v104, v88
	v_mul_f32_e32 v88, v111, v89
	s_waitcnt lgkmcnt(0)
	v_mul_f32_e32 v89, v101, v91
	v_cndmask_b32_e64 v89, v89, -v89, s[12:13]
	v_fmac_f32_e32 v89, v105, v90
	v_mul_f32_e32 v89, v111, v89
	v_cvt_pk_bf16_f32 v82, v82, v83
	v_cvt_pk_bf16_f32 v83, v84, v87
	v_cvt_pk_bf16_f32 v84, v85, v86
	v_cvt_pk_bf16_f32 v85, v88, v89
	global_store_dwordx4 v[106:107], v[82:85], off offset:64

.LBB0_272:
	v_add_u32_e32 v72, 0x80, v176
	v_ashrrev_i32_e32 v73, 31, v72
	v_lshlrev_b64 v[64:65], 6, v[72:73]
	v_lshl_add_u64 v[66:67], s[26:27], 0, v[64:65]
	global_load_dword v66, v[66:67], off
	v_bfe_u32 v92, v72, 6, 7
	s_waitcnt vmcnt(0)
	v_fmamk_f32 v66, v66, 0x3a800000, v204
	s_mov_b64 s[14:15], -1
	v_rsq_f32_e32 v71, v66
	v_mul_f32_e32 v70, 0.5, v66
	v_mul_f32_e32 v66, v71, v71
	v_fma_f32 v70, -v70, v66, 0.5
	v_fma_f32 v66, v71, v70, v71
	s_and_b64 vcc, exec, s[8:9]
	s_waitcnt lgkmcnt(0)
	v_pk_mul_f32 v[84:85], v[62:63], v[66:67] op_sel_hi:[1,0]
	v_pk_mul_f32 v[88:89], v[60:61], v[66:67] op_sel_hi:[1,0]
	v_pk_mul_f32 v[82:83], v[58:59], v[66:67] op_sel_hi:[1,0]
	v_pk_mul_f32 v[86:87], v[56:57], v[66:67] op_sel_hi:[1,0]
	v_pk_mul_f32 v[76:77], v[54:55], v[66:67] op_sel_hi:[1,0]
	v_pk_mul_f32 v[80:81], v[52:53], v[66:67] op_sel_hi:[1,0]
	v_pk_mul_f32 v[74:75], v[50:51], v[66:67] op_sel_hi:[1,0]
	v_pk_mul_f32 v[78:79], v[48:49], v[66:67] op_sel_hi:[1,0]
	s_cbranch_vccnz .LBB0_290
	v_lshlrev_b64 v[48:49], 4, v[72:73]
	s_cmp_lt_i32 s92, 4
	s_cbranch_scc1 .LBB0_285
	v_lshlrev_b64 v[50:51], 9, v[72:73]
	s_cmp_lg_u32 s92, 4
	v_lshl_add_u64 v[50:51], v[148:149], 0, v[50:51]
	s_cbranch_scc0 .LBB0_280
	v_cvt_pk_bf16_f32 v52, v88, v89
	v_cvt_pk_bf16_f32 v53, v84, v85
	v_cvt_pk_bf16_f32 v54, v86, v87
	v_cvt_pk_bf16_f32 v55, v82, v83
	global_store_dwordx4 v[50:51], v[52:55], off offset:256
	s_nop 1
	v_mul_f32_e32 v52, v89, v89
	v_mul_f32_e32 v53, v85, v85
	v_fmac_f32_e32 v52, v88, v88
	v_fmac_f32_e32 v53, v84, v84
	v_add_f32_e32 v52, v52, v53
	v_mul_f32_e32 v53, v87, v87
	v_fmac_f32_e32 v53, v86, v86
	v_add_f32_e32 v52, v53, v52
	v_mul_f32_e32 v53, v83, v83
	v_fmac_f32_e32 v53, v82, v82
	v_and_b32_e32 v54, 64, v206
	v_add_f32_e32 v53, v53, v52
	v_xor_b32_e32 v52, 16, v206
	v_add_u32_e32 v54, 64, v54
	v_cmp_lt_i32_e32 vcc, v52, v54
	s_nop 1
	v_cndmask_b32_e32 v52, v206, v52, vcc
	v_lshlrev_b32_e32 v52, 2, v52
	ds_bpermute_b32 v55, v52, v53
	s_waitcnt lgkmcnt(0)
	v_add_f32_e32 v53, v53, v55
	v_xor_b32_e32 v55, 32, v206
	v_cmp_lt_i32_e32 vcc, v55, v54
	s_nop 1
	v_cndmask_b32_e32 v54, v206, v55, vcc
	v_lshlrev_b32_e32 v54, 2, v54
	ds_bpermute_b32 v54, v54, v53
	s_and_saveexec_b64 s[14:15], s[0:1]
	s_cbranch_execz .LBB0_277
	v_lshl_add_u64 v[56:57], v[48:49], 2, s[88:89]
	s_waitcnt lgkmcnt(0)
	v_add_f32_e32 v53, v53, v54
	global_store_dword v[56:57], v53, off offset:16
	global_store_dword v[56:57], v145, off offset:32
	global_store_dword v[56:57], v145, off offset:48

.LBB0_295:
	v_add_u32_e32 v56, 0x90, v176
	v_ashrrev_i32_e32 v57, 31, v56
	v_lshlrev_b64 v[48:49], 6, v[56:57]
	s_waitcnt lgkmcnt(0)
	v_lshl_add_u64 v[50:51], s[26:27], 0, v[48:49]
	global_load_dword v50, v[50:51], off
	s_waitcnt vmcnt(0)
	v_fmamk_f32 v50, v50, 0x3a800000, v204
	s_mov_b64 s[14:15], -1
	v_rsq_f32_e32 v55, v50
	v_mul_f32_e32 v54, 0.5, v50
	v_mul_f32_e32 v50, v55, v55
	v_fma_f32 v54, -v54, v50, 0.5
	v_fma_f32 v50, v55, v54, v55
	s_and_b64 vcc, exec, s[8:9]
	v_pk_mul_f32 v[68:69], v[46:47], v[50:51] op_sel_hi:[1,0]
	v_pk_mul_f32 v[72:73], v[44:45], v[50:51] op_sel_hi:[1,0]
	v_pk_mul_f32 v[66:67], v[42:43], v[50:51] op_sel_hi:[1,0]
	v_pk_mul_f32 v[70:71], v[40:41], v[50:51] op_sel_hi:[1,0]
	v_pk_mul_f32 v[60:61], v[38:39], v[50:51] op_sel_hi:[1,0]
	v_pk_mul_f32 v[64:65], v[36:37], v[50:51] op_sel_hi:[1,0]
	v_pk_mul_f32 v[58:59], v[34:35], v[50:51] op_sel_hi:[1,0]
	v_pk_mul_f32 v[62:63], v[32:33], v[50:51] op_sel_hi:[1,0]
	s_cbranch_vccnz .LBB0_313
	v_lshlrev_b64 v[32:33], 4, v[56:57]
	s_cmp_lt_i32 s92, 4
	s_cbranch_scc1 .LBB0_308
	v_lshlrev_b64 v[34:35], 9, v[56:57]
	s_cmp_lg_u32 s92, 4
	v_lshl_add_u64 v[34:35], v[148:149], 0, v[34:35]
	s_cbranch_scc0 .LBB0_303
	v_cvt_pk_bf16_f32 v36, v72, v73
	v_cvt_pk_bf16_f32 v37, v68, v69
	v_cvt_pk_bf16_f32 v38, v70, v71
	v_cvt_pk_bf16_f32 v39, v66, v67
	global_store_dwordx4 v[34:35], v[36:39], off offset:256
	s_nop 1
	v_mul_f32_e32 v36, v73, v73
	v_mul_f32_e32 v37, v69, v69
	v_fmac_f32_e32 v36, v72, v72
	v_fmac_f32_e32 v37, v68, v68
	v_add_f32_e32 v36, v36, v37
	v_mul_f32_e32 v37, v71, v71
	v_fmac_f32_e32 v37, v70, v70
	v_add_f32_e32 v36, v37, v36
	v_mul_f32_e32 v37, v67, v67
	v_fmac_f32_e32 v37, v66, v66
	v_and_b32_e32 v38, 64, v206
	v_add_f32_e32 v37, v37, v36
	v_xor_b32_e32 v36, 16, v206
	v_add_u32_e32 v38, 64, v38
	v_cmp_lt_i32_e32 vcc, v36, v38
	s_nop 1
	v_cndmask_b32_e32 v36, v206, v36, vcc
	v_lshlrev_b32_e32 v36, 2, v36
	ds_bpermute_b32 v39, v36, v37
	s_waitcnt lgkmcnt(0)
	v_add_f32_e32 v37, v37, v39
	v_xor_b32_e32 v39, 32, v206
	v_cmp_lt_i32_e32 vcc, v39, v38
	s_nop 1
	v_cndmask_b32_e32 v38, v206, v39, vcc
	v_lshlrev_b32_e32 v38, 2, v38
	ds_bpermute_b32 v38, v38, v37
	s_and_saveexec_b64 s[14:15], s[0:1]
	s_cbranch_execz .LBB0_300
	v_lshl_add_u64 v[40:41], v[32:33], 2, s[88:89]
	s_waitcnt lgkmcnt(0)
	v_add_f32_e32 v37, v37, v38
	global_store_dword v[40:41], v37, off offset:16
	global_store_dword v[40:41], v145, off offset:32
	global_store_dword v[40:41], v145, off offset:48

.LBB0_318:
	v_add_u32_e32 v40, 0xa0, v176
	v_ashrrev_i32_e32 v41, 31, v40
	v_lshlrev_b64 v[32:33], 6, v[40:41]
	s_waitcnt lgkmcnt(0)
	v_lshl_add_u64 v[34:35], s[26:27], 0, v[32:33]
	global_load_dword v34, v[34:35], off
	s_waitcnt vmcnt(0)
	v_fmamk_f32 v34, v34, 0x3a800000, v204
	s_mov_b64 s[14:15], -1
	v_rsq_f32_e32 v39, v34
	v_mul_f32_e32 v38, 0.5, v34
	v_mul_f32_e32 v34, v39, v39
	v_fma_f32 v38, -v38, v34, 0.5
	v_fma_f32 v34, v39, v38, v39
	s_and_b64 vcc, exec, s[8:9]
	v_pk_mul_f32 v[52:53], v[30:31], v[34:35] op_sel_hi:[1,0]
	v_pk_mul_f32 v[56:57], v[28:29], v[34:35] op_sel_hi:[1,0]
	v_pk_mul_f32 v[50:51], v[26:27], v[34:35] op_sel_hi:[1,0]
	v_pk_mul_f32 v[54:55], v[24:25], v[34:35] op_sel_hi:[1,0]
	v_pk_mul_f32 v[44:45], v[22:23], v[34:35] op_sel_hi:[1,0]
	v_pk_mul_f32 v[48:49], v[20:21], v[34:35] op_sel_hi:[1,0]
	v_pk_mul_f32 v[42:43], v[18:19], v[34:35] op_sel_hi:[1,0]
	v_pk_mul_f32 v[46:47], v[16:17], v[34:35] op_sel_hi:[1,0]
	s_cbranch_vccnz .LBB0_336
	v_lshlrev_b64 v[16:17], 4, v[40:41]
	s_cmp_lt_i32 s92, 4
	s_cbranch_scc1 .LBB0_331
	v_lshlrev_b64 v[18:19], 9, v[40:41]
	s_cmp_lg_u32 s92, 4
	v_lshl_add_u64 v[18:19], v[148:149], 0, v[18:19]
	s_cbranch_scc0 .LBB0_326
	v_cvt_pk_bf16_f32 v20, v56, v57
	v_cvt_pk_bf16_f32 v21, v52, v53
	v_cvt_pk_bf16_f32 v22, v54, v55
	v_cvt_pk_bf16_f32 v23, v50, v51
	global_store_dwordx4 v[18:19], v[20:23], off offset:256
	s_nop 1
	v_mul_f32_e32 v20, v57, v57
	v_mul_f32_e32 v21, v53, v53
	v_fmac_f32_e32 v20, v56, v56
	v_fmac_f32_e32 v21, v52, v52
	v_add_f32_e32 v20, v20, v21
	v_mul_f32_e32 v21, v55, v55
	v_fmac_f32_e32 v21, v54, v54
	v_add_f32_e32 v20, v21, v20
	v_mul_f32_e32 v21, v51, v51
	v_fmac_f32_e32 v21, v50, v50
	v_and_b32_e32 v22, 64, v206
	v_add_f32_e32 v21, v21, v20
	v_xor_b32_e32 v20, 16, v206
	v_add_u32_e32 v22, 64, v22
	v_cmp_lt_i32_e32 vcc, v20, v22
	s_nop 1
	v_cndmask_b32_e32 v20, v206, v20, vcc
	v_lshlrev_b32_e32 v20, 2, v20
	ds_bpermute_b32 v23, v20, v21
	s_waitcnt lgkmcnt(0)
	v_add_f32_e32 v21, v21, v23
	v_xor_b32_e32 v23, 32, v206
	v_cmp_lt_i32_e32 vcc, v23, v22
	s_nop 1
	v_cndmask_b32_e32 v22, v206, v23, vcc
	v_lshlrev_b32_e32 v22, 2, v22
	ds_bpermute_b32 v22, v22, v21
	s_and_saveexec_b64 s[14:15], s[0:1]
	s_cbranch_execz .LBB0_323
	v_lshl_add_u64 v[24:25], v[16:17], 2, s[88:89]
	s_waitcnt lgkmcnt(0)
	v_add_f32_e32 v21, v21, v22
	global_store_dword v[24:25], v21, off offset:16
	global_store_dword v[24:25], v145, off offset:32
	global_store_dword v[24:25], v145, off offset:48

.LBB0_341:
	v_add_u32_e32 v24, 0xb0, v176
	v_ashrrev_i32_e32 v25, 31, v24
	v_lshlrev_b64 v[16:17], 6, v[24:25]
	s_waitcnt lgkmcnt(0)
	v_lshl_add_u64 v[18:19], s[26:27], 0, v[16:17]
	global_load_dword v18, v[18:19], off
	s_waitcnt vmcnt(0)
	v_fmamk_f32 v18, v18, 0x3a800000, v204
	v_rsq_f32_e32 v23, v18
	v_mul_f32_e32 v22, 0.5, v18
	v_mul_f32_e32 v18, v23, v23
	v_fma_f32 v22, -v22, v18, 0.5
	v_fma_f32 v18, v23, v22, v23
	s_and_b64 vcc, exec, s[8:9]
	v_pk_mul_f32 v[36:37], v[14:15], v[18:19] op_sel_hi:[1,0]
	v_pk_mul_f32 v[40:41], v[12:13], v[18:19] op_sel_hi:[1,0]
	v_pk_mul_f32 v[34:35], v[10:11], v[18:19] op_sel_hi:[1,0]
	v_pk_mul_f32 v[38:39], v[8:9], v[18:19] op_sel_hi:[1,0]
	v_pk_mul_f32 v[28:29], v[6:7], v[18:19] op_sel_hi:[1,0]
	v_pk_mul_f32 v[32:33], v[4:5], v[18:19] op_sel_hi:[1,0]
	v_pk_mul_f32 v[26:27], v[2:3], v[18:19] op_sel_hi:[1,0]
	v_pk_mul_f32 v[30:31], v[0:1], v[18:19] op_sel_hi:[1,0]
	s_mov_b64 s[8:9], -1
	s_cbranch_vccnz .LBB0_359
	v_lshlrev_b64 v[0:1], 4, v[24:25]
	s_cmp_lt_i32 s92, 4
	s_cbranch_scc1 .LBB0_354
	v_lshlrev_b64 v[2:3], 9, v[24:25]
	s_cmp_lg_u32 s92, 4
	v_lshl_add_u64 v[2:3], v[148:149], 0, v[2:3]
	s_cbranch_scc0 .LBB0_349
	v_cvt_pk_bf16_f32 v4, v40, v41
	v_cvt_pk_bf16_f32 v5, v36, v37
	v_cvt_pk_bf16_f32 v6, v38, v39
	v_cvt_pk_bf16_f32 v7, v34, v35
	global_store_dwordx4 v[2:3], v[4:7], off offset:256
	s_nop 1
	v_mul_f32_e32 v4, v41, v41
	v_mul_f32_e32 v5, v37, v37
	v_fmac_f32_e32 v4, v40, v40
	v_fmac_f32_e32 v5, v36, v36
	v_add_f32_e32 v4, v4, v5
	v_mul_f32_e32 v5, v39, v39
	v_fmac_f32_e32 v5, v38, v38
	v_add_f32_e32 v4, v5, v4
	v_mul_f32_e32 v5, v35, v35
	v_fmac_f32_e32 v5, v34, v34
	v_and_b32_e32 v6, 64, v206
	v_add_f32_e32 v5, v5, v4
	v_xor_b32_e32 v4, 16, v206
	v_add_u32_e32 v6, 64, v6
	v_cmp_lt_i32_e32 vcc, v4, v6
	s_nop 1
	v_cndmask_b32_e32 v4, v206, v4, vcc
	v_lshlrev_b32_e32 v4, 2, v4
	ds_bpermute_b32 v7, v4, v5
	s_waitcnt lgkmcnt(0)
	v_add_f32_e32 v5, v5, v7
	v_xor_b32_e32 v7, 32, v206
	v_cmp_lt_i32_e32 vcc, v7, v6
	s_nop 1
	v_cndmask_b32_e32 v6, v206, v7, vcc
	v_lshlrev_b32_e32 v6, 2, v6
	ds_bpermute_b32 v6, v6, v5
	s_and_saveexec_b64 s[8:9], s[0:1]
	s_cbranch_execz .LBB0_346
	v_lshl_add_u64 v[8:9], v[0:1], 2, s[88:89]
	s_waitcnt lgkmcnt(0)
	v_add_f32_e32 v5, v5, v6
	global_store_dword v[8:9], v5, off offset:16
	global_store_dword v[8:9], v145, off offset:32
	global_store_dword v[8:9], v145, off offset:48

.LBB0_435:
	v_lshl_add_u32 v150, s50, 8, v162
	v_ashrrev_i32_e32 v151, 31, v150
	v_lshlrev_b64 v[148:149], 6, v[150:151]
	v_lshl_add_u64 v[148:149], v[138:139], 0, v[148:149]
	global_load_dwordx4 v[170:173], v[148:149], off
	v_and_b32_e32 v153, 64, v167
	v_xor_b32_e32 v151, 16, v167
	v_add_u32_e32 v177, 64, v153
	v_cmp_lt_i32_e32 vcc, v151, v177
	v_xor_b32_e32 v176, 32, v167
	v_mov_b64_e32 v[148:149], s[8:9]
	v_cndmask_b32_e32 v151, v167, v151, vcc
	v_lshlrev_b32_e32 v151, 2, v151
	v_cmp_lt_i32_e32 vcc, v176, v177
	v_lshl_or_b32 v152, s51, 8, v129
	v_ashrrev_i32_e32 v153, 31, v152
	v_lshlrev_b64 v[152:153], 1, v[152:153]
	s_waitcnt vmcnt(0)
	v_mov_b32_e32 v174, v171
	v_mov_b32_e32 v175, v172
	v_mov_b32_e32 v171, v173
	v_pk_add_f32 v[170:171], v[174:175], v[170:171]
	v_or_b32_e32 v174, 16, v150
	v_add_f32_e32 v171, v170, v171
	ds_bpermute_b32 v172, v151, v171
	v_cndmask_b32_e32 v170, v167, v176, vcc
	v_lshlrev_b32_e32 v170, 2, v170
	s_waitcnt lgkmcnt(0)
	v_add_f32_e32 v171, v171, v172
	ds_bpermute_b32 v175, v170, v171
	v_mad_i64_i32 v[172:173], s[4:5], v150, s47, v[148:149]
	v_lshl_add_u64 v[172:173], v[172:173], 0, v[152:153]
	s_waitcnt lgkmcnt(0)
	v_add_f32_e32 v171, v171, v175
	v_fmamk_f32 v171, v171, 0x3b2aaaab, v168
	v_ashrrev_i32_e32 v175, 31, v174
	v_lshlrev_b64 v[176:177], 6, v[174:175]
	v_lshl_add_u64 v[176:177], v[138:139], 0, v[176:177]
	v_rsq_f32_e32 v181, v171
	v_mul_f32_e32 v180, 0.5, v171
	v_mul_f32_e32 v171, v181, v181
	v_fma_f32 v180, -v180, v171, 0.5
	v_fma_f32 v171, v181, v180, v181
	v_mul_f32_e32 v178, 0x3e16c740, v171
	v_pk_mul_f32 v[126:127], v[126:127], v[178:179] op_sel_hi:[1,0]
	v_pk_mul_f32 v[124:125], v[124:125], v[178:179] op_sel_hi:[1,0]
	v_pk_mul_f32 v[122:123], v[122:123], v[178:179] op_sel_hi:[1,0]
	v_pk_mul_f32 v[120:121], v[120:121], v[178:179] op_sel_hi:[1,0]
	v_pk_mul_f32 v[118:119], v[118:119], v[178:179] op_sel_hi:[1,0]
	v_pk_mul_f32 v[116:117], v[116:117], v[178:179] op_sel_hi:[1,0]
	v_pk_mul_f32 v[180:181], v[114:115], v[178:179] op_sel_hi:[1,0]
	v_pk_mul_f32 v[178:179], v[112:113], v[178:179] op_sel_hi:[1,0]
	v_cvt_pk_bf16_f32 v112, v124, v125
	v_cvt_pk_bf16_f32 v113, v126, v127
	v_cvt_pk_bf16_f32 v114, v120, v121
	v_cvt_pk_bf16_f32 v115, v122, v123
	global_store_dwordx4 v[172:173], v[112:115], off
	s_nop 1
	v_cvt_pk_bf16_f32 v112, v116, v117
	v_cvt_pk_bf16_f32 v113, v118, v119
	v_cvt_pk_bf16_f32 v114, v178, v179
	v_cvt_pk_bf16_f32 v115, v180, v181
	global_store_dwordx4 v[172:173], v[112:115], off offset:256
	global_load_dwordx4 v[112:115], v[176:177], off
	s_waitcnt vmcnt(0)
	v_mov_b32_e32 v116, v113
	v_mov_b32_e32 v117, v114
	v_mov_b32_e32 v113, v115
	v_pk_add_f32 v[112:113], v[116:117], v[112:113]
	v_mad_i64_i32 v[114:115], s[4:5], v174, s47, v[148:149]
	v_add_f32_e32 v112, v112, v113
	ds_bpermute_b32 v113, v151, v112
	v_lshl_add_u64 v[114:115], v[114:115], 0, v[152:153]
	s_waitcnt lgkmcnt(0)
	v_add_f32_e32 v113, v112, v113
	ds_bpermute_b32 v116, v170, v113
	v_or_b32_e32 v112, 32, v150
	s_waitcnt lgkmcnt(0)
	v_add_f32_e32 v113, v113, v116
	v_fmamk_f32 v113, v113, 0x3b2aaaab, v168
	v_mov_b32_e32 v118, v113
	v_ashrrev_i32_e32 v113, 31, v112
	v_lshlrev_b64 v[116:117], 6, v[112:113]
	v_lshl_add_u64 v[116:117], v[138:139], 0, v[116:117]
	v_mov_b32_e32 v113, v118
	v_rsq_f32_e32 v122, v113
	v_mul_f32_e32 v121, 0.5, v113
	v_mul_f32_e32 v113, v122, v122
	v_fma_f32 v121, -v121, v113, 0.5
	v_fma_f32 v113, v122, v121, v122
	v_mul_f32_e32 v118, 0x3e16c740, v113
	v_pk_mul_f32 v[110:111], v[110:111], v[118:119] op_sel_hi:[1,0]
	v_pk_mul_f32 v[108:109], v[108:109], v[118:119] op_sel_hi:[1,0]
	v_pk_mul_f32 v[106:107], v[106:107], v[118:119] op_sel_hi:[1,0]
	v_pk_mul_f32 v[104:105], v[104:105], v[118:119] op_sel_hi:[1,0]
	v_pk_mul_f32 v[102:103], v[102:103], v[118:119] op_sel_hi:[1,0]
	v_pk_mul_f32 v[100:101], v[100:101], v[118:119] op_sel_hi:[1,0]
	v_pk_mul_f32 v[120:121], v[98:99], v[118:119] op_sel_hi:[1,0]
	v_pk_mul_f32 v[118:119], v[96:97], v[118:119] op_sel_hi:[1,0]
	v_cvt_pk_bf16_f32 v96, v108, v109
	v_cvt_pk_bf16_f32 v97, v110, v111
	v_cvt_pk_bf16_f32 v98, v104, v105
	v_cvt_pk_bf16_f32 v99, v106, v107
	global_store_dwordx4 v[114:115], v[96:99], off
	s_nop 1
	v_cvt_pk_bf16_f32 v96, v100, v101
	v_cvt_pk_bf16_f32 v97, v102, v103
	v_cvt_pk_bf16_f32 v98, v118, v119
	v_cvt_pk_bf16_f32 v99, v120, v121
	global_store_dwordx4 v[114:115], v[96:99], off offset:256
	global_load_dwordx4 v[96:99], v[116:117], off
	s_waitcnt vmcnt(0)
	v_mov_b32_e32 v100, v97
	v_mov_b32_e32 v101, v98
	v_mov_b32_e32 v97, v99
	v_pk_add_f32 v[96:97], v[100:101], v[96:97]
	v_mad_i64_i32 v[98:99], s[4:5], v112, s47, v[148:149]
	v_add_f32_e32 v96, v96, v97
	ds_bpermute_b32 v97, v151, v96
	v_lshl_add_u64 v[98:99], v[98:99], 0, v[152:153]
	s_waitcnt lgkmcnt(0)
	v_add_f32_e32 v97, v96, v97
	ds_bpermute_b32 v100, v170, v97
	v_or_b32_e32 v96, 48, v150
	s_waitcnt lgkmcnt(0)
	v_add_f32_e32 v97, v97, v100
	v_fmamk_f32 v97, v97, 0x3b2aaaab, v168
	v_mov_b32_e32 v102, v97
	v_ashrrev_i32_e32 v97, 31, v96
	v_lshlrev_b64 v[100:101], 6, v[96:97]
	v_lshl_add_u64 v[100:101], v[138:139], 0, v[100:101]
	v_mov_b32_e32 v97, v102
	v_rsq_f32_e32 v106, v97
	v_mul_f32_e32 v105, 0.5, v97
	v_mul_f32_e32 v97, v106, v106
	v_fma_f32 v105, -v105, v97, 0.5
	v_fma_f32 v97, v106, v105, v106
	v_mul_f32_e32 v102, 0x3e16c740, v97
	v_pk_mul_f32 v[94:95], v[94:95], v[102:103] op_sel_hi:[1,0]
	v_pk_mul_f32 v[92:93], v[92:93], v[102:103] op_sel_hi:[1,0]
	v_pk_mul_f32 v[90:91], v[90:91], v[102:103] op_sel_hi:[1,0]
	v_pk_mul_f32 v[88:89], v[88:89], v[102:103] op_sel_hi:[1,0]
	v_pk_mul_f32 v[86:87], v[86:87], v[102:103] op_sel_hi:[1,0]
	v_pk_mul_f32 v[84:85], v[84:85], v[102:103] op_sel_hi:[1,0]
	v_pk_mul_f32 v[104:105], v[82:83], v[102:103] op_sel_hi:[1,0]
	v_pk_mul_f32 v[102:103], v[80:81], v[102:103] op_sel_hi:[1,0]
	v_cvt_pk_bf16_f32 v80, v92, v93
	v_cvt_pk_bf16_f32 v81, v94, v95
	v_cvt_pk_bf16_f32 v82, v88, v89
	v_cvt_pk_bf16_f32 v83, v90, v91
	global_store_dwordx4 v[98:99], v[80:83], off
	s_nop 1
	v_cvt_pk_bf16_f32 v80, v84, v85
	v_cvt_pk_bf16_f32 v81, v86, v87
	v_cvt_pk_bf16_f32 v82, v102, v103
	v_cvt_pk_bf16_f32 v83, v104, v105
	global_store_dwordx4 v[98:99], v[80:83], off offset:256
	global_load_dwordx4 v[80:83], v[100:101], off
	s_waitcnt vmcnt(0)
	v_mov_b32_e32 v84, v81
	v_mov_b32_e32 v85, v82
	v_mov_b32_e32 v81, v83
	v_pk_add_f32 v[80:81], v[84:85], v[80:81]
	v_mad_i64_i32 v[82:83], s[4:5], v96, s47, v[148:149]
	v_add_f32_e32 v80, v80, v81
	ds_bpermute_b32 v81, v151, v80
	v_lshl_add_u64 v[82:83], v[82:83], 0, v[152:153]
	s_waitcnt lgkmcnt(0)
	v_add_f32_e32 v81, v80, v81
	ds_bpermute_b32 v84, v170, v81
	v_add_u32_e32 v80, 0x80, v150
	s_waitcnt lgkmcnt(0)
	v_add_f32_e32 v81, v81, v84
	v_fmamk_f32 v81, v81, 0x3b2aaaab, v168
	v_mov_b32_e32 v86, v81
	v_ashrrev_i32_e32 v81, 31, v80
	v_lshlrev_b64 v[84:85], 6, v[80:81]
	v_lshl_add_u64 v[84:85], v[138:139], 0, v[84:85]
	v_mov_b32_e32 v81, v86
	v_rsq_f32_e32 v90, v81
	v_mul_f32_e32 v89, 0.5, v81
	v_mul_f32_e32 v81, v90, v90
	v_fma_f32 v89, -v89, v81, 0.5
	v_fma_f32 v81, v90, v89, v90
	v_mul_f32_e32 v86, 0x3e16c740, v81
	v_pk_mul_f32 v[78:79], v[78:79], v[86:87] op_sel_hi:[1,0]
	v_pk_mul_f32 v[76:77], v[76:77], v[86:87] op_sel_hi:[1,0]
	v_pk_mul_f32 v[74:75], v[74:75], v[86:87] op_sel_hi:[1,0]
	v_pk_mul_f32 v[72:73], v[72:73], v[86:87] op_sel_hi:[1,0]
	v_pk_mul_f32 v[70:71], v[70:71], v[86:87] op_sel_hi:[1,0]
	v_pk_mul_f32 v[68:69], v[68:69], v[86:87] op_sel_hi:[1,0]
	v_pk_mul_f32 v[88:89], v[66:67], v[86:87] op_sel_hi:[1,0]
	v_pk_mul_f32 v[86:87], v[64:65], v[86:87] op_sel_hi:[1,0]
	v_cvt_pk_bf16_f32 v64, v76, v77
	v_cvt_pk_bf16_f32 v65, v78, v79
	v_cvt_pk_bf16_f32 v66, v72, v73
	v_cvt_pk_bf16_f32 v67, v74, v75
	global_store_dwordx4 v[82:83], v[64:67], off
	s_nop 1
	v_cvt_pk_bf16_f32 v64, v68, v69
	v_cvt_pk_bf16_f32 v65, v70, v71
	v_cvt_pk_bf16_f32 v66, v86, v87
	v_cvt_pk_bf16_f32 v67, v88, v89
	global_store_dwordx4 v[82:83], v[64:67], off offset:256
	global_load_dwordx4 v[64:67], v[84:85], off
	s_waitcnt vmcnt(0)
	v_mov_b32_e32 v68, v65
	v_mov_b32_e32 v69, v66
	v_mov_b32_e32 v65, v67
	v_pk_add_f32 v[64:65], v[68:69], v[64:65]
	v_mad_i64_i32 v[66:67], s[4:5], v80, s47, v[148:149]
	v_add_f32_e32 v64, v64, v65
	ds_bpermute_b32 v65, v151, v64
	v_lshl_add_u64 v[66:67], v[66:67], 0, v[152:153]
	s_waitcnt lgkmcnt(0)
	v_add_f32_e32 v65, v64, v65
	ds_bpermute_b32 v68, v170, v65
	v_add_u32_e32 v64, 0x90, v150
	s_waitcnt lgkmcnt(0)
	v_add_f32_e32 v65, v65, v68
	v_fmamk_f32 v65, v65, 0x3b2aaaab, v168
	v_mov_b32_e32 v70, v65
	v_ashrrev_i32_e32 v65, 31, v64
	v_lshlrev_b64 v[68:69], 6, v[64:65]
	v_lshl_add_u64 v[68:69], v[138:139], 0, v[68:69]
	v_mov_b32_e32 v65, v70
	v_rsq_f32_e32 v74, v65
	v_mul_f32_e32 v73, 0.5, v65
	v_mul_f32_e32 v65, v74, v74
	v_fma_f32 v73, -v73, v65, 0.5
	v_fma_f32 v65, v74, v73, v74
	v_mul_f32_e32 v70, 0x3e16c740, v65
	v_pk_mul_f32 v[62:63], v[62:63], v[70:71] op_sel_hi:[1,0]
	v_pk_mul_f32 v[60:61], v[60:61], v[70:71] op_sel_hi:[1,0]
	v_pk_mul_f32 v[58:59], v[58:59], v[70:71] op_sel_hi:[1,0]
	v_pk_mul_f32 v[56:57], v[56:57], v[70:71] op_sel_hi:[1,0]
	v_pk_mul_f32 v[54:55], v[54:55], v[70:71] op_sel_hi:[1,0]
	v_pk_mul_f32 v[52:53], v[52:53], v[70:71] op_sel_hi:[1,0]
	v_pk_mul_f32 v[72:73], v[50:51], v[70:71] op_sel_hi:[1,0]
	v_pk_mul_f32 v[70:71], v[48:49], v[70:71] op_sel_hi:[1,0]
	v_cvt_pk_bf16_f32 v48, v60, v61
	v_cvt_pk_bf16_f32 v49, v62, v63
	v_cvt_pk_bf16_f32 v50, v56, v57
	v_cvt_pk_bf16_f32 v51, v58, v59
	global_store_dwordx4 v[66:67], v[48:51], off
	s_nop 1
	v_cvt_pk_bf16_f32 v48, v52, v53
	v_cvt_pk_bf16_f32 v49, v54, v55
	v_cvt_pk_bf16_f32 v50, v70, v71
	v_cvt_pk_bf16_f32 v51, v72, v73
	global_store_dwordx4 v[66:67], v[48:51], off offset:256
	global_load_dwordx4 v[48:51], v[68:69], off
	s_waitcnt vmcnt(0)
	v_mov_b32_e32 v52, v49
	v_mov_b32_e32 v53, v50
	v_mov_b32_e32 v49, v51
	v_pk_add_f32 v[48:49], v[52:53], v[48:49]
	v_mad_i64_i32 v[50:51], s[4:5], v64, s47, v[148:149]
	v_add_f32_e32 v48, v48, v49
	ds_bpermute_b32 v49, v151, v48
	v_lshl_add_u64 v[50:51], v[50:51], 0, v[152:153]
	s_waitcnt lgkmcnt(0)
	v_add_f32_e32 v49, v48, v49
	ds_bpermute_b32 v52, v170, v49
	v_add_u32_e32 v48, 0xa0, v150
	s_waitcnt lgkmcnt(0)
	v_add_f32_e32 v49, v49, v52
	v_fmamk_f32 v49, v49, 0x3b2aaaab, v168
	v_mov_b32_e32 v54, v49
	v_ashrrev_i32_e32 v49, 31, v48
	v_lshlrev_b64 v[52:53], 6, v[48:49]
	v_lshl_add_u64 v[52:53], v[138:139], 0, v[52:53]
	v_mov_b32_e32 v49, v54
	v_rsq_f32_e32 v58, v49
	v_mul_f32_e32 v57, 0.5, v49
	v_mul_f32_e32 v49, v58, v58
	v_fma_f32 v57, -v57, v49, 0.5
	v_fma_f32 v49, v58, v57, v58
	v_mul_f32_e32 v54, 0x3e16c740, v49
	v_pk_mul_f32 v[46:47], v[46:47], v[54:55] op_sel_hi:[1,0]
	v_pk_mul_f32 v[44:45], v[44:45], v[54:55] op_sel_hi:[1,0]
	v_pk_mul_f32 v[42:43], v[42:43], v[54:55] op_sel_hi:[1,0]
	v_pk_mul_f32 v[40:41], v[40:41], v[54:55] op_sel_hi:[1,0]
	v_pk_mul_f32 v[38:39], v[38:39], v[54:55] op_sel_hi:[1,0]
	v_pk_mul_f32 v[36:37], v[36:37], v[54:55] op_sel_hi:[1,0]
	v_pk_mul_f32 v[56:57], v[34:35], v[54:55] op_sel_hi:[1,0]
	v_pk_mul_f32 v[54:55], v[32:33], v[54:55] op_sel_hi:[1,0]
	v_cvt_pk_bf16_f32 v32, v44, v45
	v_cvt_pk_bf16_f32 v33, v46, v47
	v_cvt_pk_bf16_f32 v34, v40, v41
	v_cvt_pk_bf16_f32 v35, v42, v43
	global_store_dwordx4 v[50:51], v[32:35], off
	s_nop 1
	v_cvt_pk_bf16_f32 v32, v36, v37
	v_cvt_pk_bf16_f32 v33, v38, v39
	v_cvt_pk_bf16_f32 v34, v54, v55
	v_cvt_pk_bf16_f32 v35, v56, v57
	global_store_dwordx4 v[50:51], v[32:35], off offset:256
	global_load_dwordx4 v[32:35], v[52:53], off
	s_waitcnt vmcnt(0)
	v_mov_b32_e32 v36, v33
	v_mov_b32_e32 v37, v34
	v_mov_b32_e32 v33, v35
	v_pk_add_f32 v[32:33], v[36:37], v[32:33]
	v_mad_i64_i32 v[34:35], s[4:5], v48, s47, v[148:149]
	v_add_f32_e32 v32, v32, v33
	ds_bpermute_b32 v33, v151, v32
	v_lshl_add_u64 v[34:35], v[34:35], 0, v[152:153]
	s_waitcnt lgkmcnt(0)
	v_add_f32_e32 v33, v32, v33
	ds_bpermute_b32 v36, v170, v33
	v_add_u32_e32 v32, 0xb0, v150
	s_waitcnt lgkmcnt(0)
	v_add_f32_e32 v33, v33, v36
	v_fmamk_f32 v33, v33, 0x3b2aaaab, v168
	v_mov_b32_e32 v38, v33
	v_ashrrev_i32_e32 v33, 31, v32
	v_lshlrev_b64 v[36:37], 6, v[32:33]
	v_lshl_add_u64 v[36:37], v[138:139], 0, v[36:37]
	v_mov_b32_e32 v33, v38
	v_rsq_f32_e32 v42, v33
	v_mul_f32_e32 v41, 0.5, v33
	v_mul_f32_e32 v33, v42, v42
	v_fma_f32 v41, -v41, v33, 0.5
	v_fma_f32 v33, v42, v41, v42
	v_mul_f32_e32 v38, 0x3e16c740, v33
	v_pk_mul_f32 v[30:31], v[30:31], v[38:39] op_sel_hi:[1,0]
	v_pk_mul_f32 v[28:29], v[28:29], v[38:39] op_sel_hi:[1,0]
	v_pk_mul_f32 v[26:27], v[26:27], v[38:39] op_sel_hi:[1,0]
	v_pk_mul_f32 v[24:25], v[24:25], v[38:39] op_sel_hi:[1,0]
	v_pk_mul_f32 v[22:23], v[22:23], v[38:39] op_sel_hi:[1,0]
	v_pk_mul_f32 v[20:21], v[20:21], v[38:39] op_sel_hi:[1,0]
	v_pk_mul_f32 v[40:41], v[18:19], v[38:39] op_sel_hi:[1,0]
	v_pk_mul_f32 v[38:39], v[16:17], v[38:39] op_sel_hi:[1,0]
	v_cvt_pk_bf16_f32 v16, v28, v29
	v_cvt_pk_bf16_f32 v17, v30, v31
	v_cvt_pk_bf16_f32 v18, v24, v25
	v_cvt_pk_bf16_f32 v19, v26, v27
	global_store_dwordx4 v[34:35], v[16:19], off
	s_nop 1
	v_cvt_pk_bf16_f32 v16, v20, v21
	v_cvt_pk_bf16_f32 v17, v22, v23
	v_cvt_pk_bf16_f32 v18, v38, v39
	v_cvt_pk_bf16_f32 v19, v40, v41
	global_store_dwordx4 v[34:35], v[16:19], off offset:256
	global_load_dwordx4 v[16:19], v[36:37], off
	s_waitcnt vmcnt(0)
	v_mov_b32_e32 v20, v17
	v_mov_b32_e32 v21, v18
	v_mov_b32_e32 v17, v19
	v_pk_add_f32 v[16:17], v[20:21], v[16:17]
	s_nop 0
	v_add_f32_e32 v16, v16, v17
	ds_bpermute_b32 v17, v151, v16
	s_waitcnt lgkmcnt(0)
	v_add_f32_e32 v16, v16, v17
	ds_bpermute_b32 v17, v170, v16
	s_waitcnt lgkmcnt(0)
	v_add_f32_e32 v16, v16, v17
	v_fmamk_f32 v16, v16, 0x3b2aaaab, v168
	v_mov_b32_e32 v18, v16
	v_mad_i64_i32 v[16:17], s[4:5], v32, s47, v[148:149]
	v_lshl_add_u64 v[16:17], v[16:17], 0, v[152:153]
	v_rsq_f32_e32 v23, v18
	v_mul_f32_e32 v22, 0.5, v18
	v_mul_f32_e32 v18, v23, v23
	v_fma_f32 v22, -v22, v18, 0.5
	v_fma_f32 v18, v23, v22, v23
	v_mul_f32_e32 v18, 0x3e16c740, v18
	s_and_b64 vcc, exec, s[0:1]
	v_pk_mul_f32 v[14:15], v[14:15], v[18:19] op_sel_hi:[1,0]
	v_pk_mul_f32 v[12:13], v[12:13], v[18:19] op_sel_hi:[1,0]
	v_pk_mul_f32 v[10:11], v[10:11], v[18:19] op_sel_hi:[1,0]
	v_pk_mul_f32 v[8:9], v[8:9], v[18:19] op_sel_hi:[1,0]
	v_pk_mul_f32 v[6:7], v[6:7], v[18:19] op_sel_hi:[1,0]
	v_pk_mul_f32 v[4:5], v[4:5], v[18:19] op_sel_hi:[1,0]
	v_pk_mul_f32 v[20:21], v[2:3], v[18:19] op_sel_hi:[1,0]
	v_pk_mul_f32 v[18:19], v[0:1], v[18:19] op_sel_hi:[1,0]
	v_cvt_pk_bf16_f32 v0, v12, v13
	v_cvt_pk_bf16_f32 v1, v14, v15
	v_cvt_pk_bf16_f32 v2, v8, v9
	v_cvt_pk_bf16_f32 v3, v10, v11
	s_mov_b64 s[0:1], -1
	global_store_dwordx4 v[16:17], v[0:3], off
	s_nop 1
	v_cvt_pk_bf16_f32 v0, v4, v5
	v_cvt_pk_bf16_f32 v1, v6, v7
	v_cvt_pk_bf16_f32 v2, v18, v19
	v_cvt_pk_bf16_f32 v3, v20, v21
	global_store_dwordx4 v[16:17], v[0:3], off offset:256
	s_cbranch_vccnz .LBB0_424
	s_andn2_b64 vcc, exec, s[10:11]
	s_cbranch_vccnz .LBB0_423
	s_barrier
	s_branch .LBB0_423

.LBB0_459:
	v_lshl_add_u32 v144, s4, 8, v146
	v_ashrrev_i32_e32 v145, 31, v144
	v_lshlrev_b64 v[142:143], 6, v[144:145]
	v_lshl_add_u64 v[142:143], v[128:129], 0, v[142:143]
	global_load_dwordx4 v[156:159], v[142:143], off
	v_and_b32_e32 v155, 64, v152
	v_xor_b32_e32 v143, 16, v152
	v_add_u32_e32 v163, 64, v155
	v_cmp_lt_i32_e32 vcc, v143, v163
	v_xor_b32_e32 v162, 32, v152
	v_lshl_or_b32 v142, s5, 8, v148
	v_cndmask_b32_e32 v143, v152, v143, vcc
	v_lshlrev_b32_e32 v155, 2, v143
	v_cmp_lt_i32_e32 vcc, v162, v163
	v_ashrrev_i32_e32 v143, 31, v142
	v_lshlrev_b64 v[142:143], 1, v[142:143]
	s_waitcnt vmcnt(0)
	v_mov_b32_e32 v160, v157
	v_mov_b32_e32 v161, v158
	v_mov_b32_e32 v157, v159
	v_pk_add_f32 v[156:157], v[160:161], v[156:157]
	v_lshlrev_b64 v[160:161], 11, v[144:145]
	v_add_f32_e32 v157, v156, v157
	ds_bpermute_b32 v158, v155, v157
	v_cndmask_b32_e32 v156, v152, v162, vcc
	v_lshlrev_b32_e32 v156, 2, v156
	v_lshl_add_u64 v[160:161], s[12:13], 0, v[160:161]
	v_lshl_add_u64 v[160:161], v[160:161], 0, v[142:143]
	s_waitcnt lgkmcnt(0)
	v_add_f32_e32 v157, v157, v158
	ds_bpermute_b32 v162, v156, v157
	v_or_b32_e32 v158, 16, v144
	v_ashrrev_i32_e32 v159, 31, v158
	s_waitcnt lgkmcnt(0)
	v_add_f32_e32 v145, v157, v162
	v_fmamk_f32 v145, v145, 0x3b800000, v153
	v_lshlrev_b64 v[162:163], 6, v[158:159]
	v_lshl_add_u64 v[162:163], v[128:129], 0, v[162:163]
	v_rsq_f32_e32 v167, v145
	v_mul_f32_e32 v166, 0.5, v145
	v_mul_f32_e32 v164, v167, v167
	v_fma_f32 v166, -v166, v164, 0.5
	v_fma_f32 v164, v167, v166, v167
	v_pk_mul_f32 v[126:127], v[126:127], v[164:165] op_sel_hi:[1,0]
	v_pk_mul_f32 v[124:125], v[124:125], v[164:165] op_sel_hi:[1,0]
	v_pk_mul_f32 v[122:123], v[122:123], v[164:165] op_sel_hi:[1,0]
	v_pk_mul_f32 v[120:121], v[120:121], v[164:165] op_sel_hi:[1,0]
	v_pk_mul_f32 v[118:119], v[118:119], v[164:165] op_sel_hi:[1,0]
	v_pk_mul_f32 v[116:117], v[116:117], v[164:165] op_sel_hi:[1,0]
	v_pk_mul_f32 v[166:167], v[114:115], v[164:165] op_sel_hi:[1,0]
	v_pk_mul_f32 v[164:165], v[112:113], v[164:165] op_sel_hi:[1,0]
	v_cvt_pk_bf16_f32 v112, v124, v125
	v_cvt_pk_bf16_f32 v113, v126, v127
	v_cvt_pk_bf16_f32 v114, v120, v121
	v_cvt_pk_bf16_f32 v115, v122, v123
	global_store_dwordx4 v[160:161], v[112:115], off
	s_nop 1
	v_cvt_pk_bf16_f32 v112, v116, v117
	v_cvt_pk_bf16_f32 v113, v118, v119
	v_cvt_pk_bf16_f32 v114, v164, v165
	v_cvt_pk_bf16_f32 v115, v166, v167
	global_store_dwordx4 v[160:161], v[112:115], off offset:256
	global_load_dwordx4 v[112:115], v[162:163], off
	s_waitcnt vmcnt(0)
	v_mov_b32_e32 v116, v113
	v_mov_b32_e32 v117, v114
	v_mov_b32_e32 v113, v115
	v_pk_add_f32 v[112:113], v[116:117], v[112:113]
	v_lshlrev_b64 v[114:115], 11, v[158:159]
	v_add_f32_e32 v112, v112, v113
	ds_bpermute_b32 v113, v155, v112
	v_lshl_add_u64 v[114:115], s[12:13], 0, v[114:115]
	v_lshl_add_u64 v[114:115], v[114:115], 0, v[142:143]
	s_waitcnt lgkmcnt(0)
	v_add_f32_e32 v116, v112, v113
	ds_bpermute_b32 v117, v156, v116
	v_or_b32_e32 v112, 32, v144
	v_ashrrev_i32_e32 v113, 31, v112
	s_waitcnt lgkmcnt(0)
	v_add_f32_e32 v116, v116, v117
	v_fmamk_f32 v116, v116, 0x3b800000, v153
	v_mov_b32_e32 v118, v116
	v_lshlrev_b64 v[116:117], 6, v[112:113]
	v_lshl_add_u64 v[116:117], v[128:129], 0, v[116:117]
	v_rsq_f32_e32 v123, v118
	v_mul_f32_e32 v122, 0.5, v118
	v_mul_f32_e32 v118, v123, v123
	v_fma_f32 v122, -v122, v118, 0.5
	v_fma_f32 v118, v123, v122, v123
	v_pk_mul_f32 v[110:111], v[110:111], v[118:119] op_sel_hi:[1,0]
	v_pk_mul_f32 v[108:109], v[108:109], v[118:119] op_sel_hi:[1,0]
	v_pk_mul_f32 v[106:107], v[106:107], v[118:119] op_sel_hi:[1,0]
	v_pk_mul_f32 v[104:105], v[104:105], v[118:119] op_sel_hi:[1,0]
	v_pk_mul_f32 v[102:103], v[102:103], v[118:119] op_sel_hi:[1,0]
	v_pk_mul_f32 v[100:101], v[100:101], v[118:119] op_sel_hi:[1,0]
	v_pk_mul_f32 v[120:121], v[98:99], v[118:119] op_sel_hi:[1,0]
	v_pk_mul_f32 v[118:119], v[96:97], v[118:119] op_sel_hi:[1,0]
	v_cvt_pk_bf16_f32 v96, v108, v109
	v_cvt_pk_bf16_f32 v97, v110, v111
	v_cvt_pk_bf16_f32 v98, v104, v105
	v_cvt_pk_bf16_f32 v99, v106, v107
	global_store_dwordx4 v[114:115], v[96:99], off
	s_nop 1
	v_cvt_pk_bf16_f32 v96, v100, v101
	v_cvt_pk_bf16_f32 v97, v102, v103
	v_cvt_pk_bf16_f32 v98, v118, v119
	v_cvt_pk_bf16_f32 v99, v120, v121
	global_store_dwordx4 v[114:115], v[96:99], off offset:256
	global_load_dwordx4 v[96:99], v[116:117], off
	s_waitcnt vmcnt(0)
	v_mov_b32_e32 v100, v97
	v_mov_b32_e32 v101, v98
	v_mov_b32_e32 v97, v99
	v_pk_add_f32 v[96:97], v[100:101], v[96:97]
	v_lshlrev_b64 v[98:99], 11, v[112:113]
	v_add_f32_e32 v96, v96, v97
	ds_bpermute_b32 v97, v155, v96
	v_lshl_add_u64 v[98:99], s[12:13], 0, v[98:99]
	v_lshl_add_u64 v[98:99], v[98:99], 0, v[142:143]
	s_waitcnt lgkmcnt(0)
	v_add_f32_e32 v100, v96, v97
	ds_bpermute_b32 v101, v156, v100
	v_or_b32_e32 v96, 48, v144
	v_ashrrev_i32_e32 v97, 31, v96
	s_waitcnt lgkmcnt(0)
	v_add_f32_e32 v100, v100, v101
	v_fmamk_f32 v100, v100, 0x3b800000, v153
	v_mov_b32_e32 v102, v100
	v_lshlrev_b64 v[100:101], 6, v[96:97]
	v_lshl_add_u64 v[100:101], v[128:129], 0, v[100:101]
	v_rsq_f32_e32 v107, v102
	v_mul_f32_e32 v106, 0.5, v102
	v_mul_f32_e32 v102, v107, v107
	v_fma_f32 v106, -v106, v102, 0.5
	v_fma_f32 v102, v107, v106, v107
	v_pk_mul_f32 v[94:95], v[94:95], v[102:103] op_sel_hi:[1,0]
	v_pk_mul_f32 v[92:93], v[92:93], v[102:103] op_sel_hi:[1,0]
	v_pk_mul_f32 v[90:91], v[90:91], v[102:103] op_sel_hi:[1,0]
	v_pk_mul_f32 v[88:89], v[88:89], v[102:103] op_sel_hi:[1,0]
	v_pk_mul_f32 v[86:87], v[86:87], v[102:103] op_sel_hi:[1,0]
	v_pk_mul_f32 v[84:85], v[84:85], v[102:103] op_sel_hi:[1,0]
	v_pk_mul_f32 v[104:105], v[82:83], v[102:103] op_sel_hi:[1,0]
	v_pk_mul_f32 v[102:103], v[80:81], v[102:103] op_sel_hi:[1,0]
	v_cvt_pk_bf16_f32 v80, v92, v93
	v_cvt_pk_bf16_f32 v81, v94, v95
	v_cvt_pk_bf16_f32 v82, v88, v89
	v_cvt_pk_bf16_f32 v83, v90, v91
	global_store_dwordx4 v[98:99], v[80:83], off
	s_nop 1
	v_cvt_pk_bf16_f32 v80, v84, v85
	v_cvt_pk_bf16_f32 v81, v86, v87
	v_cvt_pk_bf16_f32 v82, v102, v103
	v_cvt_pk_bf16_f32 v83, v104, v105
	global_store_dwordx4 v[98:99], v[80:83], off offset:256
	global_load_dwordx4 v[80:83], v[100:101], off
	s_waitcnt vmcnt(0)
	v_mov_b32_e32 v84, v81
	v_mov_b32_e32 v85, v82
	v_mov_b32_e32 v81, v83
	v_pk_add_f32 v[80:81], v[84:85], v[80:81]
	v_lshlrev_b64 v[82:83], 11, v[96:97]
	v_add_f32_e32 v80, v80, v81
	ds_bpermute_b32 v81, v155, v80
	v_lshl_add_u64 v[82:83], s[12:13], 0, v[82:83]
	v_lshl_add_u64 v[82:83], v[82:83], 0, v[142:143]
	s_waitcnt lgkmcnt(0)
	v_add_f32_e32 v84, v80, v81
	ds_bpermute_b32 v85, v156, v84
	v_add_u32_e32 v80, 0x80, v144
	v_ashrrev_i32_e32 v81, 31, v80
	s_waitcnt lgkmcnt(0)
	v_add_f32_e32 v84, v84, v85
	v_fmamk_f32 v84, v84, 0x3b800000, v153
	v_mov_b32_e32 v86, v84
	v_lshlrev_b64 v[84:85], 6, v[80:81]
	v_lshl_add_u64 v[84:85], v[128:129], 0, v[84:85]
	v_rsq_f32_e32 v91, v86
	v_mul_f32_e32 v90, 0.5, v86
	v_mul_f32_e32 v86, v91, v91
	v_fma_f32 v90, -v90, v86, 0.5
	v_fma_f32 v86, v91, v90, v91
	v_pk_mul_f32 v[78:79], v[78:79], v[86:87] op_sel_hi:[1,0]
	v_pk_mul_f32 v[76:77], v[76:77], v[86:87] op_sel_hi:[1,0]
	v_pk_mul_f32 v[74:75], v[74:75], v[86:87] op_sel_hi:[1,0]
	v_pk_mul_f32 v[72:73], v[72:73], v[86:87] op_sel_hi:[1,0]
	v_pk_mul_f32 v[70:71], v[70:71], v[86:87] op_sel_hi:[1,0]
	v_pk_mul_f32 v[68:69], v[68:69], v[86:87] op_sel_hi:[1,0]
	v_pk_mul_f32 v[88:89], v[66:67], v[86:87] op_sel_hi:[1,0]
	v_pk_mul_f32 v[86:87], v[64:65], v[86:87] op_sel_hi:[1,0]
	v_cvt_pk_bf16_f32 v64, v76, v77
	v_cvt_pk_bf16_f32 v65, v78, v79
	v_cvt_pk_bf16_f32 v66, v72, v73
	v_cvt_pk_bf16_f32 v67, v74, v75
	global_store_dwordx4 v[82:83], v[64:67], off
	s_nop 1
	v_cvt_pk_bf16_f32 v64, v68, v69
	v_cvt_pk_bf16_f32 v65, v70, v71
	v_cvt_pk_bf16_f32 v66, v86, v87
	v_cvt_pk_bf16_f32 v67, v88, v89
	global_store_dwordx4 v[82:83], v[64:67], off offset:256
	global_load_dwordx4 v[64:67], v[84:85], off
	s_waitcnt vmcnt(0)
	v_mov_b32_e32 v68, v65
	v_mov_b32_e32 v69, v66
	v_mov_b32_e32 v65, v67
	v_pk_add_f32 v[64:65], v[68:69], v[64:65]
	v_lshlrev_b64 v[66:67], 11, v[80:81]
	v_add_f32_e32 v64, v64, v65
	ds_bpermute_b32 v65, v155, v64
	v_lshl_add_u64 v[66:67], s[12:13], 0, v[66:67]
	v_lshl_add_u64 v[66:67], v[66:67], 0, v[142:143]
	s_waitcnt lgkmcnt(0)
	v_add_f32_e32 v68, v64, v65
	ds_bpermute_b32 v69, v156, v68
	v_add_u32_e32 v64, 0x90, v144
	v_ashrrev_i32_e32 v65, 31, v64
	s_waitcnt lgkmcnt(0)
	v_add_f32_e32 v68, v68, v69
	v_fmamk_f32 v68, v68, 0x3b800000, v153
	v_mov_b32_e32 v70, v68
	v_lshlrev_b64 v[68:69], 6, v[64:65]
	v_lshl_add_u64 v[68:69], v[128:129], 0, v[68:69]
	v_rsq_f32_e32 v75, v70
	v_mul_f32_e32 v74, 0.5, v70
	v_mul_f32_e32 v70, v75, v75
	v_fma_f32 v74, -v74, v70, 0.5
	v_fma_f32 v70, v75, v74, v75
	v_pk_mul_f32 v[62:63], v[62:63], v[70:71] op_sel_hi:[1,0]
	v_pk_mul_f32 v[60:61], v[60:61], v[70:71] op_sel_hi:[1,0]
	v_pk_mul_f32 v[58:59], v[58:59], v[70:71] op_sel_hi:[1,0]
	v_pk_mul_f32 v[56:57], v[56:57], v[70:71] op_sel_hi:[1,0]
	v_pk_mul_f32 v[54:55], v[54:55], v[70:71] op_sel_hi:[1,0]
	v_pk_mul_f32 v[52:53], v[52:53], v[70:71] op_sel_hi:[1,0]
	v_pk_mul_f32 v[72:73], v[50:51], v[70:71] op_sel_hi:[1,0]
	v_pk_mul_f32 v[70:71], v[48:49], v[70:71] op_sel_hi:[1,0]
	v_cvt_pk_bf16_f32 v48, v60, v61
	v_cvt_pk_bf16_f32 v49, v62, v63
	v_cvt_pk_bf16_f32 v50, v56, v57
	v_cvt_pk_bf16_f32 v51, v58, v59
	global_store_dwordx4 v[66:67], v[48:51], off
	s_nop 1
	v_cvt_pk_bf16_f32 v48, v52, v53
	v_cvt_pk_bf16_f32 v49, v54, v55
	v_cvt_pk_bf16_f32 v50, v70, v71
	v_cvt_pk_bf16_f32 v51, v72, v73
	global_store_dwordx4 v[66:67], v[48:51], off offset:256
	global_load_dwordx4 v[48:51], v[68:69], off
	s_waitcnt vmcnt(0)
	v_mov_b32_e32 v52, v49
	v_mov_b32_e32 v53, v50
	v_mov_b32_e32 v49, v51
	v_pk_add_f32 v[48:49], v[52:53], v[48:49]
	v_lshlrev_b64 v[50:51], 11, v[64:65]
	v_add_f32_e32 v48, v48, v49
	ds_bpermute_b32 v49, v155, v48
	v_lshl_add_u64 v[50:51], s[12:13], 0, v[50:51]
	v_lshl_add_u64 v[50:51], v[50:51], 0, v[142:143]
	s_waitcnt lgkmcnt(0)
	v_add_f32_e32 v52, v48, v49
	ds_bpermute_b32 v53, v156, v52
	v_add_u32_e32 v48, 0xa0, v144
	v_ashrrev_i32_e32 v49, 31, v48
	s_waitcnt lgkmcnt(0)
	v_add_f32_e32 v52, v52, v53
	v_fmamk_f32 v52, v52, 0x3b800000, v153
	v_mov_b32_e32 v54, v52
	v_lshlrev_b64 v[52:53], 6, v[48:49]
	v_lshl_add_u64 v[52:53], v[128:129], 0, v[52:53]
	v_rsq_f32_e32 v59, v54
	v_mul_f32_e32 v58, 0.5, v54
	v_mul_f32_e32 v54, v59, v59
	v_fma_f32 v58, -v58, v54, 0.5
	v_fma_f32 v54, v59, v58, v59
	v_pk_mul_f32 v[46:47], v[46:47], v[54:55] op_sel_hi:[1,0]
	v_pk_mul_f32 v[44:45], v[44:45], v[54:55] op_sel_hi:[1,0]
	v_pk_mul_f32 v[42:43], v[42:43], v[54:55] op_sel_hi:[1,0]
	v_pk_mul_f32 v[40:41], v[40:41], v[54:55] op_sel_hi:[1,0]
	v_pk_mul_f32 v[38:39], v[38:39], v[54:55] op_sel_hi:[1,0]
	v_pk_mul_f32 v[36:37], v[36:37], v[54:55] op_sel_hi:[1,0]
	v_pk_mul_f32 v[56:57], v[34:35], v[54:55] op_sel_hi:[1,0]
	v_pk_mul_f32 v[54:55], v[32:33], v[54:55] op_sel_hi:[1,0]
	v_cvt_pk_bf16_f32 v32, v44, v45
	v_cvt_pk_bf16_f32 v33, v46, v47
	v_cvt_pk_bf16_f32 v34, v40, v41
	v_cvt_pk_bf16_f32 v35, v42, v43
	global_store_dwordx4 v[50:51], v[32:35], off
	s_nop 1
	v_cvt_pk_bf16_f32 v32, v36, v37
	v_cvt_pk_bf16_f32 v33, v38, v39
	v_cvt_pk_bf16_f32 v34, v54, v55
	v_cvt_pk_bf16_f32 v35, v56, v57
	global_store_dwordx4 v[50:51], v[32:35], off offset:256
	global_load_dwordx4 v[32:35], v[52:53], off
	s_waitcnt vmcnt(0)
	v_mov_b32_e32 v36, v33
	v_mov_b32_e32 v37, v34
	v_mov_b32_e32 v33, v35
	v_pk_add_f32 v[32:33], v[36:37], v[32:33]
	v_lshlrev_b64 v[34:35], 11, v[48:49]
	v_add_f32_e32 v32, v32, v33
	ds_bpermute_b32 v33, v155, v32
	v_lshl_add_u64 v[34:35], s[12:13], 0, v[34:35]
	v_lshl_add_u64 v[34:35], v[34:35], 0, v[142:143]
	s_waitcnt lgkmcnt(0)
	v_add_f32_e32 v36, v32, v33
	ds_bpermute_b32 v37, v156, v36
	v_add_u32_e32 v32, 0xb0, v144
	v_ashrrev_i32_e32 v33, 31, v32
	s_waitcnt lgkmcnt(0)
	v_add_f32_e32 v36, v36, v37
	v_fmamk_f32 v36, v36, 0x3b800000, v153
	v_mov_b32_e32 v38, v36
	v_lshlrev_b64 v[36:37], 6, v[32:33]
	v_lshl_add_u64 v[36:37], v[128:129], 0, v[36:37]
	v_rsq_f32_e32 v43, v38
	v_mul_f32_e32 v42, 0.5, v38
	v_mul_f32_e32 v38, v43, v43
	v_fma_f32 v42, -v42, v38, 0.5
	v_fma_f32 v38, v43, v42, v43
	v_pk_mul_f32 v[30:31], v[30:31], v[38:39] op_sel_hi:[1,0]
	v_pk_mul_f32 v[28:29], v[28:29], v[38:39] op_sel_hi:[1,0]
	v_pk_mul_f32 v[26:27], v[26:27], v[38:39] op_sel_hi:[1,0]
	v_pk_mul_f32 v[24:25], v[24:25], v[38:39] op_sel_hi:[1,0]
	v_pk_mul_f32 v[22:23], v[22:23], v[38:39] op_sel_hi:[1,0]
	v_pk_mul_f32 v[20:21], v[20:21], v[38:39] op_sel_hi:[1,0]
	v_pk_mul_f32 v[40:41], v[18:19], v[38:39] op_sel_hi:[1,0]
	v_pk_mul_f32 v[38:39], v[16:17], v[38:39] op_sel_hi:[1,0]
	v_cvt_pk_bf16_f32 v16, v28, v29
	v_cvt_pk_bf16_f32 v17, v30, v31
	v_cvt_pk_bf16_f32 v18, v24, v25
	v_cvt_pk_bf16_f32 v19, v26, v27
	global_store_dwordx4 v[34:35], v[16:19], off
	s_nop 1
	v_cvt_pk_bf16_f32 v16, v20, v21
	v_cvt_pk_bf16_f32 v17, v22, v23
	v_cvt_pk_bf16_f32 v18, v38, v39
	v_cvt_pk_bf16_f32 v19, v40, v41
	global_store_dwordx4 v[34:35], v[16:19], off offset:256
	global_load_dwordx4 v[16:19], v[36:37], off
	s_waitcnt vmcnt(0)
	v_mov_b32_e32 v20, v17
	v_mov_b32_e32 v21, v18
	v_mov_b32_e32 v17, v19
	v_pk_add_f32 v[16:17], v[20:21], v[16:17]
	s_nop 0
	v_add_f32_e32 v16, v16, v17
	ds_bpermute_b32 v17, v155, v16
	s_waitcnt lgkmcnt(0)
	v_add_f32_e32 v16, v16, v17
	ds_bpermute_b32 v17, v156, v16
	s_waitcnt lgkmcnt(0)
	v_add_f32_e32 v16, v16, v17
	v_fmamk_f32 v16, v16, 0x3b800000, v153
	v_mov_b32_e32 v18, v16
	v_lshlrev_b64 v[16:17], 11, v[32:33]
	v_lshl_add_u64 v[16:17], s[12:13], 0, v[16:17]
	v_lshl_add_u64 v[16:17], v[16:17], 0, v[142:143]
	v_rsq_f32_e32 v23, v18
	v_mul_f32_e32 v22, 0.5, v18
	v_mul_f32_e32 v18, v23, v23
	v_fma_f32 v22, -v22, v18, 0.5
	v_fma_f32 v18, v23, v22, v23
	s_andn2_b64 vcc, exec, s[0:1]
	v_pk_mul_f32 v[14:15], v[14:15], v[18:19] op_sel_hi:[1,0]
	v_pk_mul_f32 v[12:13], v[12:13], v[18:19] op_sel_hi:[1,0]
	v_pk_mul_f32 v[10:11], v[10:11], v[18:19] op_sel_hi:[1,0]
	v_pk_mul_f32 v[8:9], v[8:9], v[18:19] op_sel_hi:[1,0]
	v_pk_mul_f32 v[6:7], v[6:7], v[18:19] op_sel_hi:[1,0]
	v_pk_mul_f32 v[4:5], v[4:5], v[18:19] op_sel_hi:[1,0]
	v_pk_mul_f32 v[20:21], v[2:3], v[18:19] op_sel_hi:[1,0]
	v_pk_mul_f32 v[18:19], v[0:1], v[18:19] op_sel_hi:[1,0]
	v_cvt_pk_bf16_f32 v0, v12, v13
	v_cvt_pk_bf16_f32 v1, v14, v15
	v_cvt_pk_bf16_f32 v2, v8, v9
	v_cvt_pk_bf16_f32 v3, v10, v11
	s_mov_b64 s[0:1], -1
	global_store_dwordx4 v[16:17], v[0:3], off
	s_nop 1
	v_cvt_pk_bf16_f32 v0, v4, v5
	v_cvt_pk_bf16_f32 v1, v6, v7
	v_cvt_pk_bf16_f32 v2, v18, v19
	v_cvt_pk_bf16_f32 v3, v20, v21
	global_store_dwordx4 v[16:17], v[0:3], off offset:256
	s_cbranch_vccnz .LBB0_448
	s_andn2_b64 vcc, exec, s[10:11]
	s_cbranch_vccnz .LBB0_447
	s_barrier
	s_branch .LBB0_447

.LBB0_520:
	s_movk_i32 s4, 0xf000
	s_mov_b32 s5, -1
	v_lshl_add_u64 v[70:71], v[178:179], 0, s[4:5]
	s_add_i32 s4, s36, s84
	s_mov_b32 s5, m0
	s_mov_b32 m0, s4
	s_nop 0
	global_load_lds_dwordx4 v[70:71], off
	s_mov_b32 m0, s5
	v_add_u32_e32 v174, s36, v228
	ds_read_b64_tr_b16 v[170:171], v174 offset:36864
	ds_read_b64_tr_b16 v[172:173], v174 offset:37376
	v_add_f32_e32 v70, v50, v51
	v_add_f32_e32 v70, v52, v70
	v_add_f32_e32 v70, v53, v70
	v_add_f32_e32 v70, v54, v70
	v_add_f32_e32 v86, v55, v70
	s_waitcnt lgkmcnt(9)
	v_mfma_f32_32x32x16_bf16 v[66:81], v[66:69], v[110:113], 0
	v_cvt_pk_bf16_f32 v134, v50, v51
	v_cvt_pk_bf16_f32 v135, v52, v53
	ds_read_b64_tr_b16 v[166:167], v174 offset:40960
	ds_read_b64_tr_b16 v[168:169], v174 offset:41472
	v_add_f32_e32 v50, v56, v86
	v_add_f32_e32 v50, v57, v50
	v_add_f32_e32 v50, v58, v50
	v_add_f32_e32 v50, v59, v50
	v_cvt_pk_bf16_f32 v136, v54, v55
	v_cvt_pk_bf16_f32 v137, v56, v57
	s_waitcnt lgkmcnt(10)
	v_mfma_f32_32x32x16_bf16 v[82:97], v[82:85], v[110:113], 0
	ds_read_b64_tr_b16 v[162:163], v174 offset:37888
	ds_read_b64_tr_b16 v[164:165], v174 offset:38400
	s_waitcnt lgkmcnt(11)
	v_mfma_f32_32x32x16_bf16 v[66:81], v[158:161], v[106:109], v[66:81]
	v_add_f32_e32 v50, v60, v50
	v_add_f32_e32 v50, v61, v50
	v_add_f32_e32 v50, v62, v50
	v_add_f32_e32 v50, v63, v50
	v_cvt_pk_bf16_f32 v130, v58, v59
	v_cvt_pk_bf16_f32 v131, v60, v61
	ds_read_b64_tr_b16 v[158:159], v174 offset:41984
	ds_read_b64_tr_b16 v[160:161], v174 offset:42496
	v_add_f32_e32 v50, v64, v50
	v_add_f32_e32 v50, v65, v50
	v_add_f32_e32 v50, v34, v50
	v_add_f32_e32 v50, v35, v50
	v_cvt_pk_bf16_f32 v132, v62, v63
	v_cvt_pk_bf16_f32 v133, v64, v65
	s_waitcnt lgkmcnt(12)
	v_mfma_f32_32x32x16_bf16 v[82:97], v[154:157], v[106:109], v[82:97]
	ds_read_b64_tr_b16 v[154:155], v174 offset:38912
	ds_read_b64_tr_b16 v[156:157], v174 offset:39424
	s_waitcnt lgkmcnt(13)
	v_mfma_f32_32x32x16_bf16 v[66:81], v[150:153], v[102:105], v[66:81]
	v_add_f32_e32 v50, v36, v50
	v_add_f32_e32 v50, v37, v50
	v_add_f32_e32 v50, v38, v50
	v_add_f32_e32 v50, v39, v50
	v_cvt_pk_bf16_f32 v122, v34, v35
	v_cvt_pk_bf16_f32 v123, v36, v37
	ds_read_b64_tr_b16 v[150:151], v174 offset:43008
	ds_read_b64_tr_b16 v[152:153], v174 offset:43520
	v_add_f32_e32 v34, v40, v50
	v_add_f32_e32 v34, v41, v34
	v_add_f32_e32 v34, v42, v34
	v_add_f32_e32 v34, v43, v34
	v_cvt_pk_bf16_f32 v124, v38, v39
	v_cvt_pk_bf16_f32 v125, v40, v41
	s_waitcnt lgkmcnt(14)
	v_mfma_f32_32x32x16_bf16 v[82:97], v[146:149], v[102:105], v[82:97]
	ds_read_b64_tr_b16 v[146:147], v174 offset:39936
	ds_read_b64_tr_b16 v[148:149], v174 offset:40448
	s_waitcnt lgkmcnt(14)
	v_mfma_f32_32x32x16_bf16 v[66:81], v[142:145], v[98:101], v[66:81]
	v_add_f32_e32 v34, v44, v34
	v_add_f32_e32 v34, v45, v34
	v_add_f32_e32 v34, v46, v34
	v_add_f32_e32 v34, v47, v34
	v_cvt_pk_bf16_f32 v118, v42, v43
	v_cvt_pk_bf16_f32 v119, v44, v45
	ds_read_b64_tr_b16 v[142:143], v174 offset:44032
	ds_read_b64_tr_b16 v[144:145], v174 offset:44544
	v_add_f32_e32 v34, v48, v34
	v_add_f32_e32 v34, v49, v34
	v_mfma_f32_32x32x16_bf16 v[82:97], v[138:141], v[98:101], v[82:97]
	v_add_f32_e32 v138, 0, v34
	v_cvt_pk_bf16_f32 v120, v46, v47
	v_cvt_pk_bf16_f32 v121, v48, v49
	v_add_u32_e32 v38, s6, v207
	ds_read_b128 v[34:37], v38 offset:8192
	s_waitcnt lgkmcnt(0)
	v_mfma_f32_32x32x16_bf16 v[66:81], v[34:37], v[114:117], v[66:81]
	ds_read_b128 v[34:37], v38 offset:8704
	s_waitcnt lgkmcnt(0)
	v_mfma_f32_32x32x16_bf16 v[82:97], v[34:37], v[114:117], v[82:97]
	ds_read_b128 v[34:37], v38 offset:10240
	s_waitcnt lgkmcnt(0)
	v_mfma_f32_32x32x16_bf16 v[66:81], v[34:37], v[126:129], v[66:81]
	ds_read_b128 v[34:37], v38 offset:10752
	s_waitcnt lgkmcnt(0)
	v_mfma_f32_32x32x16_bf16 v[82:97], v[34:37], v[126:129], v[82:97]
	s_nop 8
	v_add_f32_e64 v50, v66, -v224
	v_add_f32_e64 v51, v67, -v224
	v_add_f32_e64 v52, v68, -v224
	v_add_f32_e64 v53, v69, -v224
	v_add_f32_e64 v54, v70, -v224
	v_add_f32_e64 v55, v71, -v224
	v_pk_add_f32 v[56:57], v[72:73], v[224:225] op_sel_hi:[1,0] neg_lo:[0,1] neg_hi:[0,1]
	v_pk_add_f32 v[58:59], v[74:75], v[224:225] op_sel_hi:[1,0] neg_lo:[0,1] neg_hi:[0,1]
	v_pk_add_f32 v[60:61], v[76:77], v[224:225] op_sel_hi:[1,0] neg_lo:[0,1] neg_hi:[0,1]
	v_pk_add_f32 v[62:63], v[78:79], v[224:225] op_sel_hi:[1,0] neg_lo:[0,1] neg_hi:[0,1]
	v_pk_add_f32 v[34:35], v[82:83], v[224:225] op_sel_hi:[1,0] neg_lo:[0,1] neg_hi:[0,1]
	v_pk_add_f32 v[36:37], v[84:85], v[224:225] op_sel_hi:[1,0] neg_lo:[0,1] neg_hi:[0,1]
	v_pk_add_f32 v[38:39], v[86:87], v[224:225] op_sel_hi:[1,0] neg_lo:[0,1] neg_hi:[0,1]
	v_pk_add_f32 v[40:41], v[88:89], v[224:225] op_sel_hi:[1,0] neg_lo:[0,1] neg_hi:[0,1]
	v_pk_add_f32 v[42:43], v[90:91], v[224:225] op_sel_hi:[1,0] neg_lo:[0,1] neg_hi:[0,1]
	v_pk_add_f32 v[44:45], v[92:93], v[224:225] op_sel_hi:[1,0] neg_lo:[0,1] neg_hi:[0,1]
	v_pk_add_f32 v[46:47], v[94:95], v[224:225] op_sel_hi:[1,0] neg_lo:[0,1] neg_hi:[0,1]
	v_pk_add_f32 v[64:65], v[80:81], v[224:225] op_sel_hi:[1,0] neg_lo:[0,1] neg_hi:[0,1]
	v_pk_add_f32 v[48:49], v[96:97], v[224:225] op_sel_hi:[1,0] neg_lo:[0,1] neg_hi:[0,1]
	s_add_i32 s4, s6, s87
	s_mov_b32 s5, m0
	s_mov_b32 m0, s4
	s_nop 0
	global_load_lds_dwordx4 v[180:181], off
	s_mov_b32 m0, s5
	v_lshl_add_u64 v[66:67], v[184:185], 0, s[20:21]
	s_add_i32 s4, s89, s71
	s_mov_b32 s5, m0
	s_mov_b32 m0, s4
	s_nop 0
	global_load_lds_dwordx4 v[66:67], off
	s_mov_b32 m0, s5
	v_max_f32_e32 v66, v50, v51
	v_max3_f32 v67, v52, v53, v35
	v_max3_f32 v66, v66, v34, v36
	v_max3_f32 v66, v66, v37, v54
	v_max3_f32 v67, v67, v56, v57
	v_max3_f32 v66, v66, v55, v38
	v_max3_f32 v67, v67, v40, v41
	v_max3_f32 v66, v66, v39, v58
	v_max3_f32 v67, v67, v60, v61
	v_max3_f32 v66, v66, v59, v42
	v_max3_f32 v67, v67, v44, v45
	v_max3_f32 v66, v66, v43, v62
	v_max3_f32 v67, v67, v64, v65
	v_max3_f32 v66, v66, v63, v46
	v_max3_f32 v67, v67, v48, v49
	v_max3_f32 v66, v66, v47, v67
	v_mov_b32_e32 v67, v66
	s_nop 1
	v_permlane32_swap_b32_e32 v66, v67
	v_max_f32_e32 v66, v66, v67
	v_cmp_lt_f32_e32 vcc, s27, v66
	s_cmp_lg_u64 vcc, 0
	v_add_f32_e32 v0, v0, v138
	s_cselect_b64 s[4:5], -1, 0
	s_cbranch_vccnz .LBB0_528

.LBB0_523:
	s_add_i32 s5, s6, s84
	s_mov_b32 s7, m0
	s_mov_b32 m0, s5
	s_nop 0
	global_load_lds_dwordx4 v[178:179], off
	s_mov_b32 m0, s7
	s_add_i32 s4, s89, 0x3000
	v_add_u32_e32 v189, s6, v228
	ds_read_b64_tr_b16 v[150:151], v189 offset:36864
	ds_read_b64_tr_b16 v[152:153], v189 offset:37376
	v_add_f32_e32 v70, v50, v51
	v_add_f32_e32 v70, v52, v70
	v_add_f32_e32 v70, v53, v70
	v_add_f32_e32 v70, v54, v70
	v_add_f32_e32 v86, v55, v70
	s_waitcnt lgkmcnt(9)
	v_mfma_f32_32x32x16_bf16 v[66:81], v[66:69], v[110:113], 0
	v_cvt_pk_bf16_f32 v134, v50, v51
	v_cvt_pk_bf16_f32 v135, v52, v53
	ds_read_b64_tr_b16 v[146:147], v189 offset:40960
	ds_read_b64_tr_b16 v[148:149], v189 offset:41472
	v_add_f32_e32 v50, v56, v86
	v_add_f32_e32 v50, v57, v50
	v_add_f32_e32 v50, v58, v50
	v_add_f32_e32 v50, v59, v50
	v_cvt_pk_bf16_f32 v136, v54, v55
	v_cvt_pk_bf16_f32 v137, v56, v57
	s_waitcnt lgkmcnt(10)
	v_mfma_f32_32x32x16_bf16 v[82:97], v[82:85], v[110:113], 0
	ds_read_b64_tr_b16 v[138:139], v189 offset:37888
	ds_read_b64_tr_b16 v[140:141], v189 offset:38400
	s_waitcnt lgkmcnt(11)
	v_mfma_f32_32x32x16_bf16 v[66:81], v[174:177], v[106:109], v[66:81]
	v_add_f32_e32 v50, v60, v50
	v_add_f32_e32 v50, v61, v50
	v_add_f32_e32 v50, v62, v50
	v_add_f32_e32 v50, v63, v50
	v_cvt_pk_bf16_f32 v130, v58, v59
	v_cvt_pk_bf16_f32 v131, v60, v61
	ds_read_b64_tr_b16 v[142:143], v189 offset:41984
	ds_read_b64_tr_b16 v[144:145], v189 offset:42496
	v_add_f32_e32 v50, v64, v50
	v_add_f32_e32 v50, v65, v50
	v_add_f32_e32 v50, v34, v50
	v_add_f32_e32 v50, v35, v50
	v_cvt_pk_bf16_f32 v132, v62, v63
	v_cvt_pk_bf16_f32 v133, v64, v65
	s_waitcnt lgkmcnt(12)
	v_mfma_f32_32x32x16_bf16 v[82:97], v[166:169], v[106:109], v[82:97]
	ds_read_b64_tr_b16 v[174:175], v189 offset:38912
	ds_read_b64_tr_b16 v[176:177], v189 offset:39424
	s_waitcnt lgkmcnt(13)
	v_mfma_f32_32x32x16_bf16 v[66:81], v[162:165], v[102:105], v[66:81]
	v_add_f32_e32 v50, v36, v50
	v_add_f32_e32 v50, v37, v50
	v_add_f32_e32 v50, v38, v50
	v_add_f32_e32 v50, v39, v50
	v_cvt_pk_bf16_f32 v122, v34, v35
	v_cvt_pk_bf16_f32 v123, v36, v37
	ds_read_b64_tr_b16 v[162:163], v189 offset:43008
	ds_read_b64_tr_b16 v[164:165], v189 offset:43520
	v_add_f32_e32 v34, v40, v50
	v_add_f32_e32 v34, v41, v34
	v_add_f32_e32 v34, v42, v34
	v_add_f32_e32 v34, v43, v34
	v_cvt_pk_bf16_f32 v124, v38, v39
	v_cvt_pk_bf16_f32 v125, v40, v41
	s_waitcnt lgkmcnt(14)
	v_mfma_f32_32x32x16_bf16 v[82:97], v[158:161], v[102:105], v[82:97]
	ds_read_b64_tr_b16 v[166:167], v189 offset:39936
	ds_read_b64_tr_b16 v[168:169], v189 offset:40448
	s_waitcnt lgkmcnt(14)
	v_mfma_f32_32x32x16_bf16 v[66:81], v[170:173], v[98:101], v[66:81]
	v_add_f32_e32 v34, v44, v34
	v_add_f32_e32 v34, v45, v34
	v_add_f32_e32 v34, v46, v34
	v_add_f32_e32 v34, v47, v34
	v_cvt_pk_bf16_f32 v118, v42, v43
	v_cvt_pk_bf16_f32 v119, v44, v45
	ds_read_b64_tr_b16 v[170:171], v189 offset:44032
	ds_read_b64_tr_b16 v[172:173], v189 offset:44544
	v_add_f32_e32 v34, v48, v34
	v_add_f32_e32 v34, v49, v34
	v_mfma_f32_32x32x16_bf16 v[82:97], v[154:157], v[98:101], v[82:97]
	v_add_f32_e32 v154, 0, v34
	v_cvt_pk_bf16_f32 v120, v46, v47
	v_cvt_pk_bf16_f32 v121, v48, v49
	ds_read_b128 v[34:37], v188 offset:8192
	s_cmpk_lg_i32 s89, 0x6000
	s_cselect_b32 s6, s4, 0
	s_waitcnt lgkmcnt(0)
	v_mfma_f32_32x32x16_bf16 v[66:81], v[34:37], v[114:117], v[66:81]
	ds_read_b128 v[34:37], v188 offset:8704
	s_waitcnt lgkmcnt(0)
	v_mfma_f32_32x32x16_bf16 v[82:97], v[34:37], v[114:117], v[82:97]
	ds_read_b128 v[34:37], v188 offset:10240
	s_waitcnt lgkmcnt(0)
	v_mfma_f32_32x32x16_bf16 v[66:81], v[34:37], v[126:129], v[66:81]
	ds_read_b128 v[34:37], v188 offset:10752
	s_waitcnt lgkmcnt(0)
	v_mfma_f32_32x32x16_bf16 v[82:97], v[34:37], v[126:129], v[82:97]
	s_nop 8
	v_add_f32_e64 v50, v66, -v224
	v_add_f32_e64 v51, v67, -v224
	v_add_f32_e64 v52, v68, -v224
	v_add_f32_e64 v53, v69, -v224
	v_add_f32_e64 v54, v70, -v224
	v_add_f32_e64 v55, v71, -v224
	v_pk_add_f32 v[56:57], v[72:73], v[224:225] op_sel_hi:[1,0] neg_lo:[0,1] neg_hi:[0,1]
	v_pk_add_f32 v[58:59], v[74:75], v[224:225] op_sel_hi:[1,0] neg_lo:[0,1] neg_hi:[0,1]
	v_pk_add_f32 v[60:61], v[76:77], v[224:225] op_sel_hi:[1,0] neg_lo:[0,1] neg_hi:[0,1]
	v_pk_add_f32 v[62:63], v[78:79], v[224:225] op_sel_hi:[1,0] neg_lo:[0,1] neg_hi:[0,1]
	v_pk_add_f32 v[34:35], v[82:83], v[224:225] op_sel_hi:[1,0] neg_lo:[0,1] neg_hi:[0,1]
	v_pk_add_f32 v[36:37], v[84:85], v[224:225] op_sel_hi:[1,0] neg_lo:[0,1] neg_hi:[0,1]
	v_pk_add_f32 v[38:39], v[86:87], v[224:225] op_sel_hi:[1,0] neg_lo:[0,1] neg_hi:[0,1]
	v_pk_add_f32 v[40:41], v[88:89], v[224:225] op_sel_hi:[1,0] neg_lo:[0,1] neg_hi:[0,1]
	v_pk_add_f32 v[42:43], v[90:91], v[224:225] op_sel_hi:[1,0] neg_lo:[0,1] neg_hi:[0,1]
	v_pk_add_f32 v[44:45], v[92:93], v[224:225] op_sel_hi:[1,0] neg_lo:[0,1] neg_hi:[0,1]
	v_pk_add_f32 v[46:47], v[94:95], v[224:225] op_sel_hi:[1,0] neg_lo:[0,1] neg_hi:[0,1]
	v_pk_add_f32 v[64:65], v[80:81], v[224:225] op_sel_hi:[1,0] neg_lo:[0,1] neg_hi:[0,1]
	v_pk_add_f32 v[48:49], v[96:97], v[224:225] op_sel_hi:[1,0] neg_lo:[0,1] neg_hi:[0,1]
	v_lshl_add_u64 v[66:67], v[186:187], 0, s[96:97]
	s_add_i32 s4, s89, s87
	s_mov_b32 s5, m0
	s_mov_b32 m0, s4
	s_nop 0
	global_load_lds_dwordx4 v[66:67], off
	s_mov_b32 m0, s5
	v_max_f32_e32 v66, v50, v51
	v_max3_f32 v67, v52, v53, v35
	v_max3_f32 v66, v66, v34, v36
	v_max3_f32 v66, v66, v37, v54
	v_max3_f32 v67, v67, v56, v57
	v_max3_f32 v66, v66, v55, v38
	v_max3_f32 v67, v67, v40, v41
	v_max3_f32 v66, v66, v39, v58
	v_max3_f32 v67, v67, v60, v61
	v_max3_f32 v66, v66, v59, v42
	v_max3_f32 v67, v67, v44, v45
	v_max3_f32 v66, v66, v43, v62
	v_max3_f32 v67, v67, v64, v65
	v_max3_f32 v66, v66, v63, v46
	v_max3_f32 v67, v67, v48, v49
	v_max3_f32 v66, v66, v47, v67
	v_mov_b32_e32 v67, v66
	s_nop 1
	v_permlane32_swap_b32_e32 v66, v67
	v_max_f32_e32 v66, v66, v67
	v_lshl_add_u64 v[184:185], v[184:185], 0, s[90:91]
	s_add_i32 s4, s6, s71
	s_mov_b32 s5, m0
	s_mov_b32 m0, s4
	s_nop 0
	global_load_lds_dwordx4 v[184:185], off
	s_mov_b32 m0, s5
	v_cmp_lt_f32_e32 vcc, s27, v66
	s_cmp_lg_u64 vcc, 0
	v_add_f32_e32 v0, v0, v154
	s_cselect_b64 s[4:5], -1, 0
	s_cbranch_vccnz .LBB0_531

.LBB0_534:
	s_mov_b64 s[4:5], 0x7d000
	s_cmp_lg_u32 0, -1
	v_lshl_add_u64 v[70:71], v[226:227], 0, s[4:5]
	s_cselect_b32 s4, 0, 0
	s_add_i32 s5, s4, s86
	s_addk_i32 s5, 0x6000
	s_mov_b32 s6, m0
	s_mov_b32 m0, s5
	s_nop 0
	global_load_lds_dwordx4 v[70:71], off
	s_mov_b32 m0, s6
	ds_read_b64_tr_b16 v[170:171], v228 offset:61440
	ds_read_b64_tr_b16 v[172:173], v228 offset:61952
	v_add_f32_e32 v70, v50, v51
	v_add_f32_e32 v70, v52, v70
	v_add_f32_e32 v70, v53, v70
	v_add_f32_e32 v70, v54, v70
	v_add_f32_e32 v86, v55, v70
	v_cvt_pk_bf16_f32 v134, v50, v51
	v_cvt_pk_bf16_f32 v135, v52, v53
	s_waitcnt lgkmcnt(9)
	v_mfma_f32_32x32x16_bf16 v[66:81], v[66:69], v[110:113], 0
	ds_read_b64_tr_b16 v[166:167], v229 offset:28672
	ds_read_b64_tr_b16 v[168:169], v229 offset:29184
	v_add_f32_e32 v50, v56, v86
	v_add_f32_e32 v50, v57, v50
	v_add_f32_e32 v50, v58, v50
	v_add_f32_e32 v50, v59, v50
	v_cvt_pk_bf16_f32 v136, v54, v55
	v_cvt_pk_bf16_f32 v137, v56, v57
	s_waitcnt lgkmcnt(10)
	v_mfma_f32_32x32x16_bf16 v[82:97], v[82:85], v[110:113], 0
	ds_read_b64_tr_b16 v[162:163], v228 offset:62464
	ds_read_b64_tr_b16 v[164:165], v228 offset:62976
	v_add_f32_e32 v50, v60, v50
	v_add_f32_e32 v50, v61, v50
	v_add_f32_e32 v50, v62, v50
	v_add_f32_e32 v50, v63, v50
	v_cvt_pk_bf16_f32 v130, v58, v59
	v_cvt_pk_bf16_f32 v131, v60, v61
	s_waitcnt lgkmcnt(11)
	v_mfma_f32_32x32x16_bf16 v[66:81], v[158:161], v[106:109], v[66:81]
	ds_read_b64_tr_b16 v[158:159], v229 offset:29696
	ds_read_b64_tr_b16 v[160:161], v229 offset:30208
	v_add_f32_e32 v50, v64, v50
	v_add_f32_e32 v50, v65, v50
	v_add_f32_e32 v50, v34, v50
	v_add_f32_e32 v50, v35, v50
	v_cvt_pk_bf16_f32 v132, v62, v63
	v_cvt_pk_bf16_f32 v133, v64, v65
	s_waitcnt lgkmcnt(12)
	v_mfma_f32_32x32x16_bf16 v[82:97], v[154:157], v[106:109], v[82:97]
	ds_read_b64_tr_b16 v[154:155], v228 offset:63488
	ds_read_b64_tr_b16 v[156:157], v228 offset:64000
	v_add_f32_e32 v50, v36, v50
	v_add_f32_e32 v50, v37, v50
	v_add_f32_e32 v50, v38, v50
	v_add_f32_e32 v50, v39, v50
	v_cvt_pk_bf16_f32 v122, v34, v35
	v_cvt_pk_bf16_f32 v123, v36, v37
	s_waitcnt lgkmcnt(13)
	v_mfma_f32_32x32x16_bf16 v[66:81], v[150:153], v[102:105], v[66:81]
	ds_read_b64_tr_b16 v[150:151], v229 offset:30720
	ds_read_b64_tr_b16 v[152:153], v229 offset:31232
	v_add_f32_e32 v34, v40, v50
	v_add_f32_e32 v34, v41, v34
	v_add_f32_e32 v34, v42, v34
	v_add_f32_e32 v34, v43, v34
	v_cvt_pk_bf16_f32 v124, v38, v39
	v_cvt_pk_bf16_f32 v125, v40, v41
	s_waitcnt lgkmcnt(14)
	v_mfma_f32_32x32x16_bf16 v[82:97], v[146:149], v[102:105], v[82:97]
	ds_read_b64_tr_b16 v[146:147], v228 offset:64512
	ds_read_b64_tr_b16 v[148:149], v228 offset:65024
	v_add_f32_e32 v34, v44, v34
	v_add_f32_e32 v34, v45, v34
	v_add_f32_e32 v34, v46, v34
	v_add_f32_e32 v34, v47, v34
	v_cvt_pk_bf16_f32 v118, v42, v43
	v_cvt_pk_bf16_f32 v119, v44, v45
	s_waitcnt lgkmcnt(14)
	v_mfma_f32_32x32x16_bf16 v[66:81], v[142:145], v[98:101], v[66:81]
	ds_read_b64_tr_b16 v[142:143], v229 offset:31744
	ds_read_b64_tr_b16 v[144:145], v229 offset:32256
	v_add_f32_e32 v34, v48, v34
	v_add_f32_e32 v34, v49, v34
	v_mfma_f32_32x32x16_bf16 v[82:97], v[138:141], v[98:101], v[82:97]
	v_add_f32_e32 v138, 0, v34
	v_cvt_pk_bf16_f32 v120, v46, v47
	v_cvt_pk_bf16_f32 v121, v48, v49
	ds_read_b128 v[34:37], v207 offset:8192
	v_add_f32_e32 v184, v0, v138
	s_waitcnt lgkmcnt(0)
	v_mfma_f32_32x32x16_bf16 v[66:81], v[34:37], v[114:117], v[66:81]
	ds_read_b128 v[34:37], v207 offset:8704
	s_waitcnt lgkmcnt(0)
	v_mfma_f32_32x32x16_bf16 v[82:97], v[34:37], v[114:117], v[82:97]
	ds_read_b128 v[34:37], v207 offset:10240
	s_waitcnt lgkmcnt(0)
	v_mfma_f32_32x32x16_bf16 v[66:81], v[34:37], v[126:129], v[66:81]
	ds_read_b128 v[34:37], v207 offset:10752
	s_waitcnt lgkmcnt(0)
	v_mfma_f32_32x32x16_bf16 v[82:97], v[34:37], v[126:129], v[82:97]
	s_nop 8
	v_add_f32_e64 v50, v66, -v224
	v_add_f32_e64 v51, v67, -v224
	v_add_f32_e64 v52, v68, -v224
	v_add_f32_e64 v53, v69, -v224
	v_add_f32_e64 v54, v70, -v224
	v_add_f32_e64 v55, v71, -v224
	v_pk_add_f32 v[56:57], v[72:73], v[224:225] op_sel_hi:[1,0] neg_lo:[0,1] neg_hi:[0,1]
	v_pk_add_f32 v[58:59], v[74:75], v[224:225] op_sel_hi:[1,0] neg_lo:[0,1] neg_hi:[0,1]
	v_pk_add_f32 v[60:61], v[76:77], v[224:225] op_sel_hi:[1,0] neg_lo:[0,1] neg_hi:[0,1]
	v_pk_add_f32 v[62:63], v[78:79], v[224:225] op_sel_hi:[1,0] neg_lo:[0,1] neg_hi:[0,1]
	v_pk_add_f32 v[34:35], v[82:83], v[224:225] op_sel_hi:[1,0] neg_lo:[0,1] neg_hi:[0,1]
	v_pk_add_f32 v[36:37], v[84:85], v[224:225] op_sel_hi:[1,0] neg_lo:[0,1] neg_hi:[0,1]
	v_pk_add_f32 v[38:39], v[86:87], v[224:225] op_sel_hi:[1,0] neg_lo:[0,1] neg_hi:[0,1]
	v_pk_add_f32 v[40:41], v[88:89], v[224:225] op_sel_hi:[1,0] neg_lo:[0,1] neg_hi:[0,1]
	v_pk_add_f32 v[42:43], v[90:91], v[224:225] op_sel_hi:[1,0] neg_lo:[0,1] neg_hi:[0,1]
	v_pk_add_f32 v[44:45], v[92:93], v[224:225] op_sel_hi:[1,0] neg_lo:[0,1] neg_hi:[0,1]
	v_pk_add_f32 v[46:47], v[94:95], v[224:225] op_sel_hi:[1,0] neg_lo:[0,1] neg_hi:[0,1]
	v_pk_add_f32 v[64:65], v[80:81], v[224:225] op_sel_hi:[1,0] neg_lo:[0,1] neg_hi:[0,1]
	v_pk_add_f32 v[48:49], v[96:97], v[224:225] op_sel_hi:[1,0] neg_lo:[0,1] neg_hi:[0,1]
	v_lshl_add_u64 v[66:67], v[182:183], 0, s[38:39]
	s_mov_b64 s[6:7], 0xf80000
	s_mov_b32 s5, m0
	s_mov_b32 m0, s87
	s_nop 0
	global_load_lds_dwordx4 v[66:67], off
	s_mov_b32 m0, s5
	v_lshl_add_u64 v[66:67], v[222:223], 0, s[6:7]
	s_add_i32 s4, s4, s85
	v_max_f32_e32 v0, v50, v51
	s_add_i32 s36, s4, 0xc000
	s_mov_b32 s4, m0
	s_mov_b32 m0, s36
	s_nop 0
	global_load_lds_dwordx4 v[66:67], off
	s_mov_b32 m0, s4
	v_max3_f32 v66, v52, v53, v35
	v_max3_f32 v0, v0, v34, v36
	v_max3_f32 v0, v0, v37, v54
	v_max3_f32 v66, v66, v56, v57
	v_max3_f32 v0, v0, v55, v38
	v_max3_f32 v66, v66, v40, v41
	v_max3_f32 v0, v0, v39, v58
	v_max3_f32 v66, v66, v60, v61
	v_max3_f32 v0, v0, v59, v42
	v_max3_f32 v66, v66, v44, v45
	v_max3_f32 v0, v0, v43, v62
	v_max3_f32 v66, v66, v64, v65
	v_max3_f32 v0, v0, v63, v46
	v_max3_f32 v66, v66, v48, v49
	v_max3_f32 v0, v0, v47, v66
	v_mov_b32_e32 v66, v0
	s_nop 1
	v_permlane32_swap_b32_e32 v0, v66
	v_max_f32_e32 v0, v0, v66
	v_cmp_lt_f32_e32 vcc, s27, v0
	s_cmp_lg_u64 vcc, 0
	s_cselect_b64 s[4:5], -1, 0
	s_cbranch_vccnz .LBB0_584

.LBB0_537:
	s_mov_b64 s[4:5], 0x7e000
	v_lshl_add_u64 v[70:71], v[226:227], 0, s[4:5]
	s_mov_b32 s4, m0
	s_mov_b32 m0, s84
	s_nop 0
	global_load_lds_dwordx4 v[70:71], off
	s_mov_b32 m0, s4
	ds_read_b64_tr_b16 v[166:167], v228 offset:36864
	ds_read_b64_tr_b16 v[168:169], v228 offset:37376
	v_add_f32_e32 v70, v50, v51
	v_add_f32_e32 v70, v52, v70
	v_add_f32_e32 v70, v53, v70
	v_add_f32_e32 v70, v54, v70
	v_add_f32_e32 v86, v55, v70
	s_waitcnt lgkmcnt(9)
	v_mfma_f32_32x32x16_bf16 v[66:81], v[66:69], v[110:113], 0
	v_cvt_pk_bf16_f32 v134, v50, v51
	v_cvt_pk_bf16_f32 v135, v52, v53
	ds_read_b64_tr_b16 v[158:159], v228 offset:40960
	ds_read_b64_tr_b16 v[160:161], v228 offset:41472
	v_add_f32_e32 v50, v56, v86
	v_add_f32_e32 v50, v57, v50
	v_add_f32_e32 v50, v58, v50
	v_add_f32_e32 v50, v59, v50
	v_cvt_pk_bf16_f32 v136, v54, v55
	v_cvt_pk_bf16_f32 v137, v56, v57
	s_waitcnt lgkmcnt(10)
	v_mfma_f32_32x32x16_bf16 v[82:97], v[82:85], v[110:113], 0
	ds_read_b64_tr_b16 v[146:147], v228 offset:37888
	ds_read_b64_tr_b16 v[148:149], v228 offset:38400
	s_waitcnt lgkmcnt(11)
	v_mfma_f32_32x32x16_bf16 v[66:81], v[178:181], v[106:109], v[66:81]
	v_add_f32_e32 v50, v60, v50
	v_add_f32_e32 v50, v61, v50
	v_add_f32_e32 v50, v62, v50
	v_add_f32_e32 v50, v63, v50
	v_cvt_pk_bf16_f32 v130, v58, v59
	v_cvt_pk_bf16_f32 v131, v60, v61
	ds_read_b64_tr_b16 v[150:151], v228 offset:41984
	ds_read_b64_tr_b16 v[152:153], v228 offset:42496
	v_add_f32_e32 v50, v64, v50
	v_add_f32_e32 v50, v65, v50
	v_add_f32_e32 v50, v34, v50
	v_add_f32_e32 v50, v35, v50
	v_cvt_pk_bf16_f32 v132, v62, v63
	v_cvt_pk_bf16_f32 v133, v64, v65
	s_waitcnt lgkmcnt(12)
	v_mfma_f32_32x32x16_bf16 v[82:97], v[162:165], v[106:109], v[82:97]
	ds_read_b64_tr_b16 v[162:163], v228 offset:38912
	ds_read_b64_tr_b16 v[164:165], v228 offset:39424
	s_waitcnt lgkmcnt(13)
	v_mfma_f32_32x32x16_bf16 v[66:81], v[138:141], v[102:105], v[66:81]
	v_add_f32_e32 v50, v36, v50
	v_add_f32_e32 v50, v37, v50
	v_add_f32_e32 v50, v38, v50
	v_add_f32_e32 v50, v39, v50
	v_cvt_pk_bf16_f32 v122, v34, v35
	v_cvt_pk_bf16_f32 v123, v36, v37
	ds_read_b64_tr_b16 v[138:139], v228 offset:43008
	ds_read_b64_tr_b16 v[140:141], v228 offset:43520
	v_add_f32_e32 v34, v40, v50
	v_add_f32_e32 v34, v41, v34
	v_add_f32_e32 v34, v42, v34
	v_add_f32_e32 v34, v43, v34
	v_cvt_pk_bf16_f32 v124, v38, v39
	v_cvt_pk_bf16_f32 v125, v40, v41
	s_waitcnt lgkmcnt(14)
	v_mfma_f32_32x32x16_bf16 v[82:97], v[174:177], v[102:105], v[82:97]
	ds_read_b64_tr_b16 v[142:143], v228 offset:39936
	ds_read_b64_tr_b16 v[144:145], v228 offset:40448
	s_waitcnt lgkmcnt(14)
	v_mfma_f32_32x32x16_bf16 v[66:81], v[154:157], v[98:101], v[66:81]
	v_add_f32_e32 v34, v44, v34
	v_add_f32_e32 v34, v45, v34
	v_add_f32_e32 v34, v46, v34
	v_add_f32_e32 v34, v47, v34
	v_cvt_pk_bf16_f32 v118, v42, v43
	v_cvt_pk_bf16_f32 v119, v44, v45
	ds_read_b64_tr_b16 v[154:155], v228 offset:44032
	ds_read_b64_tr_b16 v[156:157], v228 offset:44544
	v_add_f32_e32 v34, v48, v34
	v_add_f32_e32 v34, v49, v34
	v_mfma_f32_32x32x16_bf16 v[82:97], v[170:173], v[98:101], v[82:97]
	v_add_f32_e32 v170, 0, v34
	v_cvt_pk_bf16_f32 v120, v46, v47
	v_cvt_pk_bf16_f32 v121, v48, v49
	ds_read_b128 v[34:37], v207 offset:20480
	v_add_f32_e32 v219, v184, v170
	s_waitcnt lgkmcnt(0)
	v_mfma_f32_32x32x16_bf16 v[66:81], v[34:37], v[114:117], v[66:81]
	ds_read_b128 v[34:37], v207 offset:20992
	s_waitcnt lgkmcnt(0)
	v_mfma_f32_32x32x16_bf16 v[82:97], v[34:37], v[114:117], v[82:97]
	ds_read_b128 v[34:37], v207 offset:22528
	s_waitcnt lgkmcnt(0)
	v_mfma_f32_32x32x16_bf16 v[66:81], v[34:37], v[126:129], v[66:81]
	ds_read_b128 v[34:37], v207 offset:23040
	s_waitcnt lgkmcnt(0)
	v_mfma_f32_32x32x16_bf16 v[82:97], v[34:37], v[126:129], v[82:97]
	s_nop 8
	v_add_f32_e64 v50, v66, -v224
	v_add_f32_e64 v51, v67, -v224
	v_add_f32_e64 v52, v68, -v224
	v_add_f32_e64 v53, v69, -v224
	v_add_f32_e64 v54, v70, -v224
	v_add_f32_e64 v55, v71, -v224
	v_pk_add_f32 v[56:57], v[72:73], v[224:225] op_sel_hi:[1,0] neg_lo:[0,1] neg_hi:[0,1]
	v_pk_add_f32 v[58:59], v[74:75], v[224:225] op_sel_hi:[1,0] neg_lo:[0,1] neg_hi:[0,1]
	v_pk_add_f32 v[60:61], v[76:77], v[224:225] op_sel_hi:[1,0] neg_lo:[0,1] neg_hi:[0,1]
	v_pk_add_f32 v[62:63], v[78:79], v[224:225] op_sel_hi:[1,0] neg_lo:[0,1] neg_hi:[0,1]
	v_pk_add_f32 v[34:35], v[82:83], v[224:225] op_sel_hi:[1,0] neg_lo:[0,1] neg_hi:[0,1]
	v_pk_add_f32 v[36:37], v[84:85], v[224:225] op_sel_hi:[1,0] neg_lo:[0,1] neg_hi:[0,1]
	v_pk_add_f32 v[38:39], v[86:87], v[224:225] op_sel_hi:[1,0] neg_lo:[0,1] neg_hi:[0,1]
	v_pk_add_f32 v[40:41], v[88:89], v[224:225] op_sel_hi:[1,0] neg_lo:[0,1] neg_hi:[0,1]
	v_pk_add_f32 v[42:43], v[90:91], v[224:225] op_sel_hi:[1,0] neg_lo:[0,1] neg_hi:[0,1]
	v_pk_add_f32 v[44:45], v[92:93], v[224:225] op_sel_hi:[1,0] neg_lo:[0,1] neg_hi:[0,1]
	v_pk_add_f32 v[46:47], v[94:95], v[224:225] op_sel_hi:[1,0] neg_lo:[0,1] neg_hi:[0,1]
	v_pk_add_f32 v[64:65], v[80:81], v[224:225] op_sel_hi:[1,0] neg_lo:[0,1] neg_hi:[0,1]
	v_pk_add_f32 v[48:49], v[96:97], v[224:225] op_sel_hi:[1,0] neg_lo:[0,1] neg_hi:[0,1]
	s_cmp_lg_u32 0, -1
	s_cselect_b32 s4, 0, 0
	s_add_i32 s6, s4, s85
	v_lshl_add_u64 v[66:67], v[182:183], 0, s[40:41]
	s_add_i32 s4, s6, 0x3000
	s_mov_b32 s5, m0
	s_mov_b32 m0, s4
	s_nop 0
	global_load_lds_dwordx4 v[66:67], off
	s_mov_b32 m0, s5
	s_mov_b64 s[4:5], 0xfa0000
	v_lshl_add_u64 v[66:67], v[222:223], 0, s[4:5]
	s_add_i32 s6, s6, 0xf000
	s_mov_b32 s4, m0
	s_mov_b32 m0, s6
	s_nop 0
	global_load_lds_dwordx4 v[66:67], off
	s_mov_b32 m0, s4
	v_max_f32_e32 v66, v50, v51
	v_max3_f32 v67, v52, v53, v35
	v_max3_f32 v66, v66, v34, v36
	v_max3_f32 v66, v66, v37, v54
	v_max3_f32 v67, v67, v56, v57
	v_max3_f32 v66, v66, v55, v38
	v_max3_f32 v67, v67, v40, v41
	v_max3_f32 v66, v66, v39, v58
	v_max3_f32 v67, v67, v60, v61
	v_max3_f32 v66, v66, v59, v42
	v_max3_f32 v67, v67, v44, v45
	v_max3_f32 v66, v66, v43, v62
	v_max3_f32 v67, v67, v64, v65
	v_max3_f32 v66, v66, v63, v46
	v_max3_f32 v67, v67, v48, v49
	v_max3_f32 v66, v66, v47, v67
	v_mov_b32_e32 v67, v66
	s_nop 1
	v_permlane32_swap_b32_e32 v66, v67
	v_max_f32_e32 v66, v66, v67
	v_cmp_lt_f32_e32 vcc, s27, v66
	s_cmp_lg_u64 vcc, 0
	s_cselect_b64 s[4:5], -1, 0
	s_cbranch_vccnz .LBB0_587

.LBB0_540:
	s_mov_b64 s[4:5], 0x7f000
	s_cmp_lg_u32 0, -1
	v_lshl_add_u64 v[70:71], v[226:227], 0, s[4:5]
	s_cselect_b32 s4, 0, 0
	s_add_i32 s4, s4, s86
	s_addk_i32 s4, 0x3000
	s_mov_b32 s5, m0
	s_mov_b32 m0, s4
	s_nop 0
	global_load_lds_dwordx4 v[70:71], off
	s_mov_b32 m0, s5
	ds_read_b64_tr_b16 v[166:167], v228 offset:49152
	ds_read_b64_tr_b16 v[168:169], v228 offset:49664
	v_add_f32_e32 v70, v50, v51
	v_add_f32_e32 v70, v52, v70
	v_add_f32_e32 v70, v53, v70
	v_add_f32_e32 v70, v54, v70
	v_add_f32_e32 v86, v55, v70
	s_waitcnt lgkmcnt(9)
	v_mfma_f32_32x32x16_bf16 v[66:81], v[66:69], v[110:113], 0
	v_cvt_pk_bf16_f32 v134, v50, v51
	v_cvt_pk_bf16_f32 v135, v52, v53
	ds_read_b64_tr_b16 v[154:155], v228 offset:53248
	ds_read_b64_tr_b16 v[156:157], v228 offset:53760
	v_add_f32_e32 v50, v56, v86
	v_add_f32_e32 v50, v57, v50
	v_add_f32_e32 v50, v58, v50
	v_add_f32_e32 v50, v59, v50
	v_cvt_pk_bf16_f32 v136, v54, v55
	v_cvt_pk_bf16_f32 v137, v56, v57
	s_waitcnt lgkmcnt(10)
	v_mfma_f32_32x32x16_bf16 v[82:97], v[82:85], v[110:113], 0
	ds_read_b64_tr_b16 v[146:147], v228 offset:50176
	ds_read_b64_tr_b16 v[148:149], v228 offset:50688
	s_waitcnt lgkmcnt(11)
	v_mfma_f32_32x32x16_bf16 v[66:81], v[186:189], v[106:109], v[66:81]
	v_add_f32_e32 v50, v60, v50
	v_add_f32_e32 v50, v61, v50
	v_add_f32_e32 v50, v62, v50
	v_add_f32_e32 v50, v63, v50
	v_cvt_pk_bf16_f32 v130, v58, v59
	v_cvt_pk_bf16_f32 v131, v60, v61
	ds_read_b64_tr_b16 v[150:151], v228 offset:54272
	ds_read_b64_tr_b16 v[152:153], v228 offset:54784
	v_add_f32_e32 v50, v64, v50
	v_add_f32_e32 v50, v65, v50
	v_add_f32_e32 v50, v34, v50
	v_add_f32_e32 v50, v35, v50
	v_cvt_pk_bf16_f32 v132, v62, v63
	v_cvt_pk_bf16_f32 v133, v64, v65
	s_waitcnt lgkmcnt(12)
	v_mfma_f32_32x32x16_bf16 v[82:97], v[182:185], v[106:109], v[82:97]
	ds_read_b64_tr_b16 v[162:163], v228 offset:51200
	ds_read_b64_tr_b16 v[164:165], v228 offset:51712
	s_waitcnt lgkmcnt(13)
	v_mfma_f32_32x32x16_bf16 v[66:81], v[178:181], v[102:105], v[66:81]
	v_add_f32_e32 v50, v36, v50
	v_add_f32_e32 v50, v37, v50
	v_add_f32_e32 v50, v38, v50
	v_add_f32_e32 v50, v39, v50
	v_cvt_pk_bf16_f32 v122, v34, v35
	v_cvt_pk_bf16_f32 v123, v36, v37
	ds_read_b64_tr_b16 v[138:139], v228 offset:55296
	ds_read_b64_tr_b16 v[140:141], v228 offset:55808
	v_add_f32_e32 v34, v40, v50
	v_add_f32_e32 v34, v41, v34
	v_add_f32_e32 v34, v42, v34
	v_add_f32_e32 v34, v43, v34
	v_cvt_pk_bf16_f32 v124, v38, v39
	v_cvt_pk_bf16_f32 v125, v40, v41
	s_waitcnt lgkmcnt(14)
	v_mfma_f32_32x32x16_bf16 v[82:97], v[158:161], v[102:105], v[82:97]
	ds_read_b64_tr_b16 v[142:143], v228 offset:52224
	ds_read_b64_tr_b16 v[144:145], v228 offset:52736
	s_waitcnt lgkmcnt(14)
	v_mfma_f32_32x32x16_bf16 v[66:81], v[174:177], v[98:101], v[66:81]
	v_add_f32_e32 v34, v44, v34
	v_add_f32_e32 v34, v45, v34
	v_add_f32_e32 v34, v46, v34
	v_add_f32_e32 v34, v47, v34
	v_cvt_pk_bf16_f32 v118, v42, v43
	v_cvt_pk_bf16_f32 v119, v44, v45
	ds_read_b64_tr_b16 v[158:159], v228 offset:56320
	ds_read_b64_tr_b16 v[160:161], v228 offset:56832
	v_add_f32_e32 v34, v48, v34
	v_add_f32_e32 v34, v49, v34
	v_mfma_f32_32x32x16_bf16 v[82:97], v[170:173], v[98:101], v[82:97]
	v_add_f32_e32 v170, 0, v34
	v_cvt_pk_bf16_f32 v120, v46, v47
	v_cvt_pk_bf16_f32 v121, v48, v49
	ds_read_b128 v[34:37], v207 offset:32768
	v_add_f32_e32 v219, v219, v170
	s_waitcnt lgkmcnt(0)
	v_mfma_f32_32x32x16_bf16 v[66:81], v[34:37], v[114:117], v[66:81]
	ds_read_b128 v[34:37], v207 offset:33280
	s_waitcnt lgkmcnt(0)
	v_mfma_f32_32x32x16_bf16 v[82:97], v[34:37], v[114:117], v[82:97]
	ds_read_b128 v[34:37], v207 offset:34816
	s_waitcnt lgkmcnt(0)
	v_mfma_f32_32x32x16_bf16 v[66:81], v[34:37], v[126:129], v[66:81]
	ds_read_b128 v[34:37], v207 offset:35328
	s_waitcnt lgkmcnt(0)
	v_mfma_f32_32x32x16_bf16 v[82:97], v[34:37], v[126:129], v[82:97]
	s_nop 8
	v_add_f32_e64 v50, v66, -v224
	v_add_f32_e64 v51, v67, -v224
	v_add_f32_e64 v52, v68, -v224
	v_add_f32_e64 v53, v69, -v224
	v_add_f32_e64 v54, v70, -v224
	v_add_f32_e64 v55, v71, -v224
	v_pk_add_f32 v[56:57], v[72:73], v[224:225] op_sel_hi:[1,0] neg_lo:[0,1] neg_hi:[0,1]
	v_pk_add_f32 v[58:59], v[74:75], v[224:225] op_sel_hi:[1,0] neg_lo:[0,1] neg_hi:[0,1]
	v_pk_add_f32 v[60:61], v[76:77], v[224:225] op_sel_hi:[1,0] neg_lo:[0,1] neg_hi:[0,1]
	v_pk_add_f32 v[62:63], v[78:79], v[224:225] op_sel_hi:[1,0] neg_lo:[0,1] neg_hi:[0,1]
	v_pk_add_f32 v[34:35], v[82:83], v[224:225] op_sel_hi:[1,0] neg_lo:[0,1] neg_hi:[0,1]
	v_pk_add_f32 v[36:37], v[84:85], v[224:225] op_sel_hi:[1,0] neg_lo:[0,1] neg_hi:[0,1]
	v_pk_add_f32 v[38:39], v[86:87], v[224:225] op_sel_hi:[1,0] neg_lo:[0,1] neg_hi:[0,1]
	v_pk_add_f32 v[40:41], v[88:89], v[224:225] op_sel_hi:[1,0] neg_lo:[0,1] neg_hi:[0,1]
	v_pk_add_f32 v[42:43], v[90:91], v[224:225] op_sel_hi:[1,0] neg_lo:[0,1] neg_hi:[0,1]
	v_pk_add_f32 v[44:45], v[92:93], v[224:225] op_sel_hi:[1,0] neg_lo:[0,1] neg_hi:[0,1]
	v_pk_add_f32 v[46:47], v[94:95], v[224:225] op_sel_hi:[1,0] neg_lo:[0,1] neg_hi:[0,1]
	v_pk_add_f32 v[64:65], v[80:81], v[224:225] op_sel_hi:[1,0] neg_lo:[0,1] neg_hi:[0,1]
	v_pk_add_f32 v[48:49], v[96:97], v[224:225] op_sel_hi:[1,0] neg_lo:[0,1] neg_hi:[0,1]
	v_lshl_add_u64 v[66:67], v[222:223], 0, s[38:39]
	s_mov_b32 s4, m0
	s_mov_b32 m0, s71
	s_nop 0
	global_load_lds_dwordx4 v[66:67], off
	s_mov_b32 m0, s4
	v_max_f32_e32 v66, v50, v51
	v_max3_f32 v67, v52, v53, v35
	v_max3_f32 v66, v66, v34, v36
	v_max3_f32 v66, v66, v37, v54
	v_max3_f32 v67, v67, v56, v57
	v_max3_f32 v66, v66, v55, v38
	v_max3_f32 v67, v67, v40, v41
	v_max3_f32 v66, v66, v39, v58
	v_max3_f32 v67, v67, v60, v61
	v_max3_f32 v66, v66, v59, v42
	v_max3_f32 v67, v67, v44, v45
	v_max3_f32 v66, v66, v43, v62
	v_max3_f32 v67, v67, v64, v65
	v_max3_f32 v66, v66, v63, v46
	v_max3_f32 v67, v67, v48, v49
	v_max3_f32 v66, v66, v47, v67
	v_mov_b32_e32 v67, v66
	s_nop 1
	v_permlane32_swap_b32_e32 v66, v67
	v_max_f32_e32 v66, v66, v67
	v_cmp_lt_f32_e32 vcc, s27, v66
	s_cmp_lg_u64 vcc, 0
	s_cselect_b64 s[4:5], -1, 0
	s_cbranch_vccnz .LBB0_590

.LBB0_543:
	ds_read_b64_tr_b16 v[166:167], v228 offset:61440
	ds_read_b64_tr_b16 v[168:169], v228 offset:61952
	v_add_f32_e32 v70, v50, v51
	v_add_f32_e32 v70, v52, v70
	v_add_f32_e32 v70, v53, v70
	v_add_f32_e32 v70, v54, v70
	v_add_f32_e32 v86, v55, v70
	s_waitcnt lgkmcnt(9)
	v_mfma_f32_32x32x16_bf16 v[66:81], v[66:69], v[110:113], 0
	v_cvt_pk_bf16_f32 v134, v50, v51
	v_cvt_pk_bf16_f32 v135, v52, v53
	ds_read_b64_tr_b16 v[158:159], v229 offset:28672
	ds_read_b64_tr_b16 v[160:161], v229 offset:29184
	v_add_f32_e32 v50, v56, v86
	v_add_f32_e32 v50, v57, v50
	v_add_f32_e32 v50, v58, v50
	v_add_f32_e32 v50, v59, v50
	v_cvt_pk_bf16_f32 v136, v54, v55
	v_cvt_pk_bf16_f32 v137, v56, v57
	s_waitcnt lgkmcnt(10)
	v_mfma_f32_32x32x16_bf16 v[82:97], v[82:85], v[110:113], 0
	ds_read_b64_tr_b16 v[146:147], v228 offset:62464
	ds_read_b64_tr_b16 v[148:149], v228 offset:62976
	s_waitcnt lgkmcnt(11)
	v_mfma_f32_32x32x16_bf16 v[66:81], v[186:189], v[106:109], v[66:81]
	v_add_f32_e32 v50, v60, v50
	v_add_f32_e32 v50, v61, v50
	v_add_f32_e32 v50, v62, v50
	v_add_f32_e32 v50, v63, v50
	v_cvt_pk_bf16_f32 v130, v58, v59
	v_cvt_pk_bf16_f32 v131, v60, v61
	ds_read_b64_tr_b16 v[150:151], v229 offset:29696
	ds_read_b64_tr_b16 v[152:153], v229 offset:30208
	v_add_f32_e32 v50, v64, v50
	v_add_f32_e32 v50, v65, v50
	v_add_f32_e32 v50, v34, v50
	v_add_f32_e32 v50, v35, v50
	v_cvt_pk_bf16_f32 v132, v62, v63
	v_cvt_pk_bf16_f32 v133, v64, v65
	s_waitcnt lgkmcnt(12)
	v_mfma_f32_32x32x16_bf16 v[82:97], v[182:185], v[106:109], v[82:97]
	ds_read_b64_tr_b16 v[162:163], v228 offset:63488
	ds_read_b64_tr_b16 v[164:165], v228 offset:64000
	s_waitcnt lgkmcnt(13)
	v_mfma_f32_32x32x16_bf16 v[66:81], v[178:181], v[102:105], v[66:81]
	v_add_f32_e32 v50, v36, v50
	v_add_f32_e32 v50, v37, v50
	v_add_f32_e32 v50, v38, v50
	v_add_f32_e32 v50, v39, v50
	v_cvt_pk_bf16_f32 v122, v34, v35
	v_cvt_pk_bf16_f32 v123, v36, v37
	ds_read_b64_tr_b16 v[138:139], v229 offset:30720
	ds_read_b64_tr_b16 v[140:141], v229 offset:31232
	v_add_f32_e32 v34, v40, v50
	v_add_f32_e32 v34, v41, v34
	v_add_f32_e32 v34, v42, v34
	v_add_f32_e32 v34, v43, v34
	v_cvt_pk_bf16_f32 v124, v38, v39
	v_cvt_pk_bf16_f32 v125, v40, v41
	s_waitcnt lgkmcnt(14)
	v_mfma_f32_32x32x16_bf16 v[82:97], v[154:157], v[102:105], v[82:97]
	ds_read_b64_tr_b16 v[142:143], v228 offset:64512
	ds_read_b64_tr_b16 v[144:145], v228 offset:65024
	s_waitcnt lgkmcnt(14)
	v_mfma_f32_32x32x16_bf16 v[66:81], v[174:177], v[98:101], v[66:81]
	v_add_f32_e32 v34, v44, v34
	v_add_f32_e32 v34, v45, v34
	v_add_f32_e32 v34, v46, v34
	v_add_f32_e32 v34, v47, v34
	v_cvt_pk_bf16_f32 v118, v42, v43
	v_cvt_pk_bf16_f32 v119, v44, v45
	ds_read_b64_tr_b16 v[154:155], v229 offset:31744
	ds_read_b64_tr_b16 v[156:157], v229 offset:32256
	v_add_f32_e32 v34, v48, v34
	v_add_f32_e32 v34, v49, v34
	v_mfma_f32_32x32x16_bf16 v[82:97], v[170:173], v[98:101], v[82:97]
	v_add_f32_e32 v170, 0, v34
	v_cvt_pk_bf16_f32 v120, v46, v47
	v_cvt_pk_bf16_f32 v121, v48, v49
	ds_read_b128 v[34:37], v207 offset:8192
	v_add_f32_e32 v178, v219, v170
	s_waitcnt lgkmcnt(0)
	v_mfma_f32_32x32x16_bf16 v[66:81], v[34:37], v[114:117], v[66:81]
	ds_read_b128 v[34:37], v207 offset:8704
	s_waitcnt lgkmcnt(0)
	v_mfma_f32_32x32x16_bf16 v[82:97], v[34:37], v[114:117], v[82:97]
	ds_read_b128 v[34:37], v207 offset:10240
	s_waitcnt lgkmcnt(0)
	v_mfma_f32_32x32x16_bf16 v[66:81], v[34:37], v[126:129], v[66:81]
	ds_read_b128 v[34:37], v207 offset:10752
	s_waitcnt lgkmcnt(0)
	v_mfma_f32_32x32x16_bf16 v[82:97], v[34:37], v[126:129], v[82:97]
	s_nop 8
	v_add_f32_e64 v50, v66, -v224
	v_add_f32_e64 v51, v67, -v224
	v_add_f32_e64 v52, v68, -v224
	v_add_f32_e64 v53, v69, -v224
	v_add_f32_e64 v54, v70, -v224
	v_add_f32_e64 v55, v71, -v224
	v_pk_add_f32 v[56:57], v[72:73], v[224:225] op_sel_hi:[1,0] neg_lo:[0,1] neg_hi:[0,1]
	v_pk_add_f32 v[58:59], v[74:75], v[224:225] op_sel_hi:[1,0] neg_lo:[0,1] neg_hi:[0,1]
	v_pk_add_f32 v[60:61], v[76:77], v[224:225] op_sel_hi:[1,0] neg_lo:[0,1] neg_hi:[0,1]
	v_pk_add_f32 v[62:63], v[78:79], v[224:225] op_sel_hi:[1,0] neg_lo:[0,1] neg_hi:[0,1]
	v_pk_add_f32 v[34:35], v[82:83], v[224:225] op_sel_hi:[1,0] neg_lo:[0,1] neg_hi:[0,1]
	v_pk_add_f32 v[36:37], v[84:85], v[224:225] op_sel_hi:[1,0] neg_lo:[0,1] neg_hi:[0,1]
	v_pk_add_f32 v[38:39], v[86:87], v[224:225] op_sel_hi:[1,0] neg_lo:[0,1] neg_hi:[0,1]
	v_pk_add_f32 v[40:41], v[88:89], v[224:225] op_sel_hi:[1,0] neg_lo:[0,1] neg_hi:[0,1]
	v_pk_add_f32 v[42:43], v[90:91], v[224:225] op_sel_hi:[1,0] neg_lo:[0,1] neg_hi:[0,1]
	v_pk_add_f32 v[44:45], v[92:93], v[224:225] op_sel_hi:[1,0] neg_lo:[0,1] neg_hi:[0,1]
	v_pk_add_f32 v[46:47], v[94:95], v[224:225] op_sel_hi:[1,0] neg_lo:[0,1] neg_hi:[0,1]
	v_pk_add_f32 v[64:65], v[80:81], v[224:225] op_sel_hi:[1,0] neg_lo:[0,1] neg_hi:[0,1]
	v_pk_add_f32 v[48:49], v[96:97], v[224:225] op_sel_hi:[1,0] neg_lo:[0,1] neg_hi:[0,1]
	v_lshl_add_u64 v[66:67], v[222:223], 0, s[40:41]
	s_mov_b32 s4, m0
	s_mov_b32 m0, s36
	s_nop 0
	global_load_lds_dwordx4 v[66:67], off
	s_mov_b32 m0, s4
	v_max_f32_e32 v66, v50, v51
	v_max3_f32 v67, v52, v53, v35
	v_max3_f32 v66, v66, v34, v36
	v_max3_f32 v66, v66, v37, v54
	v_max3_f32 v67, v67, v56, v57
	v_max3_f32 v66, v66, v55, v38
	v_max3_f32 v67, v67, v40, v41
	v_max3_f32 v66, v66, v39, v58
	v_max3_f32 v67, v67, v60, v61
	v_max3_f32 v66, v66, v59, v42
	v_max3_f32 v67, v67, v44, v45
	v_max3_f32 v66, v66, v43, v62
	v_max3_f32 v67, v67, v64, v65
	v_max3_f32 v66, v66, v63, v46
	v_max3_f32 v67, v67, v48, v49
	v_max3_f32 v66, v66, v47, v67
	v_mov_b32_e32 v67, v66
	s_nop 1
	v_permlane32_swap_b32_e32 v66, v67
	v_max_f32_e32 v66, v66, v67
	v_cmp_lt_f32_e32 vcc, s27, v66
	s_cmp_lg_u64 vcc, 0
	s_cselect_b64 s[4:5], -1, 0
	s_cbranch_vccnz .LBB0_593

.LBB0_546:
	ds_read_b64_tr_b16 v[154:155], v228 offset:36864
	ds_read_b64_tr_b16 v[156:157], v228 offset:37376
	v_add_f32_e32 v70, v50, v51
	v_add_f32_e32 v70, v52, v70
	v_add_f32_e32 v70, v53, v70
	v_add_f32_e32 v70, v54, v70
	v_add_f32_e32 v86, v55, v70
	s_waitcnt lgkmcnt(9)
	v_mfma_f32_32x32x16_bf16 v[66:81], v[66:69], v[110:113], 0
	v_cvt_pk_bf16_f32 v134, v50, v51
	v_cvt_pk_bf16_f32 v135, v52, v53
	ds_read_b64_tr_b16 v[138:139], v228 offset:40960
	ds_read_b64_tr_b16 v[140:141], v228 offset:41472
	v_add_f32_e32 v50, v56, v86
	v_add_f32_e32 v50, v57, v50
	v_add_f32_e32 v50, v58, v50
	v_add_f32_e32 v50, v59, v50
	v_cvt_pk_bf16_f32 v136, v54, v55
	v_cvt_pk_bf16_f32 v137, v56, v57
	s_waitcnt lgkmcnt(10)
	v_mfma_f32_32x32x16_bf16 v[82:97], v[82:85], v[110:113], 0
	ds_read_b64_tr_b16 v[110:111], v228 offset:37888
	ds_read_b64_tr_b16 v[112:113], v228 offset:38400
	s_waitcnt lgkmcnt(11)
	v_mfma_f32_32x32x16_bf16 v[66:81], v[174:177], v[106:109], v[66:81]
	v_add_f32_e32 v50, v60, v50
	v_add_f32_e32 v50, v61, v50
	v_add_f32_e32 v50, v62, v50
	v_add_f32_e32 v50, v63, v50
	v_cvt_pk_bf16_f32 v130, v58, v59
	v_cvt_pk_bf16_f32 v131, v60, v61
	ds_read_b64_tr_b16 v[142:143], v228 offset:41984
	ds_read_b64_tr_b16 v[144:145], v228 offset:42496
	v_add_f32_e32 v50, v64, v50
	v_add_f32_e32 v50, v65, v50
	v_add_f32_e32 v50, v34, v50
	v_add_f32_e32 v50, v35, v50
	v_cvt_pk_bf16_f32 v132, v62, v63
	v_cvt_pk_bf16_f32 v133, v64, v65
	s_waitcnt lgkmcnt(12)
	v_mfma_f32_32x32x16_bf16 v[82:97], v[170:173], v[106:109], v[82:97]
	ds_read_b64_tr_b16 v[150:151], v228 offset:38912
	ds_read_b64_tr_b16 v[152:153], v228 offset:39424
	s_waitcnt lgkmcnt(13)
	v_mfma_f32_32x32x16_bf16 v[66:81], v[166:169], v[102:105], v[66:81]
	v_add_f32_e32 v50, v36, v50
	v_add_f32_e32 v50, v37, v50
	v_add_f32_e32 v50, v38, v50
	v_add_f32_e32 v50, v39, v50
	v_cvt_pk_bf16_f32 v122, v34, v35
	v_cvt_pk_bf16_f32 v123, v36, v37
	ds_read_b64_tr_b16 v[106:107], v228 offset:43008
	ds_read_b64_tr_b16 v[108:109], v228 offset:43520
	v_add_f32_e32 v34, v40, v50
	v_add_f32_e32 v34, v41, v34
	v_add_f32_e32 v34, v42, v34
	v_add_f32_e32 v34, v43, v34
	v_cvt_pk_bf16_f32 v124, v38, v39
	v_cvt_pk_bf16_f32 v125, v40, v41
	s_waitcnt lgkmcnt(14)
	v_mfma_f32_32x32x16_bf16 v[82:97], v[146:149], v[102:105], v[82:97]
	ds_read_b64_tr_b16 v[102:103], v228 offset:39936
	ds_read_b64_tr_b16 v[104:105], v228 offset:40448
	s_waitcnt lgkmcnt(14)
	v_mfma_f32_32x32x16_bf16 v[66:81], v[162:165], v[98:101], v[66:81]
	v_add_f32_e32 v34, v44, v34
	v_add_f32_e32 v34, v45, v34
	v_add_f32_e32 v34, v46, v34
	v_add_f32_e32 v34, v47, v34
	v_cvt_pk_bf16_f32 v118, v42, v43
	v_cvt_pk_bf16_f32 v119, v44, v45
	ds_read_b64_tr_b16 v[146:147], v228 offset:44032
	ds_read_b64_tr_b16 v[148:149], v228 offset:44544
	v_add_f32_e32 v34, v48, v34
	v_add_f32_e32 v34, v49, v34
	v_mfma_f32_32x32x16_bf16 v[82:97], v[158:161], v[98:101], v[82:97]
	v_add_f32_e32 v98, 0, v34
	v_cvt_pk_bf16_f32 v120, v46, v47
	v_cvt_pk_bf16_f32 v121, v48, v49
	ds_read_b128 v[34:37], v207 offset:20480
	s_waitcnt lgkmcnt(0)
	v_mfma_f32_32x32x16_bf16 v[66:81], v[34:37], v[114:117], v[66:81]
	ds_read_b128 v[34:37], v207 offset:20992
	s_waitcnt lgkmcnt(0)
	v_mfma_f32_32x32x16_bf16 v[82:97], v[34:37], v[114:117], v[82:97]
	ds_read_b128 v[34:37], v207 offset:22528
	s_waitcnt lgkmcnt(0)
	v_mfma_f32_32x32x16_bf16 v[66:81], v[34:37], v[126:129], v[66:81]
	ds_read_b128 v[34:37], v207 offset:23040
	s_waitcnt lgkmcnt(0)
	v_mfma_f32_32x32x16_bf16 v[82:97], v[34:37], v[126:129], v[82:97]
	s_nop 8
	v_add_f32_e64 v50, v66, -v224
	v_add_f32_e64 v51, v67, -v224
	v_add_f32_e64 v52, v68, -v224
	v_add_f32_e64 v53, v69, -v224
	v_add_f32_e64 v54, v70, -v224
	v_add_f32_e64 v55, v71, -v224
	v_pk_add_f32 v[56:57], v[72:73], v[224:225] op_sel_hi:[1,0] neg_lo:[0,1] neg_hi:[0,1]
	v_pk_add_f32 v[58:59], v[74:75], v[224:225] op_sel_hi:[1,0] neg_lo:[0,1] neg_hi:[0,1]
	v_pk_add_f32 v[60:61], v[76:77], v[224:225] op_sel_hi:[1,0] neg_lo:[0,1] neg_hi:[0,1]
	v_pk_add_f32 v[62:63], v[78:79], v[224:225] op_sel_hi:[1,0] neg_lo:[0,1] neg_hi:[0,1]
	v_pk_add_f32 v[34:35], v[82:83], v[224:225] op_sel_hi:[1,0] neg_lo:[0,1] neg_hi:[0,1]
	v_pk_add_f32 v[36:37], v[84:85], v[224:225] op_sel_hi:[1,0] neg_lo:[0,1] neg_hi:[0,1]
	v_pk_add_f32 v[38:39], v[86:87], v[224:225] op_sel_hi:[1,0] neg_lo:[0,1] neg_hi:[0,1]
	v_pk_add_f32 v[40:41], v[88:89], v[224:225] op_sel_hi:[1,0] neg_lo:[0,1] neg_hi:[0,1]
	v_pk_add_f32 v[42:43], v[90:91], v[224:225] op_sel_hi:[1,0] neg_lo:[0,1] neg_hi:[0,1]
	v_pk_add_f32 v[44:45], v[92:93], v[224:225] op_sel_hi:[1,0] neg_lo:[0,1] neg_hi:[0,1]
	v_pk_add_f32 v[46:47], v[94:95], v[224:225] op_sel_hi:[1,0] neg_lo:[0,1] neg_hi:[0,1]
	v_pk_add_f32 v[64:65], v[80:81], v[224:225] op_sel_hi:[1,0] neg_lo:[0,1] neg_hi:[0,1]
	v_pk_add_f32 v[48:49], v[96:97], v[224:225] op_sel_hi:[1,0] neg_lo:[0,1] neg_hi:[0,1]
	v_max_f32_e32 v66, v50, v51
	v_max3_f32 v67, v52, v53, v35
	v_max3_f32 v66, v66, v34, v36
	v_max3_f32 v66, v66, v37, v54
	v_max3_f32 v67, v67, v56, v57
	v_max3_f32 v66, v66, v55, v38
	v_max3_f32 v67, v67, v40, v41
	v_max3_f32 v66, v66, v39, v58
	v_max3_f32 v67, v67, v60, v61
	v_max3_f32 v66, v66, v59, v42
	v_max3_f32 v67, v67, v44, v45
	v_max3_f32 v66, v66, v43, v62
	v_max3_f32 v67, v67, v64, v65
	v_max3_f32 v68, v66, v63, v46
	v_max3_f32 v67, v67, v48, v49
	v_max3_f32 v67, v68, v47, v67
	v_mov_b32_e32 v68, v67
	s_nop 1
	v_permlane32_swap_b32_e32 v67, v68
	v_max_f32_e32 v67, v67, v68
	v_cmp_lt_f32_e32 vcc, s27, v67
	s_cmp_lg_u64 vcc, 0
	v_add_f32_e32 v66, v178, v98
	s_cselect_b64 s[4:5], -1, 0
	s_cbranch_vccnz .LBB0_596

.LBB0_553:
	v_add_u32_e32 v186, s5, v228
	ds_read_b64_tr_b16 v[178:179], v186 offset:24576
	ds_read_b64_tr_b16 v[180:181], v186 offset:25088
	s_waitcnt lgkmcnt(9)
	v_mfma_f32_32x32x16_bf16 v[98:113], v[82:85], v[158:161], v[34:49]
	v_add_f32_e32 v86, v66, v67
	v_add_f32_e32 v86, v68, v86
	v_add_f32_e32 v86, v69, v86
	v_add_f32_e32 v86, v70, v86
	v_add_f32_e32 v86, v71, v86
	v_cvt_pk_bf16_f32 v154, v66, v67
	v_cvt_pk_bf16_f32 v155, v68, v69
	ds_read_b64_tr_b16 v[174:175], v186 offset:28672
	ds_read_b64_tr_b16 v[176:177], v186 offset:29184
	v_add_f32_e32 v66, v72, v86
	s_waitcnt lgkmcnt(10)
	v_mfma_f32_32x32x16_bf16 v[82:97], v[166:169], v[158:161], v[34:49]
	v_add_f32_e32 v66, v73, v66
	v_add_f32_e32 v66, v74, v66
	v_add_f32_e32 v130, v75, v66
	v_cvt_pk_bf16_f32 v156, v70, v71
	v_cvt_pk_bf16_f32 v157, v72, v73
	ds_read_b64_tr_b16 v[66:67], v186 offset:25600
	ds_read_b64_tr_b16 v[68:69], v186 offset:26112
	s_waitcnt lgkmcnt(11)
	v_mfma_f32_32x32x16_bf16 v[98:113], v[170:173], v[150:153], v[98:113]
	v_add_f32_e32 v70, v76, v130
	v_add_f32_e32 v70, v77, v70
	v_add_f32_e32 v70, v78, v70
	v_add_f32_e32 v130, v79, v70
	v_cvt_pk_bf16_f32 v146, v74, v75
	v_cvt_pk_bf16_f32 v147, v76, v77
	ds_read_b64_tr_b16 v[70:71], v186 offset:29696
	ds_read_b64_tr_b16 v[72:73], v186 offset:30208
	s_waitcnt lgkmcnt(12)
	v_mfma_f32_32x32x16_bf16 v[82:97], v[162:165], v[150:153], v[82:97]
	v_add_f32_e32 v74, v80, v130
	v_add_f32_e32 v74, v81, v74
	v_add_f32_e32 v74, v50, v74
	v_add_f32_e32 v130, v51, v74
	v_cvt_pk_bf16_f32 v148, v78, v79
	v_cvt_pk_bf16_f32 v149, v80, v81
	ds_read_b64_tr_b16 v[74:75], v186 offset:26624
	ds_read_b64_tr_b16 v[76:77], v186 offset:27136
	s_waitcnt lgkmcnt(13)
	v_mfma_f32_32x32x16_bf16 v[98:113], v[126:129], v[142:145], v[98:113]
	v_add_f32_e32 v78, v52, v130
	v_add_f32_e32 v78, v53, v78
	v_add_f32_e32 v78, v54, v78
	v_add_f32_e32 v78, v55, v78
	v_cvt_pk_bf16_f32 v138, v50, v51
	v_cvt_pk_bf16_f32 v139, v52, v53
	ds_read_b64_tr_b16 v[50:51], v186 offset:30720
	ds_read_b64_tr_b16 v[52:53], v186 offset:31232
	s_waitcnt lgkmcnt(14)
	v_mfma_f32_32x32x16_bf16 v[82:97], v[122:125], v[142:145], v[82:97]
	v_add_f32_e32 v78, v56, v78
	v_add_f32_e32 v78, v57, v78
	v_add_f32_e32 v78, v58, v78
	v_add_f32_e32 v78, v59, v78
	v_cvt_pk_bf16_f32 v140, v54, v55
	v_cvt_pk_bf16_f32 v141, v56, v57
	ds_read_b64_tr_b16 v[54:55], v186 offset:27648
	ds_read_b64_tr_b16 v[56:57], v186 offset:28160
	s_waitcnt lgkmcnt(14)
	v_mfma_f32_32x32x16_bf16 v[98:113], v[118:121], v[134:137], v[98:113]
	v_add_f32_e32 v78, v60, v78
	v_add_f32_e32 v78, v61, v78
	v_add_f32_e32 v78, v62, v78
	v_add_f32_e32 v78, v63, v78
	v_cvt_pk_bf16_f32 v130, v58, v59
	v_cvt_pk_bf16_f32 v131, v60, v61
	ds_read_b64_tr_b16 v[58:59], v186 offset:31744
	ds_read_b64_tr_b16 v[60:61], v186 offset:32256
	v_mfma_f32_32x32x16_bf16 v[82:97], v[114:117], v[134:137], v[82:97]
	v_add_f32_e32 v78, v64, v78
	v_add_f32_e32 v78, v65, v78
	v_cvt_pk_bf16_f32 v132, v62, v63
	v_cvt_pk_bf16_f32 v133, v64, v65
	v_lshl_add_u64 v[62:63], v[182:183], 0, s[62:63]
	s_add_i32 s4, s6, s40
	s_mov_b32 s5, m0
	s_mov_b32 m0, s4
	s_nop 0
	global_load_lds_dwordx4 v[62:63], off
	s_mov_b32 m0, s5
	v_lshl_add_u64 v[62:63], v[184:185], 0, s[94:95]
	s_add_i32 s4, s42, s37
	s_mov_b32 s5, m0
	s_mov_b32 m0, s4
	s_nop 0
	global_load_lds_dwordx4 v[62:63], off
	s_mov_b32 m0, s5
	v_max_f32_e32 v62, v99, v99
	v_max_f32_e32 v63, v98, v98
	v_max_f32_e32 v62, v63, v62
	v_max3_f32 v63, v100, v101, v83
	v_max3_f32 v62, v62, v82, v84
	v_max3_f32 v62, v62, v85, v102
	v_max3_f32 v63, v63, v104, v105
	v_max3_f32 v62, v62, v103, v86
	v_max3_f32 v63, v63, v88, v89
	v_max3_f32 v62, v62, v87, v106
	v_max3_f32 v63, v63, v108, v109
	v_max3_f32 v62, v62, v107, v90
	v_max3_f32 v63, v63, v92, v93
	v_max3_f32 v62, v62, v91, v110
	v_max3_f32 v63, v63, v112, v113
	v_max3_f32 v62, v62, v111, v94
	v_max3_f32 v63, v63, v96, v97
	v_max3_f32 v62, v62, v95, v63
	v_mov_b32_e32 v63, v62
	s_nop 1
	v_permlane32_swap_b32_e32 v62, v63
	v_max_f32_e32 v62, v62, v63
	v_cmp_lt_f32_e32 vcc, s27, v62
	s_cmp_lg_u64 vcc, 0
	v_add_f32_e32 v0, v0, v78
	s_cselect_b64 s[4:5], -1, 0
	s_cbranch_vccnz .LBB0_561

.LBB0_556:
	s_add_i32 s4, s42, 0x2000
	s_cmpk_lg_i32 s42, 0x4000
	s_cselect_b32 s7, s4, 0
	v_add_u32_e32 v186, s6, v228
	ds_read_b64_tr_b16 v[118:119], v186 offset:24576
	ds_read_b64_tr_b16 v[120:121], v186 offset:25088
	s_waitcnt lgkmcnt(9)
	v_mfma_f32_32x32x16_bf16 v[66:81], v[62:65], v[158:161], v[34:49]
	v_add_f32_e32 v50, v98, v99
	v_add_f32_e32 v50, v100, v50
	v_add_f32_e32 v50, v101, v50
	v_add_f32_e32 v50, v102, v50
	v_add_f32_e32 v50, v103, v50
	v_cvt_pk_bf16_f32 v154, v98, v99
	v_cvt_pk_bf16_f32 v155, v100, v101
	ds_read_b64_tr_b16 v[114:115], v186 offset:28672
	ds_read_b64_tr_b16 v[116:117], v186 offset:29184
	v_add_f32_e32 v50, v104, v50
	v_add_f32_e32 v50, v105, v50
	v_add_f32_e32 v50, v106, v50
	v_add_f32_e32 v130, v107, v50
	s_waitcnt lgkmcnt(10)
	v_mfma_f32_32x32x16_bf16 v[50:65], v[174:177], v[158:161], v[34:49]
	v_cvt_pk_bf16_f32 v156, v102, v103
	v_cvt_pk_bf16_f32 v157, v104, v105
	ds_read_b64_tr_b16 v[98:99], v186 offset:25600
	ds_read_b64_tr_b16 v[100:101], v186 offset:26112
	s_waitcnt lgkmcnt(11)
	v_mfma_f32_32x32x16_bf16 v[66:81], v[178:181], v[150:153], v[66:81]
	v_add_f32_e32 v102, v108, v130
	v_add_f32_e32 v102, v109, v102
	v_add_f32_e32 v102, v110, v102
	v_add_f32_e32 v130, v111, v102
	v_cvt_pk_bf16_f32 v146, v106, v107
	v_cvt_pk_bf16_f32 v147, v108, v109
	ds_read_b64_tr_b16 v[102:103], v186 offset:29696
	ds_read_b64_tr_b16 v[104:105], v186 offset:30208
	s_waitcnt lgkmcnt(12)
	v_mfma_f32_32x32x16_bf16 v[50:65], v[170:173], v[150:153], v[50:65]
	v_add_f32_e32 v106, v112, v130
	v_add_f32_e32 v106, v113, v106
	v_add_f32_e32 v106, v82, v106
	v_add_f32_e32 v130, v83, v106
	v_cvt_pk_bf16_f32 v148, v110, v111
	v_cvt_pk_bf16_f32 v149, v112, v113
	ds_read_b64_tr_b16 v[106:107], v186 offset:26624
	ds_read_b64_tr_b16 v[108:109], v186 offset:27136
	s_waitcnt lgkmcnt(13)
	v_mfma_f32_32x32x16_bf16 v[66:81], v[166:169], v[142:145], v[66:81]
	v_add_f32_e32 v110, v84, v130
	v_add_f32_e32 v110, v85, v110
	v_add_f32_e32 v110, v86, v110
	v_add_f32_e32 v130, v87, v110
	v_cvt_pk_bf16_f32 v138, v82, v83
	v_cvt_pk_bf16_f32 v139, v84, v85
	ds_read_b64_tr_b16 v[110:111], v186 offset:30720
	ds_read_b64_tr_b16 v[112:113], v186 offset:31232
	s_waitcnt lgkmcnt(14)
	v_mfma_f32_32x32x16_bf16 v[50:65], v[162:165], v[142:145], v[50:65]
	v_add_f32_e32 v82, v88, v130
	v_add_f32_e32 v82, v89, v82
	v_add_f32_e32 v82, v90, v82
	v_add_f32_e32 v82, v91, v82
	v_cvt_pk_bf16_f32 v140, v86, v87
	v_cvt_pk_bf16_f32 v141, v88, v89
	ds_read_b64_tr_b16 v[86:87], v186 offset:27648
	ds_read_b64_tr_b16 v[88:89], v186 offset:28160
	s_waitcnt lgkmcnt(14)
	v_mfma_f32_32x32x16_bf16 v[66:81], v[126:129], v[134:137], v[66:81]
	v_add_f32_e32 v82, v92, v82
	v_add_f32_e32 v82, v93, v82
	v_add_f32_e32 v82, v94, v82
	v_add_f32_e32 v82, v95, v82
	v_cvt_pk_bf16_f32 v130, v90, v91
	v_cvt_pk_bf16_f32 v131, v92, v93
	ds_read_b64_tr_b16 v[90:91], v186 offset:31744
	ds_read_b64_tr_b16 v[92:93], v186 offset:32256
	v_mfma_f32_32x32x16_bf16 v[50:65], v[122:125], v[134:137], v[50:65]
	v_add_f32_e32 v82, v96, v82
	v_add_f32_e32 v82, v97, v82
	v_add_f32_e32 v84, 0, v82
	v_cvt_pk_bf16_f32 v132, v94, v95
	v_cvt_pk_bf16_f32 v133, v96, v97
	v_lshl_add_u64 v[82:83], v[182:183], 0, s[64:65]
	s_add_i32 s4, s42, s40
	s_mov_b32 s5, m0
	s_mov_b32 m0, s4
	s_nop 0
	global_load_lds_dwordx4 v[82:83], off
	s_mov_b32 m0, s5
	v_max_f32_e32 v82, v67, v67
	v_max_f32_e32 v83, v66, v66
	v_max_f32_e32 v82, v83, v82
	s_nop 1
	v_max3_f32 v83, v68, v69, v51
	v_max3_f32 v82, v82, v50, v52
	v_max3_f32 v82, v82, v53, v70
	v_max3_f32 v83, v83, v72, v73
	v_max3_f32 v82, v82, v71, v54
	v_max3_f32 v83, v83, v56, v57
	v_max3_f32 v82, v82, v55, v74
	v_max3_f32 v83, v83, v76, v77
	v_max3_f32 v82, v82, v75, v58
	v_max3_f32 v83, v83, v60, v61
	v_max3_f32 v82, v82, v59, v78
	v_max3_f32 v83, v83, v80, v81
	v_max3_f32 v82, v82, v79, v62
	v_max3_f32 v83, v83, v64, v65
	v_max3_f32 v82, v82, v63, v83
	v_mov_b32_e32 v83, v82
	s_nop 1
	v_permlane32_swap_b32_e32 v82, v83
	v_max_f32_e32 v82, v82, v83
	v_lshl_add_u64 v[184:185], v[184:185], 0, s[14:15]
	s_add_i32 s4, s7, s37
	s_mov_b32 s5, m0
	s_mov_b32 m0, s4
	s_nop 0
	global_load_lds_dwordx4 v[184:185], off
	s_mov_b32 m0, s5
	v_cmp_lt_f32_e32 vcc, s27, v82
	s_cmp_lg_u64 vcc, 0
	v_add_f32_e32 v0, v0, v84
	s_cselect_b64 s[4:5], -1, 0
	s_cbranch_vccnz .LBB0_564

.LBB0_567:
	ds_read_b64_tr_b16 v[178:179], v228 offset:40960
	ds_read_b64_tr_b16 v[180:181], v228 offset:41472
	s_waitcnt lgkmcnt(9)
	v_mfma_f32_32x32x16_bf16 v[98:113], v[82:85], v[158:161], v[34:49]
	v_add_f32_e32 v86, v66, v67
	v_add_f32_e32 v86, v68, v86
	v_add_f32_e32 v86, v69, v86
	v_add_f32_e32 v86, v70, v86
	v_add_f32_e32 v86, v71, v86
	v_cvt_pk_bf16_f32 v154, v66, v67
	v_cvt_pk_bf16_f32 v155, v68, v69
	ds_read_b64_tr_b16 v[174:175], v228 offset:45056
	ds_read_b64_tr_b16 v[176:177], v228 offset:45568
	v_add_f32_e32 v66, v72, v86
	s_waitcnt lgkmcnt(10)
	v_mfma_f32_32x32x16_bf16 v[82:97], v[166:169], v[158:161], v[34:49]
	v_add_f32_e32 v66, v73, v66
	v_add_f32_e32 v66, v74, v66
	v_add_f32_e32 v130, v75, v66
	v_cvt_pk_bf16_f32 v156, v70, v71
	v_cvt_pk_bf16_f32 v157, v72, v73
	ds_read_b64_tr_b16 v[66:67], v228 offset:41984
	ds_read_b64_tr_b16 v[68:69], v228 offset:42496
	s_waitcnt lgkmcnt(11)
	v_mfma_f32_32x32x16_bf16 v[98:113], v[170:173], v[150:153], v[98:113]
	v_add_f32_e32 v70, v76, v130
	v_add_f32_e32 v70, v77, v70
	v_add_f32_e32 v70, v78, v70
	v_add_f32_e32 v130, v79, v70
	v_cvt_pk_bf16_f32 v146, v74, v75
	v_cvt_pk_bf16_f32 v147, v76, v77
	ds_read_b64_tr_b16 v[70:71], v228 offset:46080
	ds_read_b64_tr_b16 v[72:73], v228 offset:46592
	s_waitcnt lgkmcnt(12)
	v_mfma_f32_32x32x16_bf16 v[82:97], v[162:165], v[150:153], v[82:97]
	v_add_f32_e32 v74, v80, v130
	v_add_f32_e32 v74, v81, v74
	v_add_f32_e32 v74, v50, v74
	v_add_f32_e32 v130, v51, v74
	v_cvt_pk_bf16_f32 v148, v78, v79
	v_cvt_pk_bf16_f32 v149, v80, v81
	ds_read_b64_tr_b16 v[74:75], v228 offset:43008
	ds_read_b64_tr_b16 v[76:77], v228 offset:43520
	s_waitcnt lgkmcnt(13)
	v_mfma_f32_32x32x16_bf16 v[98:113], v[126:129], v[142:145], v[98:113]
	v_add_f32_e32 v78, v52, v130
	v_add_f32_e32 v78, v53, v78
	v_add_f32_e32 v78, v54, v78
	v_add_f32_e32 v78, v55, v78
	v_cvt_pk_bf16_f32 v138, v50, v51
	v_cvt_pk_bf16_f32 v139, v52, v53
	ds_read_b64_tr_b16 v[50:51], v228 offset:47104
	ds_read_b64_tr_b16 v[52:53], v228 offset:47616
	s_waitcnt lgkmcnt(14)
	v_mfma_f32_32x32x16_bf16 v[82:97], v[122:125], v[142:145], v[82:97]
	v_add_f32_e32 v78, v56, v78
	v_add_f32_e32 v78, v57, v78
	v_add_f32_e32 v78, v58, v78
	v_add_f32_e32 v78, v59, v78
	v_cvt_pk_bf16_f32 v140, v54, v55
	v_cvt_pk_bf16_f32 v141, v56, v57
	ds_read_b64_tr_b16 v[54:55], v228 offset:44032
	ds_read_b64_tr_b16 v[56:57], v228 offset:44544
	s_waitcnt lgkmcnt(14)
	v_mfma_f32_32x32x16_bf16 v[98:113], v[118:121], v[134:137], v[98:113]
	v_add_f32_e32 v78, v60, v78
	v_add_f32_e32 v78, v61, v78
	v_add_f32_e32 v78, v62, v78
	v_add_f32_e32 v78, v63, v78
	v_cvt_pk_bf16_f32 v130, v58, v59
	v_cvt_pk_bf16_f32 v131, v60, v61
	ds_read_b64_tr_b16 v[58:59], v228 offset:48128
	ds_read_b64_tr_b16 v[60:61], v228 offset:48640
	v_mfma_f32_32x32x16_bf16 v[82:97], v[114:117], v[134:137], v[82:97]
	v_add_f32_e32 v78, v64, v78
	v_add_f32_e32 v78, v65, v78
	v_cvt_pk_bf16_f32 v132, v62, v63
	v_cvt_pk_bf16_f32 v133, v64, v65
	v_lshl_add_u64 v[62:63], v[224:225], 0, s[68:69]
	s_mov_b32 s4, m0
	s_mov_b32 m0, s40
	s_nop 0
	global_load_lds_dwordx4 v[62:63], off
	s_mov_b32 m0, s4
	s_mov_b64 s[4:5], 0x1f0000
	s_cmp_lg_u32 0, -1
	v_lshl_add_u64 v[62:63], v[222:223], 0, s[4:5]
	s_cselect_b32 s4, 0, 0
	s_add_i32 s4, s4, s38
	v_add_f32_e32 v221, v0, v78
	s_add_i32 s40, s4, 0x8000
	s_mov_b32 s4, m0
	s_mov_b32 m0, s40
	s_nop 0
	global_load_lds_dwordx4 v[62:63], off
	s_mov_b32 m0, s4
	v_max_f32_e32 v0, v99, v99
	v_max_f32_e32 v62, v98, v98
	v_max_f32_e32 v0, v62, v0
	v_max3_f32 v62, v100, v101, v83
	v_max3_f32 v0, v0, v82, v84
	v_max3_f32 v0, v0, v85, v102
	v_max3_f32 v62, v62, v104, v105
	v_max3_f32 v0, v0, v103, v86
	v_max3_f32 v62, v62, v88, v89
	v_max3_f32 v0, v0, v87, v106
	v_max3_f32 v62, v62, v108, v109
	v_max3_f32 v0, v0, v107, v90
	v_max3_f32 v62, v62, v92, v93
	v_max3_f32 v0, v0, v91, v110
	v_max3_f32 v62, v62, v112, v113
	v_max3_f32 v0, v0, v111, v94
	v_max3_f32 v62, v62, v96, v97
	v_max3_f32 v0, v0, v95, v62
	v_mov_b32_e32 v62, v0
	s_nop 1
	v_permlane32_swap_b32_e32 v0, v62
	v_max_f32_e32 v0, v0, v62
	v_cmp_lt_f32_e32 vcc, s27, v0
	s_cmp_lg_u64 vcc, 0
	s_cselect_b64 s[4:5], -1, 0
	s_cbranch_vccnz .LBB0_599

.LBB0_570:
	v_lshl_add_u64 v[224:225], v[224:225], 0, s[66:67]
	v_lshl_add_u64 v[226:227], v[222:223], 0, s[66:67]
	ds_read_b64_tr_b16 v[162:163], v228 offset:24576
	ds_read_b64_tr_b16 v[164:165], v228 offset:25088
	s_waitcnt lgkmcnt(9)
	v_mfma_f32_32x32x16_bf16 v[114:129], v[62:65], v[158:161], v[34:49]
	v_add_f32_e32 v50, v98, v99
	v_add_f32_e32 v50, v100, v50
	v_add_f32_e32 v50, v101, v50
	v_add_f32_e32 v50, v102, v50
	v_add_f32_e32 v50, v103, v50
	v_cvt_pk_bf16_f32 v154, v98, v99
	v_cvt_pk_bf16_f32 v155, v100, v101
	ds_read_b64_tr_b16 v[74:75], v228 offset:28672
	ds_read_b64_tr_b16 v[76:77], v228 offset:29184
	v_add_f32_e32 v50, v104, v50
	v_add_f32_e32 v50, v105, v50
	v_add_f32_e32 v50, v106, v50
	v_add_f32_e32 v70, v107, v50
	s_waitcnt lgkmcnt(10)
	v_mfma_f32_32x32x16_bf16 v[50:65], v[182:185], v[158:161], v[34:49]
	v_cvt_pk_bf16_f32 v156, v102, v103
	v_cvt_pk_bf16_f32 v157, v104, v105
	ds_read_b64_tr_b16 v[66:67], v228 offset:25600
	ds_read_b64_tr_b16 v[68:69], v228 offset:26112
	s_waitcnt lgkmcnt(11)
	v_mfma_f32_32x32x16_bf16 v[114:129], v[186:189], v[150:153], v[114:129]
	v_add_f32_e32 v70, v108, v70
	v_add_f32_e32 v70, v109, v70
	v_add_f32_e32 v70, v110, v70
	v_add_f32_e32 v98, v111, v70
	v_cvt_pk_bf16_f32 v146, v106, v107
	v_cvt_pk_bf16_f32 v147, v108, v109
	ds_read_b64_tr_b16 v[70:71], v228 offset:29696
	ds_read_b64_tr_b16 v[72:73], v228 offset:30208
	s_waitcnt lgkmcnt(12)
	v_mfma_f32_32x32x16_bf16 v[50:65], v[78:81], v[150:153], v[50:65]
	v_add_f32_e32 v78, v112, v98
	v_add_f32_e32 v78, v113, v78
	v_add_f32_e32 v78, v82, v78
	v_add_f32_e32 v98, v83, v78
	v_cvt_pk_bf16_f32 v148, v110, v111
	v_cvt_pk_bf16_f32 v149, v112, v113
	ds_read_b64_tr_b16 v[78:79], v228 offset:26624
	ds_read_b64_tr_b16 v[80:81], v228 offset:27136
	s_waitcnt lgkmcnt(13)
	v_mfma_f32_32x32x16_bf16 v[114:129], v[178:181], v[142:145], v[114:129]
	v_add_f32_e32 v98, v84, v98
	v_add_f32_e32 v98, v85, v98
	v_add_f32_e32 v98, v86, v98
	v_add_f32_e32 v98, v87, v98
	v_cvt_pk_bf16_f32 v138, v82, v83
	v_cvt_pk_bf16_f32 v139, v84, v85
	ds_read_b64_tr_b16 v[82:83], v228 offset:30720
	ds_read_b64_tr_b16 v[84:85], v228 offset:31232
	s_waitcnt lgkmcnt(14)
	v_mfma_f32_32x32x16_bf16 v[50:65], v[174:177], v[142:145], v[50:65]
	v_add_f32_e32 v98, v88, v98
	v_add_f32_e32 v98, v89, v98
	v_add_f32_e32 v98, v90, v98
	v_add_f32_e32 v98, v91, v98
	v_cvt_pk_bf16_f32 v140, v86, v87
	v_cvt_pk_bf16_f32 v141, v88, v89
	ds_read_b64_tr_b16 v[86:87], v228 offset:27648
	ds_read_b64_tr_b16 v[88:89], v228 offset:28160
	s_waitcnt lgkmcnt(14)
	v_mfma_f32_32x32x16_bf16 v[114:129], v[170:173], v[134:137], v[114:129]
	v_add_f32_e32 v98, v92, v98
	v_add_f32_e32 v98, v93, v98
	v_add_f32_e32 v98, v94, v98
	v_add_f32_e32 v98, v95, v98
	v_cvt_pk_bf16_f32 v130, v90, v91
	v_cvt_pk_bf16_f32 v131, v92, v93
	ds_read_b64_tr_b16 v[90:91], v228 offset:31744
	ds_read_b64_tr_b16 v[92:93], v228 offset:32256
	v_mfma_f32_32x32x16_bf16 v[50:65], v[166:169], v[134:137], v[50:65]
	v_add_f32_e32 v98, v96, v98
	v_add_f32_e32 v98, v97, v98
	v_cvt_pk_bf16_f32 v132, v94, v95
	v_cvt_pk_bf16_f32 v133, v96, v97
	s_cmp_lg_u32 0, -1
	s_cselect_b32 s4, 0, 0
	v_lshl_add_u64 v[94:95], v[224:225], 0, s[64:65]
	s_add_i32 s4, s4, s38
	s_add_i32 s5, s4, 0x2000
	s_mov_b32 s6, m0
	s_mov_b32 m0, s5
	s_nop 0
	global_load_lds_dwordx4 v[94:95], off
	s_mov_b32 m0, s6
	v_lshl_add_u64 v[94:95], v[226:227], 0, s[14:15]
	s_add_i32 s4, s4, 0xa000
	s_mov_b32 s5, m0
	s_mov_b32 m0, s4
	s_nop 0
	global_load_lds_dwordx4 v[94:95], off
	s_mov_b32 m0, s5
	v_max_f32_e32 v94, v115, v115
	v_max_f32_e32 v95, v114, v114
	v_max_f32_e32 v94, v95, v94
	v_max3_f32 v95, v116, v117, v51
	v_max3_f32 v94, v94, v50, v52
	v_max3_f32 v94, v94, v53, v118
	v_max3_f32 v95, v95, v120, v121
	v_max3_f32 v94, v94, v119, v54
	v_max3_f32 v95, v95, v56, v57
	v_max3_f32 v94, v94, v55, v122
	v_max3_f32 v95, v95, v124, v125
	v_max3_f32 v94, v94, v123, v58
	v_max3_f32 v95, v95, v60, v61
	v_max3_f32 v94, v94, v59, v126
	v_max3_f32 v95, v95, v128, v129
	v_max3_f32 v94, v94, v127, v62
	v_max3_f32 v95, v95, v64, v65
	v_max3_f32 v94, v94, v63, v95
	v_mov_b32_e32 v95, v94
	s_nop 1
	v_permlane32_swap_b32_e32 v94, v95
	v_max_f32_e32 v94, v94, v95
	v_cmp_lt_f32_e32 vcc, s27, v94
	s_cmp_lg_u64 vcc, 0
	v_add_f32_e32 v221, v221, v98
	s_cselect_b64 s[4:5], -1, 0
	s_cbranch_vccnz .LBB0_602

.LBB0_573:
	ds_read_b64_tr_b16 v[162:163], v228 offset:32768
	ds_read_b64_tr_b16 v[164:165], v228 offset:33280
	s_waitcnt lgkmcnt(9)
	v_mfma_f32_32x32x16_bf16 v[98:113], v[74:77], v[158:161], v[34:49]
	v_add_f32_e32 v66, v114, v115
	v_add_f32_e32 v66, v116, v66
	v_add_f32_e32 v66, v117, v66
	v_add_f32_e32 v66, v118, v66
	v_add_f32_e32 v66, v119, v66
	v_cvt_pk_bf16_f32 v154, v114, v115
	v_cvt_pk_bf16_f32 v155, v116, v117
	ds_read_b64_tr_b16 v[90:91], v228 offset:36864
	ds_read_b64_tr_b16 v[92:93], v228 offset:37376
	v_add_f32_e32 v66, v120, v66
	v_add_f32_e32 v66, v121, v66
	v_add_f32_e32 v66, v122, v66
	v_add_f32_e32 v86, v123, v66
	s_waitcnt lgkmcnt(10)
	v_mfma_f32_32x32x16_bf16 v[66:81], v[182:185], v[158:161], v[34:49]
	v_cvt_pk_bf16_f32 v156, v118, v119
	v_cvt_pk_bf16_f32 v157, v120, v121
	ds_read_b64_tr_b16 v[82:83], v228 offset:33792
	ds_read_b64_tr_b16 v[84:85], v228 offset:34304
	s_waitcnt lgkmcnt(11)
	v_mfma_f32_32x32x16_bf16 v[98:113], v[186:189], v[150:153], v[98:113]
	v_add_f32_e32 v86, v124, v86
	v_add_f32_e32 v86, v125, v86
	v_add_f32_e32 v86, v126, v86
	v_add_f32_e32 v114, v127, v86
	v_cvt_pk_bf16_f32 v146, v122, v123
	v_cvt_pk_bf16_f32 v147, v124, v125
	ds_read_b64_tr_b16 v[86:87], v228 offset:37888
	ds_read_b64_tr_b16 v[88:89], v228 offset:38400
	s_waitcnt lgkmcnt(12)
	v_mfma_f32_32x32x16_bf16 v[66:81], v[94:97], v[150:153], v[66:81]
	v_add_f32_e32 v94, v128, v114
	v_add_f32_e32 v94, v129, v94
	v_add_f32_e32 v94, v50, v94
	v_add_f32_e32 v114, v51, v94
	v_cvt_pk_bf16_f32 v148, v126, v127
	v_cvt_pk_bf16_f32 v149, v128, v129
	ds_read_b64_tr_b16 v[94:95], v228 offset:34816
	ds_read_b64_tr_b16 v[96:97], v228 offset:35328
	s_waitcnt lgkmcnt(13)
	v_mfma_f32_32x32x16_bf16 v[98:113], v[178:181], v[142:145], v[98:113]
	v_add_f32_e32 v114, v52, v114
	v_add_f32_e32 v114, v53, v114
	v_add_f32_e32 v114, v54, v114
	v_add_f32_e32 v114, v55, v114
	v_cvt_pk_bf16_f32 v138, v50, v51
	v_cvt_pk_bf16_f32 v139, v52, v53
	ds_read_b64_tr_b16 v[50:51], v228 offset:38912
	ds_read_b64_tr_b16 v[52:53], v228 offset:39424
	s_waitcnt lgkmcnt(14)
	v_mfma_f32_32x32x16_bf16 v[66:81], v[174:177], v[142:145], v[66:81]
	v_add_f32_e32 v114, v56, v114
	v_add_f32_e32 v114, v57, v114
	v_add_f32_e32 v114, v58, v114
	v_add_f32_e32 v114, v59, v114
	v_cvt_pk_bf16_f32 v140, v54, v55
	v_cvt_pk_bf16_f32 v141, v56, v57
	ds_read_b64_tr_b16 v[54:55], v228 offset:35840
	ds_read_b64_tr_b16 v[56:57], v228 offset:36352
	s_waitcnt lgkmcnt(14)
	v_mfma_f32_32x32x16_bf16 v[98:113], v[170:173], v[134:137], v[98:113]
	v_add_f32_e32 v114, v60, v114
	v_add_f32_e32 v114, v61, v114
	v_add_f32_e32 v114, v62, v114
	v_add_f32_e32 v114, v63, v114
	v_cvt_pk_bf16_f32 v130, v58, v59
	v_cvt_pk_bf16_f32 v131, v60, v61
	ds_read_b64_tr_b16 v[58:59], v228 offset:39936
	ds_read_b64_tr_b16 v[60:61], v228 offset:40448
	v_mfma_f32_32x32x16_bf16 v[66:81], v[166:169], v[134:137], v[66:81]
	v_add_f32_e32 v114, v64, v114
	v_add_f32_e32 v114, v65, v114
	v_cvt_pk_bf16_f32 v132, v62, v63
	v_cvt_pk_bf16_f32 v133, v64, v65
	v_lshl_add_u64 v[62:63], v[222:223], 0, s[68:69]
	s_mov_b32 s4, m0
	s_mov_b32 m0, s37
	s_nop 0
	global_load_lds_dwordx4 v[62:63], off
	s_mov_b32 m0, s4
	v_max_f32_e32 v62, v99, v99
	v_max_f32_e32 v63, v98, v98
	v_max_f32_e32 v62, v63, v62
	s_nop 2
	v_max3_f32 v63, v100, v101, v67
	v_max3_f32 v62, v62, v66, v68
	v_max3_f32 v62, v62, v69, v102
	v_max3_f32 v63, v63, v104, v105
	v_max3_f32 v62, v62, v103, v70
	v_max3_f32 v63, v63, v72, v73
	v_max3_f32 v62, v62, v71, v106
	v_max3_f32 v63, v63, v108, v109
	v_max3_f32 v62, v62, v107, v74
	v_max3_f32 v63, v63, v76, v77
	v_max3_f32 v62, v62, v75, v110
	v_max3_f32 v63, v63, v112, v113
	v_max3_f32 v62, v62, v111, v78
	v_max3_f32 v63, v63, v80, v81
	v_max3_f32 v62, v62, v79, v63
	v_mov_b32_e32 v63, v62
	s_nop 1
	v_permlane32_swap_b32_e32 v62, v63
	v_max_f32_e32 v62, v62, v63
	v_cmp_lt_f32_e32 vcc, s27, v62
	s_cmp_lg_u64 vcc, 0
	v_add_f32_e32 v182, v221, v114
	s_cselect_b64 s[4:5], -1, 0
	s_cbranch_vccnz .LBB0_605

.LBB0_576:
	s_mov_b64 s[4:5], 0x1f4000
	v_lshl_add_u64 v[184:185], v[222:223], 0, s[4:5]
	ds_read_b64_tr_b16 v[118:119], v228 offset:40960
	ds_read_b64_tr_b16 v[120:121], v228 offset:41472
	s_waitcnt lgkmcnt(9)
	v_mfma_f32_32x32x16_bf16 v[82:97], v[62:65], v[158:161], v[34:49]
	v_add_f32_e32 v50, v98, v99
	v_add_f32_e32 v50, v100, v50
	v_add_f32_e32 v50, v101, v50
	v_add_f32_e32 v50, v102, v50
	v_add_f32_e32 v50, v103, v50
	v_cvt_pk_bf16_f32 v154, v98, v99
	v_cvt_pk_bf16_f32 v155, v100, v101
	ds_read_b64_tr_b16 v[114:115], v228 offset:45056
	ds_read_b64_tr_b16 v[116:117], v228 offset:45568
	v_add_f32_e32 v50, v104, v50
	v_add_f32_e32 v50, v105, v50
	v_add_f32_e32 v50, v106, v50
	v_add_f32_e32 v130, v107, v50
	s_waitcnt lgkmcnt(10)
	v_mfma_f32_32x32x16_bf16 v[50:65], v[174:177], v[158:161], v[34:49]
	v_cvt_pk_bf16_f32 v156, v102, v103
	v_cvt_pk_bf16_f32 v157, v104, v105
	ds_read_b64_tr_b16 v[98:99], v228 offset:41984
	ds_read_b64_tr_b16 v[100:101], v228 offset:42496
	s_waitcnt lgkmcnt(11)
	v_mfma_f32_32x32x16_bf16 v[82:97], v[178:181], v[150:153], v[82:97]
	v_add_f32_e32 v102, v108, v130
	v_add_f32_e32 v102, v109, v102
	v_add_f32_e32 v102, v110, v102
	v_add_f32_e32 v130, v111, v102
	v_cvt_pk_bf16_f32 v146, v106, v107
	v_cvt_pk_bf16_f32 v147, v108, v109
	ds_read_b64_tr_b16 v[102:103], v228 offset:46080
	ds_read_b64_tr_b16 v[104:105], v228 offset:46592
	s_waitcnt lgkmcnt(12)
	v_mfma_f32_32x32x16_bf16 v[50:65], v[170:173], v[150:153], v[50:65]
	v_add_f32_e32 v106, v112, v130
	v_add_f32_e32 v106, v113, v106
	v_add_f32_e32 v106, v66, v106
	v_add_f32_e32 v130, v67, v106
	v_cvt_pk_bf16_f32 v148, v110, v111
	v_cvt_pk_bf16_f32 v149, v112, v113
	ds_read_b64_tr_b16 v[106:107], v228 offset:43008
	ds_read_b64_tr_b16 v[108:109], v228 offset:43520
	s_waitcnt lgkmcnt(13)
	v_mfma_f32_32x32x16_bf16 v[82:97], v[166:169], v[142:145], v[82:97]
	v_add_f32_e32 v110, v68, v130
	v_add_f32_e32 v110, v69, v110
	v_add_f32_e32 v110, v70, v110
	v_add_f32_e32 v110, v71, v110
	v_cvt_pk_bf16_f32 v138, v66, v67
	v_cvt_pk_bf16_f32 v139, v68, v69
	ds_read_b64_tr_b16 v[66:67], v228 offset:47104
	ds_read_b64_tr_b16 v[68:69], v228 offset:47616
	s_waitcnt lgkmcnt(14)
	v_mfma_f32_32x32x16_bf16 v[50:65], v[162:165], v[142:145], v[50:65]
	v_add_f32_e32 v110, v72, v110
	v_add_f32_e32 v110, v73, v110
	v_add_f32_e32 v110, v74, v110
	v_add_f32_e32 v110, v75, v110
	v_cvt_pk_bf16_f32 v140, v70, v71
	v_cvt_pk_bf16_f32 v141, v72, v73
	ds_read_b64_tr_b16 v[70:71], v228 offset:44032
	ds_read_b64_tr_b16 v[72:73], v228 offset:44544
	s_waitcnt lgkmcnt(14)
	v_mfma_f32_32x32x16_bf16 v[82:97], v[126:129], v[134:137], v[82:97]
	v_add_f32_e32 v110, v76, v110
	v_add_f32_e32 v110, v77, v110
	v_add_f32_e32 v110, v78, v110
	v_add_f32_e32 v110, v79, v110
	v_cvt_pk_bf16_f32 v130, v74, v75
	v_cvt_pk_bf16_f32 v131, v76, v77
	ds_read_b64_tr_b16 v[74:75], v228 offset:48128
	ds_read_b64_tr_b16 v[76:77], v228 offset:48640
	v_mfma_f32_32x32x16_bf16 v[50:65], v[122:125], v[134:137], v[50:65]
	v_add_f32_e32 v110, v80, v110
	v_add_f32_e32 v110, v81, v110
	v_cvt_pk_bf16_f32 v132, v78, v79
	v_cvt_pk_bf16_f32 v133, v80, v81
	v_lshl_add_u64 v[78:79], v[184:185], 0, s[14:15]
	s_mov_b32 s4, m0
	s_mov_b32 m0, s40
	s_nop 0
	global_load_lds_dwordx4 v[78:79], off
	s_mov_b32 m0, s4
	v_max_f32_e32 v78, v83, v83
	v_max_f32_e32 v79, v82, v82
	v_max_f32_e32 v78, v79, v78
	s_nop 2
	v_max3_f32 v79, v84, v85, v51
	v_max3_f32 v78, v78, v50, v52
	v_max3_f32 v78, v78, v53, v86
	v_max3_f32 v79, v79, v88, v89
	v_max3_f32 v78, v78, v87, v54
	v_max3_f32 v79, v79, v56, v57
	v_max3_f32 v78, v78, v55, v90
	v_max3_f32 v79, v79, v92, v93
	v_max3_f32 v78, v78, v91, v58
	v_max3_f32 v79, v79, v60, v61
	v_max3_f32 v78, v78, v59, v94
	v_max3_f32 v79, v79, v96, v97
	v_max3_f32 v78, v78, v95, v62
	v_max3_f32 v79, v79, v64, v65
	v_max3_f32 v78, v78, v63, v79
	v_mov_b32_e32 v79, v78
	s_nop 1
	v_permlane32_swap_b32_e32 v78, v79
	v_max_f32_e32 v78, v78, v79
	v_cmp_lt_f32_e32 vcc, s27, v78
	s_cmp_lg_u64 vcc, 0
	v_add_f32_e32 v170, v182, v110
	s_cselect_b64 s[4:5], -1, 0
	s_cbranch_vccnz .LBB0_608

.LBB0_579:
	ds_read_b64_tr_b16 v[98:99], v228 offset:24576
	ds_read_b64_tr_b16 v[100:101], v228 offset:25088
	v_add_f32_e32 v66, v82, v83
	v_add_f32_e32 v66, v84, v66
	v_add_f32_e32 v66, v85, v66
	v_add_f32_e32 v66, v86, v66
	v_add_f32_e32 v106, v87, v66
	s_waitcnt lgkmcnt(9)
	v_mfma_f32_32x32x16_bf16 v[66:81], v[166:169], v[158:161], v[34:49]
	v_cvt_pk_bf16_f32 v154, v82, v83
	v_cvt_pk_bf16_f32 v155, v84, v85
	ds_read_b64_tr_b16 v[82:83], v228 offset:28672
	ds_read_b64_tr_b16 v[84:85], v228 offset:29184
	s_waitcnt lgkmcnt(10)
	v_mfma_f32_32x32x16_bf16 v[34:49], v[162:165], v[158:161], v[34:49]
	v_add_f32_e32 v106, v88, v106
	v_add_f32_e32 v106, v89, v106
	v_add_f32_e32 v106, v90, v106
	v_add_f32_e32 v106, v91, v106
	v_cvt_pk_bf16_f32 v156, v86, v87
	v_cvt_pk_bf16_f32 v157, v88, v89
	ds_read_b64_tr_b16 v[86:87], v228 offset:25600
	ds_read_b64_tr_b16 v[88:89], v228 offset:26112
	s_waitcnt lgkmcnt(11)
	v_mfma_f32_32x32x16_bf16 v[66:81], v[126:129], v[150:153], v[66:81]
	v_add_f32_e32 v106, v92, v106
	v_add_f32_e32 v106, v93, v106
	v_add_f32_e32 v106, v94, v106
	v_add_f32_e32 v106, v95, v106
	v_cvt_pk_bf16_f32 v146, v90, v91
	v_cvt_pk_bf16_f32 v147, v92, v93
	ds_read_b64_tr_b16 v[90:91], v228 offset:29696
	ds_read_b64_tr_b16 v[92:93], v228 offset:30208
	s_waitcnt lgkmcnt(12)
	v_mfma_f32_32x32x16_bf16 v[34:49], v[122:125], v[150:153], v[34:49]
	v_add_f32_e32 v106, v96, v106
	v_add_f32_e32 v106, v97, v106
	v_add_f32_e32 v106, v50, v106
	v_add_f32_e32 v106, v51, v106
	v_cvt_pk_bf16_f32 v148, v94, v95
	v_cvt_pk_bf16_f32 v149, v96, v97
	ds_read_b64_tr_b16 v[94:95], v228 offset:26624
	ds_read_b64_tr_b16 v[96:97], v228 offset:27136
	s_waitcnt lgkmcnt(13)
	v_mfma_f32_32x32x16_bf16 v[66:81], v[102:105], v[142:145], v[66:81]
	v_add_f32_e32 v102, v52, v106
	v_add_f32_e32 v102, v53, v102
	v_add_f32_e32 v102, v54, v102
	v_add_f32_e32 v106, v55, v102
	v_cvt_pk_bf16_f32 v138, v50, v51
	v_cvt_pk_bf16_f32 v139, v52, v53
	ds_read_b64_tr_b16 v[102:103], v228 offset:30720
	ds_read_b64_tr_b16 v[104:105], v228 offset:31232
	s_waitcnt lgkmcnt(14)
	v_mfma_f32_32x32x16_bf16 v[34:49], v[118:121], v[142:145], v[34:49]
	v_add_f32_e32 v50, v56, v106
	v_add_f32_e32 v50, v57, v50
	v_add_f32_e32 v50, v58, v50
	v_add_f32_e32 v50, v59, v50
	v_cvt_pk_bf16_f32 v140, v54, v55
	v_cvt_pk_bf16_f32 v141, v56, v57
	ds_read_b64_tr_b16 v[106:107], v228 offset:27648
	ds_read_b64_tr_b16 v[108:109], v228 offset:28160
	s_waitcnt lgkmcnt(14)
	v_mfma_f32_32x32x16_bf16 v[66:81], v[114:117], v[134:137], v[66:81]
	v_add_f32_e32 v50, v60, v50
	v_add_f32_e32 v50, v61, v50
	v_add_f32_e32 v50, v62, v50
	v_add_f32_e32 v50, v63, v50
	v_cvt_pk_bf16_f32 v130, v58, v59
	v_cvt_pk_bf16_f32 v131, v60, v61
	ds_read_b64_tr_b16 v[114:115], v228 offset:31744
	ds_read_b64_tr_b16 v[116:117], v228 offset:32256
	v_mfma_f32_32x32x16_bf16 v[34:49], v[110:113], v[134:137], v[34:49]
	v_add_f32_e32 v50, v64, v50
	v_add_f32_e32 v50, v65, v50
	v_cvt_pk_bf16_f32 v132, v62, v63
	v_cvt_pk_bf16_f32 v133, v64, v65
	v_max_f32_e32 v51, v67, v67
	v_max_f32_e32 v52, v66, v66
	v_max_f32_e32 v51, v52, v51
	s_nop 4
	v_max3_f32 v52, v68, v69, v35
	v_max3_f32 v51, v51, v34, v36
	v_max3_f32 v51, v51, v37, v70
	v_max3_f32 v52, v52, v72, v73
	v_max3_f32 v51, v51, v71, v38
	v_max3_f32 v52, v52, v40, v41
	v_max3_f32 v51, v51, v39, v74
	v_max3_f32 v52, v52, v76, v77
	v_max3_f32 v51, v51, v75, v42
	v_max3_f32 v52, v52, v44, v45
	v_max3_f32 v51, v51, v43, v78
	v_max3_f32 v52, v52, v80, v81
	v_max3_f32 v51, v51, v79, v46
	v_max3_f32 v52, v52, v48, v49
	v_add_f32_e32 v110, v170, v50
	v_max3_f32 v50, v51, v47, v52
	v_mov_b32_e32 v51, v50
	s_nop 1
	v_permlane32_swap_b32_e32 v50, v51
	v_max_f32_e32 v50, v50, v51
	v_cmp_lt_f32_e32 vcc, s27, v50
	s_cmp_lg_u64 vcc, 0
	s_cselect_b64 s[4:5], -1, 0
	s_cbranch_vccnz .LBB0_611

.LBB0_939:
	v_lshl_add_u32 v148, s4, 8, v150
	v_ashrrev_i32_e32 v149, 31, v148
	v_lshlrev_b64 v[160:161], 6, v[148:149]
	v_lshl_add_u64 v[160:161], v[138:139], 0, v[160:161]
	global_load_dwordx4 v[160:163], v[160:161], off
	v_and_b32_e32 v164, 64, v155
	v_xor_b32_e32 v159, 16, v155
	v_add_u32_e32 v166, 64, v164
	v_cmp_lt_i32_e32 vcc, v159, v166
	v_xor_b32_e32 v165, 32, v155
	s_lshl_b32 s4, s5, 8
	v_cndmask_b32_e32 v159, v155, v159, vcc
	v_lshlrev_b32_e32 v159, 2, v159
	v_cmp_lt_i32_e32 vcc, v165, v166
	s_or_b32 s4, s4, s40
	s_cmp_lt_i32 s5, 4
	v_cndmask_b32_e32 v170, v155, v165, vcc
	s_cselect_b64 vcc, -1, 0
	v_lshlrev_b64 v[166:167], 7, v[148:149]
	v_cndmask_b32_e32 v149, 1.0, v158, vcc
	s_ashr_i32 s4, s4, 6
	s_ashr_i32 s5, s4, 31
	s_lshl_b64 s[4:5], s[4:5], 22
	s_add_u32 s26, s10, s4
	s_addc_u32 s27, s11, s5
	v_lshl_add_u64 v[166:167], s[26:27], 0, v[166:167]
	v_lshl_add_u64 v[166:167], v[166:167], 0, v[136:137]
	v_or_b32_e32 v164, 16, v148
	v_ashrrev_i32_e32 v165, 31, v164
	s_waitcnt vmcnt(0)
	v_mov_b32_e32 v168, v161
	v_mov_b32_e32 v169, v162
	v_mov_b32_e32 v161, v163
	v_pk_add_f32 v[160:161], v[168:169], v[160:161]
	v_lshlrev_b64 v[162:163], 6, v[164:165]
	v_add_f32_e32 v161, v160, v161
	ds_bpermute_b32 v168, v159, v161
	v_lshlrev_b32_e32 v160, 2, v170
	v_lshl_add_u64 v[162:163], v[138:139], 0, v[162:163]
	s_waitcnt lgkmcnt(0)
	v_add_f32_e32 v161, v161, v168
	ds_bpermute_b32 v168, v160, v161
	s_waitcnt lgkmcnt(0)
	v_add_f32_e32 v161, v161, v168
	v_fmamk_f32 v161, v161, 0x3a800000, v156
	v_add_co_u32_e32 v168, vcc, s49, v166
	s_nop 1
	v_addc_co_u32_e32 v169, vcc, 0, v167, vcc
	v_rsq_f32_e32 v174, v161
	v_mul_f32_e32 v173, 0.5, v161
	v_mul_f32_e32 v161, v174, v174
	v_fma_f32 v173, -v173, v161, 0.5
	v_fma_f32 v161, v174, v173, v174
	v_mul_f32_e32 v170, v149, v161
	v_pk_mul_f32 v[126:127], v[126:127], v[170:171] op_sel_hi:[1,0]
	v_pk_mul_f32 v[124:125], v[124:125], v[170:171] op_sel_hi:[1,0]
	v_pk_mul_f32 v[122:123], v[122:123], v[170:171] op_sel_hi:[1,0]
	v_pk_mul_f32 v[120:121], v[120:121], v[170:171] op_sel_hi:[1,0]
	v_pk_mul_f32 v[118:119], v[118:119], v[170:171] op_sel_hi:[1,0]
	v_pk_mul_f32 v[116:117], v[116:117], v[170:171] op_sel_hi:[1,0]
	v_pk_mul_f32 v[172:173], v[114:115], v[170:171] op_sel_hi:[1,0]
	v_pk_mul_f32 v[170:171], v[112:113], v[170:171] op_sel_hi:[1,0]
	v_cvt_pk_bf16_f32 v112, v124, v125
	v_cvt_pk_bf16_f32 v113, v126, v127
	v_cvt_pk_bf16_f32 v114, v120, v121
	v_cvt_pk_bf16_f32 v115, v122, v123
	global_store_dwordx4 v[166:167], v[112:115], off
	s_nop 1
	v_cvt_pk_bf16_f32 v112, v116, v117
	v_cvt_pk_bf16_f32 v113, v118, v119
	v_cvt_pk_bf16_f32 v114, v170, v171
	v_cvt_pk_bf16_f32 v115, v172, v173
	global_store_dwordx4 v[168:169], v[112:115], off
	global_load_dwordx4 v[112:115], v[162:163], off
	s_waitcnt vmcnt(0)
	v_mov_b32_e32 v116, v113
	v_mov_b32_e32 v117, v114
	v_mov_b32_e32 v113, v115
	v_pk_add_f32 v[112:113], v[116:117], v[112:113]
	v_lshlrev_b64 v[114:115], 7, v[164:165]
	v_add_f32_e32 v112, v112, v113
	ds_bpermute_b32 v113, v159, v112
	v_lshl_add_u64 v[114:115], s[26:27], 0, v[114:115]
	v_lshl_add_u64 v[114:115], v[114:115], 0, v[136:137]
	s_waitcnt lgkmcnt(0)
	v_add_f32_e32 v118, v112, v113
	ds_bpermute_b32 v119, v160, v118
	v_or_b32_e32 v112, 32, v148
	v_ashrrev_i32_e32 v113, 31, v112
	v_lshlrev_b64 v[116:117], 6, v[112:113]
	v_lshl_add_u64 v[116:117], v[138:139], 0, v[116:117]
	s_waitcnt lgkmcnt(0)
	v_add_f32_e32 v118, v118, v119
	v_fmamk_f32 v118, v118, 0x3a800000, v156
	v_mov_b32_e32 v120, v118
	v_add_co_u32_e32 v118, vcc, s49, v114
	s_nop 1
	v_addc_co_u32_e32 v119, vcc, 0, v115, vcc
	v_rsq_f32_e32 v125, v120
	v_mul_f32_e32 v124, 0.5, v120
	v_mul_f32_e32 v120, v125, v125
	v_fma_f32 v124, -v124, v120, 0.5
	v_fma_f32 v120, v125, v124, v125
	v_mul_f32_e32 v120, v149, v120
	v_pk_mul_f32 v[110:111], v[110:111], v[120:121] op_sel_hi:[1,0]
	v_pk_mul_f32 v[108:109], v[108:109], v[120:121] op_sel_hi:[1,0]
	v_pk_mul_f32 v[106:107], v[106:107], v[120:121] op_sel_hi:[1,0]
	v_pk_mul_f32 v[104:105], v[104:105], v[120:121] op_sel_hi:[1,0]
	v_pk_mul_f32 v[102:103], v[102:103], v[120:121] op_sel_hi:[1,0]
	v_pk_mul_f32 v[100:101], v[100:101], v[120:121] op_sel_hi:[1,0]
	v_pk_mul_f32 v[122:123], v[98:99], v[120:121] op_sel_hi:[1,0]
	v_pk_mul_f32 v[120:121], v[96:97], v[120:121] op_sel_hi:[1,0]
	v_cvt_pk_bf16_f32 v96, v108, v109
	v_cvt_pk_bf16_f32 v97, v110, v111
	v_cvt_pk_bf16_f32 v98, v104, v105
	v_cvt_pk_bf16_f32 v99, v106, v107
	global_store_dwordx4 v[114:115], v[96:99], off
	s_nop 1
	v_cvt_pk_bf16_f32 v96, v100, v101
	v_cvt_pk_bf16_f32 v97, v102, v103
	v_cvt_pk_bf16_f32 v98, v120, v121
	v_cvt_pk_bf16_f32 v99, v122, v123
	global_store_dwordx4 v[118:119], v[96:99], off
	global_load_dwordx4 v[96:99], v[116:117], off
	s_waitcnt vmcnt(0)
	v_mov_b32_e32 v100, v97
	v_mov_b32_e32 v101, v98
	v_mov_b32_e32 v97, v99
	v_pk_add_f32 v[96:97], v[100:101], v[96:97]
	v_lshlrev_b64 v[98:99], 7, v[112:113]
	v_add_f32_e32 v96, v96, v97
	ds_bpermute_b32 v97, v159, v96
	v_lshl_add_u64 v[98:99], s[26:27], 0, v[98:99]
	v_lshl_add_u64 v[98:99], v[98:99], 0, v[136:137]
	s_waitcnt lgkmcnt(0)
	v_add_f32_e32 v102, v96, v97
	ds_bpermute_b32 v103, v160, v102
	v_or_b32_e32 v96, 48, v148
	v_ashrrev_i32_e32 v97, 31, v96
	v_lshlrev_b64 v[100:101], 6, v[96:97]
	v_lshl_add_u64 v[100:101], v[138:139], 0, v[100:101]
	s_waitcnt lgkmcnt(0)
	v_add_f32_e32 v102, v102, v103
	v_fmamk_f32 v102, v102, 0x3a800000, v156
	v_mov_b32_e32 v104, v102
	v_add_co_u32_e32 v102, vcc, s49, v98
	s_nop 1
	v_addc_co_u32_e32 v103, vcc, 0, v99, vcc
	v_rsq_f32_e32 v109, v104
	v_mul_f32_e32 v108, 0.5, v104
	v_mul_f32_e32 v104, v109, v109
	v_fma_f32 v108, -v108, v104, 0.5
	v_fma_f32 v104, v109, v108, v109
	v_mul_f32_e32 v104, v149, v104
	v_pk_mul_f32 v[94:95], v[94:95], v[104:105] op_sel_hi:[1,0]
	v_pk_mul_f32 v[92:93], v[92:93], v[104:105] op_sel_hi:[1,0]
	v_pk_mul_f32 v[90:91], v[90:91], v[104:105] op_sel_hi:[1,0]
	v_pk_mul_f32 v[88:89], v[88:89], v[104:105] op_sel_hi:[1,0]
	v_pk_mul_f32 v[86:87], v[86:87], v[104:105] op_sel_hi:[1,0]
	v_pk_mul_f32 v[84:85], v[84:85], v[104:105] op_sel_hi:[1,0]
	v_pk_mul_f32 v[106:107], v[82:83], v[104:105] op_sel_hi:[1,0]
	v_pk_mul_f32 v[104:105], v[80:81], v[104:105] op_sel_hi:[1,0]
	v_cvt_pk_bf16_f32 v80, v92, v93
	v_cvt_pk_bf16_f32 v81, v94, v95
	v_cvt_pk_bf16_f32 v82, v88, v89
	v_cvt_pk_bf16_f32 v83, v90, v91
	global_store_dwordx4 v[98:99], v[80:83], off
	s_nop 1
	v_cvt_pk_bf16_f32 v80, v84, v85
	v_cvt_pk_bf16_f32 v81, v86, v87
	v_cvt_pk_bf16_f32 v82, v104, v105
	v_cvt_pk_bf16_f32 v83, v106, v107
	global_store_dwordx4 v[102:103], v[80:83], off
	global_load_dwordx4 v[80:83], v[100:101], off
	s_waitcnt vmcnt(0)
	v_mov_b32_e32 v84, v81
	v_mov_b32_e32 v85, v82
	v_mov_b32_e32 v81, v83
	v_pk_add_f32 v[80:81], v[84:85], v[80:81]
	v_lshlrev_b64 v[82:83], 7, v[96:97]
	v_add_f32_e32 v80, v80, v81
	ds_bpermute_b32 v81, v159, v80
	v_lshl_add_u64 v[82:83], s[26:27], 0, v[82:83]
	v_lshl_add_u64 v[82:83], v[82:83], 0, v[136:137]
	s_waitcnt lgkmcnt(0)
	v_add_f32_e32 v86, v80, v81
	ds_bpermute_b32 v87, v160, v86
	v_add_u32_e32 v80, 0x80, v148
	v_ashrrev_i32_e32 v81, 31, v80
	v_lshlrev_b64 v[84:85], 6, v[80:81]
	v_lshl_add_u64 v[84:85], v[138:139], 0, v[84:85]
	s_waitcnt lgkmcnt(0)
	v_add_f32_e32 v86, v86, v87
	v_fmamk_f32 v86, v86, 0x3a800000, v156
	v_mov_b32_e32 v88, v86
	v_add_co_u32_e32 v86, vcc, s49, v82
	s_nop 1
	v_addc_co_u32_e32 v87, vcc, 0, v83, vcc
	v_rsq_f32_e32 v93, v88
	v_mul_f32_e32 v92, 0.5, v88
	v_mul_f32_e32 v88, v93, v93
	v_fma_f32 v92, -v92, v88, 0.5
	v_fma_f32 v88, v93, v92, v93
	v_mul_f32_e32 v88, v149, v88
	v_pk_mul_f32 v[78:79], v[78:79], v[88:89] op_sel_hi:[1,0]
	v_pk_mul_f32 v[76:77], v[76:77], v[88:89] op_sel_hi:[1,0]
	v_pk_mul_f32 v[74:75], v[74:75], v[88:89] op_sel_hi:[1,0]
	v_pk_mul_f32 v[72:73], v[72:73], v[88:89] op_sel_hi:[1,0]
	v_pk_mul_f32 v[70:71], v[70:71], v[88:89] op_sel_hi:[1,0]
	v_pk_mul_f32 v[68:69], v[68:69], v[88:89] op_sel_hi:[1,0]
	v_pk_mul_f32 v[90:91], v[66:67], v[88:89] op_sel_hi:[1,0]
	v_pk_mul_f32 v[88:89], v[64:65], v[88:89] op_sel_hi:[1,0]
	v_cvt_pk_bf16_f32 v64, v76, v77
	v_cvt_pk_bf16_f32 v65, v78, v79
	v_cvt_pk_bf16_f32 v66, v72, v73
	v_cvt_pk_bf16_f32 v67, v74, v75
	global_store_dwordx4 v[82:83], v[64:67], off
	s_nop 1
	v_cvt_pk_bf16_f32 v64, v68, v69
	v_cvt_pk_bf16_f32 v65, v70, v71
	v_cvt_pk_bf16_f32 v66, v88, v89
	v_cvt_pk_bf16_f32 v67, v90, v91
	global_store_dwordx4 v[86:87], v[64:67], off
	global_load_dwordx4 v[64:67], v[84:85], off
	s_waitcnt vmcnt(0)
	v_mov_b32_e32 v68, v65
	v_mov_b32_e32 v69, v66
	v_mov_b32_e32 v65, v67
	v_pk_add_f32 v[64:65], v[68:69], v[64:65]
	v_lshlrev_b64 v[66:67], 7, v[80:81]
	v_add_f32_e32 v64, v64, v65
	ds_bpermute_b32 v65, v159, v64
	v_lshl_add_u64 v[66:67], s[26:27], 0, v[66:67]
	v_lshl_add_u64 v[66:67], v[66:67], 0, v[136:137]
	s_waitcnt lgkmcnt(0)
	v_add_f32_e32 v70, v64, v65
	ds_bpermute_b32 v71, v160, v70
	v_add_u32_e32 v64, 0x90, v148
	v_ashrrev_i32_e32 v65, 31, v64
	v_lshlrev_b64 v[68:69], 6, v[64:65]
	v_lshl_add_u64 v[68:69], v[138:139], 0, v[68:69]
	s_waitcnt lgkmcnt(0)
	v_add_f32_e32 v70, v70, v71
	v_fmamk_f32 v70, v70, 0x3a800000, v156
	v_mov_b32_e32 v72, v70
	v_add_co_u32_e32 v70, vcc, s49, v66
	s_nop 1
	v_addc_co_u32_e32 v71, vcc, 0, v67, vcc
	v_rsq_f32_e32 v77, v72
	v_mul_f32_e32 v76, 0.5, v72
	v_mul_f32_e32 v72, v77, v77
	v_fma_f32 v76, -v76, v72, 0.5
	v_fma_f32 v72, v77, v76, v77
	v_mul_f32_e32 v72, v149, v72
	v_pk_mul_f32 v[62:63], v[62:63], v[72:73] op_sel_hi:[1,0]
	v_pk_mul_f32 v[60:61], v[60:61], v[72:73] op_sel_hi:[1,0]
	v_pk_mul_f32 v[58:59], v[58:59], v[72:73] op_sel_hi:[1,0]
	v_pk_mul_f32 v[56:57], v[56:57], v[72:73] op_sel_hi:[1,0]
	v_pk_mul_f32 v[54:55], v[54:55], v[72:73] op_sel_hi:[1,0]
	v_pk_mul_f32 v[52:53], v[52:53], v[72:73] op_sel_hi:[1,0]
	v_pk_mul_f32 v[74:75], v[50:51], v[72:73] op_sel_hi:[1,0]
	v_pk_mul_f32 v[72:73], v[48:49], v[72:73] op_sel_hi:[1,0]
	v_cvt_pk_bf16_f32 v48, v60, v61
	v_cvt_pk_bf16_f32 v49, v62, v63
	v_cvt_pk_bf16_f32 v50, v56, v57
	v_cvt_pk_bf16_f32 v51, v58, v59
	global_store_dwordx4 v[66:67], v[48:51], off
	s_nop 1
	v_cvt_pk_bf16_f32 v48, v52, v53
	v_cvt_pk_bf16_f32 v49, v54, v55
	v_cvt_pk_bf16_f32 v50, v72, v73
	v_cvt_pk_bf16_f32 v51, v74, v75
	global_store_dwordx4 v[70:71], v[48:51], off
	global_load_dwordx4 v[48:51], v[68:69], off
	s_waitcnt vmcnt(0)
	v_mov_b32_e32 v52, v49
	v_mov_b32_e32 v53, v50
	v_mov_b32_e32 v49, v51
	v_pk_add_f32 v[48:49], v[52:53], v[48:49]
	v_lshlrev_b64 v[50:51], 7, v[64:65]
	v_add_f32_e32 v48, v48, v49
	ds_bpermute_b32 v49, v159, v48
	v_lshl_add_u64 v[50:51], s[26:27], 0, v[50:51]
	v_lshl_add_u64 v[50:51], v[50:51], 0, v[136:137]
	s_waitcnt lgkmcnt(0)
	v_add_f32_e32 v54, v48, v49
	ds_bpermute_b32 v55, v160, v54
	v_add_u32_e32 v48, 0xa0, v148
	v_ashrrev_i32_e32 v49, 31, v48
	v_lshlrev_b64 v[52:53], 6, v[48:49]
	v_lshl_add_u64 v[52:53], v[138:139], 0, v[52:53]
	s_waitcnt lgkmcnt(0)
	v_add_f32_e32 v54, v54, v55
	v_fmamk_f32 v54, v54, 0x3a800000, v156
	v_mov_b32_e32 v56, v54
	v_add_co_u32_e32 v54, vcc, s49, v50
	s_nop 1
	v_addc_co_u32_e32 v55, vcc, 0, v51, vcc
	v_rsq_f32_e32 v61, v56
	v_mul_f32_e32 v60, 0.5, v56
	v_mul_f32_e32 v56, v61, v61
	v_fma_f32 v60, -v60, v56, 0.5
	v_fma_f32 v56, v61, v60, v61
	v_mul_f32_e32 v56, v149, v56
	v_pk_mul_f32 v[46:47], v[46:47], v[56:57] op_sel_hi:[1,0]
	v_pk_mul_f32 v[44:45], v[44:45], v[56:57] op_sel_hi:[1,0]
	v_pk_mul_f32 v[42:43], v[42:43], v[56:57] op_sel_hi:[1,0]
	v_pk_mul_f32 v[40:41], v[40:41], v[56:57] op_sel_hi:[1,0]
	v_pk_mul_f32 v[38:39], v[38:39], v[56:57] op_sel_hi:[1,0]
	v_pk_mul_f32 v[36:37], v[36:37], v[56:57] op_sel_hi:[1,0]
	v_pk_mul_f32 v[58:59], v[34:35], v[56:57] op_sel_hi:[1,0]
	v_pk_mul_f32 v[56:57], v[32:33], v[56:57] op_sel_hi:[1,0]
	v_cvt_pk_bf16_f32 v32, v44, v45
	v_cvt_pk_bf16_f32 v33, v46, v47
	v_cvt_pk_bf16_f32 v34, v40, v41
	v_cvt_pk_bf16_f32 v35, v42, v43
	global_store_dwordx4 v[50:51], v[32:35], off
	s_nop 1
	v_cvt_pk_bf16_f32 v32, v36, v37
	v_cvt_pk_bf16_f32 v33, v38, v39
	v_cvt_pk_bf16_f32 v34, v56, v57
	v_cvt_pk_bf16_f32 v35, v58, v59
	global_store_dwordx4 v[54:55], v[32:35], off
	global_load_dwordx4 v[32:35], v[52:53], off
	s_waitcnt vmcnt(0)
	v_mov_b32_e32 v36, v33
	v_mov_b32_e32 v37, v34
	v_mov_b32_e32 v33, v35
	v_pk_add_f32 v[32:33], v[36:37], v[32:33]
	v_lshlrev_b64 v[34:35], 7, v[48:49]
	v_add_f32_e32 v32, v32, v33
	ds_bpermute_b32 v33, v159, v32
	v_lshl_add_u64 v[34:35], s[26:27], 0, v[34:35]
	v_lshl_add_u64 v[34:35], v[34:35], 0, v[136:137]
	s_waitcnt lgkmcnt(0)
	v_add_f32_e32 v38, v32, v33
	ds_bpermute_b32 v39, v160, v38
	v_add_u32_e32 v32, 0xb0, v148
	v_ashrrev_i32_e32 v33, 31, v32
	v_lshlrev_b64 v[36:37], 6, v[32:33]
	v_lshl_add_u64 v[36:37], v[138:139], 0, v[36:37]
	s_waitcnt lgkmcnt(0)
	v_add_f32_e32 v38, v38, v39
	v_fmamk_f32 v38, v38, 0x3a800000, v156
	v_mov_b32_e32 v40, v38
	v_add_co_u32_e32 v38, vcc, s49, v34
	s_nop 1
	v_addc_co_u32_e32 v39, vcc, 0, v35, vcc
	v_rsq_f32_e32 v45, v40
	v_mul_f32_e32 v44, 0.5, v40
	v_mul_f32_e32 v40, v45, v45
	v_fma_f32 v44, -v44, v40, 0.5
	v_fma_f32 v40, v45, v44, v45
	v_mul_f32_e32 v40, v149, v40
	v_pk_mul_f32 v[30:31], v[30:31], v[40:41] op_sel_hi:[1,0]
	v_pk_mul_f32 v[28:29], v[28:29], v[40:41] op_sel_hi:[1,0]
	v_pk_mul_f32 v[26:27], v[26:27], v[40:41] op_sel_hi:[1,0]
	v_pk_mul_f32 v[24:25], v[24:25], v[40:41] op_sel_hi:[1,0]
	v_pk_mul_f32 v[22:23], v[22:23], v[40:41] op_sel_hi:[1,0]
	v_pk_mul_f32 v[20:21], v[20:21], v[40:41] op_sel_hi:[1,0]
	v_pk_mul_f32 v[42:43], v[18:19], v[40:41] op_sel_hi:[1,0]
	v_pk_mul_f32 v[40:41], v[16:17], v[40:41] op_sel_hi:[1,0]
	v_cvt_pk_bf16_f32 v16, v28, v29
	v_cvt_pk_bf16_f32 v17, v30, v31
	v_cvt_pk_bf16_f32 v18, v24, v25
	v_cvt_pk_bf16_f32 v19, v26, v27
	global_store_dwordx4 v[34:35], v[16:19], off
	s_nop 1
	v_cvt_pk_bf16_f32 v16, v20, v21
	v_cvt_pk_bf16_f32 v17, v22, v23
	v_cvt_pk_bf16_f32 v18, v40, v41
	v_cvt_pk_bf16_f32 v19, v42, v43
	global_store_dwordx4 v[38:39], v[16:19], off
	global_load_dwordx4 v[16:19], v[36:37], off
	s_waitcnt vmcnt(0)
	v_mov_b32_e32 v20, v17
	v_mov_b32_e32 v21, v18
	v_mov_b32_e32 v17, v19
	v_pk_add_f32 v[16:17], v[20:21], v[16:17]
	s_nop 0
	v_add_f32_e32 v16, v16, v17
	ds_bpermute_b32 v17, v159, v16
	s_waitcnt lgkmcnt(0)
	v_add_f32_e32 v16, v16, v17
	ds_bpermute_b32 v17, v160, v16
	s_waitcnt lgkmcnt(0)
	v_add_f32_e32 v16, v16, v17
	v_fmamk_f32 v16, v16, 0x3a800000, v156
	v_mov_b32_e32 v18, v16
	v_lshlrev_b64 v[16:17], 7, v[32:33]
	v_lshl_add_u64 v[16:17], s[26:27], 0, v[16:17]
	v_lshl_add_u64 v[16:17], v[16:17], 0, v[136:137]
	v_mov_b32_e32 v19, v18
	v_add_co_u32_e32 v18, vcc, 0x800000, v16
	v_rsq_f32_e32 v23, v19
	v_mul_f32_e32 v22, 0.5, v19
	v_mul_f32_e32 v20, v23, v23
	v_fma_f32 v22, -v22, v20, 0.5
	v_fma_f32 v20, v23, v22, v23
	s_nop 0
	v_addc_co_u32_e32 v19, vcc, 0, v17, vcc
	v_mul_f32_e32 v20, v149, v20
	s_andn2_b64 vcc, exec, s[0:1]
	v_pk_mul_f32 v[14:15], v[14:15], v[20:21] op_sel_hi:[1,0]
	v_pk_mul_f32 v[12:13], v[12:13], v[20:21] op_sel_hi:[1,0]
	v_pk_mul_f32 v[10:11], v[10:11], v[20:21] op_sel_hi:[1,0]
	v_pk_mul_f32 v[8:9], v[8:9], v[20:21] op_sel_hi:[1,0]
	v_pk_mul_f32 v[6:7], v[6:7], v[20:21] op_sel_hi:[1,0]
	v_pk_mul_f32 v[4:5], v[4:5], v[20:21] op_sel_hi:[1,0]
	v_pk_mul_f32 v[22:23], v[2:3], v[20:21] op_sel_hi:[1,0]
	v_pk_mul_f32 v[20:21], v[0:1], v[20:21] op_sel_hi:[1,0]
	v_cvt_pk_bf16_f32 v0, v12, v13
	v_cvt_pk_bf16_f32 v1, v14, v15
	v_cvt_pk_bf16_f32 v2, v8, v9
	v_cvt_pk_bf16_f32 v3, v10, v11
	s_mov_b64 s[0:1], -1
	global_store_dwordx4 v[16:17], v[0:3], off
	s_nop 1
	v_cvt_pk_bf16_f32 v0, v4, v5
	v_cvt_pk_bf16_f32 v1, v6, v7
	v_cvt_pk_bf16_f32 v2, v20, v21
	v_cvt_pk_bf16_f32 v3, v22, v23
	global_store_dwordx4 v[18:19], v[0:3], off
	s_cbranch_vccnz .LBB0_932
	s_andn2_b64 vcc, exec, s[8:9]
	s_cbranch_vccnz .LBB0_931
	s_barrier
	s_branch .LBB0_931

.LBB0_1019:
	s_add_i32 s46, s84, s42
	s_cmp_gt_i32 s85, 5
	s_cselect_b32 s47, s33, 0xa000
	s_add_i32 s46, s46, s47
	v_add_u32_e32 v81, s46, v153
	ds_read_b128 v[64:67], v81
	ds_read_b128 v[126:129], v81 offset:512
	s_waitcnt lgkmcnt(1)
	v_mfma_f32_32x32x16_bf16 v[48:63], v[64:67], v[84:87], v[32:47]
	v_mov_b64_e32 v[78:79], v[46:47]
	v_mov_b64_e32 v[76:77], v[44:45]
	v_mov_b64_e32 v[74:75], v[42:43]
	v_mov_b64_e32 v[72:73], v[40:41]
	v_mov_b64_e32 v[70:71], v[38:39]
	v_mov_b64_e32 v[68:69], v[36:37]
	v_mov_b64_e32 v[66:67], v[34:35]
	v_mov_b64_e32 v[64:65], v[32:33]
	s_waitcnt lgkmcnt(0)
	s_nop 0
	v_mfma_f32_32x32x16_bf16 v[64:79], v[126:129], v[84:87], v[64:79]
	ds_read_b128 v[126:129], v81 offset:2048
	s_waitcnt lgkmcnt(0)
	v_mfma_f32_32x32x16_bf16 v[48:63], v[126:129], v[88:91], v[48:63]
	ds_read_b128 v[126:129], v81 offset:2560
	s_waitcnt lgkmcnt(0)
	v_mfma_f32_32x32x16_bf16 v[64:79], v[126:129], v[88:91], v[64:79]
	ds_read_b128 v[126:129], v81 offset:4096
	s_waitcnt lgkmcnt(0)
	v_mfma_f32_32x32x16_bf16 v[48:63], v[126:129], v[92:95], v[48:63]
	ds_read_b128 v[126:129], v81 offset:4608
	s_waitcnt lgkmcnt(0)
	v_mfma_f32_32x32x16_bf16 v[64:79], v[126:129], v[92:95], v[64:79]
	ds_read_b128 v[126:129], v81 offset:6144
	s_waitcnt lgkmcnt(0)
	v_mfma_f32_32x32x16_bf16 v[48:63], v[126:129], v[96:99], v[48:63]
	s_nop 11
	ds_read_b128 v[48:51], v81 offset:6656
	s_waitcnt lgkmcnt(0)
	v_mfma_f32_32x32x16_bf16 v[64:79], v[48:51], v[96:99], v[64:79]
	v_add_u32_e32 v48, s86, v199
	v_add_u32_e32 v49, s86, v198
	v_add_u32_e32 v50, s86, v197
	v_add_u32_e32 v51, s86, v196
	v_add_u32_e32 v52, s86, v195
	v_add_u32_e32 v53, s86, v194
	v_add_u32_e32 v54, s86, v189
	v_add_u32_e32 v55, s86, v188
	v_add_u32_e32 v56, s86, v187
	v_add_u32_e32 v57, s86, v186
	v_add_u32_e32 v58, s86, v185
	v_add_u32_e32 v59, s86, v184
	v_add_u32_e32 v81, s86, v183
	v_add_u32_e32 v83, s86, v182
	ds_read_b32 v48, v48
	ds_read_b32 v49, v49
	ds_read_b32 v50, v50
	ds_read_b32 v51, v51
	ds_read_b32 v52, v52
	ds_read_b32 v53, v53
	ds_read_b32 v54, v54
	ds_read_b32 v55, v55
	v_add_u32_e32 v126, s86, v181
	v_add_u32_e32 v127, s86, v180
	ds_read_b32 v56, v56
	ds_read_b32 v57, v57
	ds_read_b32 v58, v58
	ds_read_b32 v59, v59
	ds_read_b32 v82, v81
	ds_read_b32 v136, v83
	ds_read_b32 v83, v126
	ds_read_b32 v137, v127
	v_add_u32_e32 v81, s86, v179
	v_add_u32_e32 v126, s86, v178
	v_add_u32_e32 v127, s86, v177
	v_add_u32_e32 v128, s86, v117
	ds_read_b32 v200, v81
	ds_read_b32 v202, v126
	ds_read_b32 v201, v127
	ds_read_b32 v203, v128
	s_waitcnt lgkmcnt(14)
	v_pk_add_f32 v[128:129], v[64:65], v[48:49]
	v_pk_add_f32 v[130:131], v[66:67], v[50:51]
	v_add_u32_e32 v50, s46, v154
	v_pk_add_f32 v[132:133], v[68:69], v[52:53]
	s_waitcnt lgkmcnt(12)
	v_pk_add_f32 v[134:135], v[70:71], v[54:55]
	s_waitcnt lgkmcnt(10)
	v_pk_add_f32 v[126:127], v[72:73], v[56:57]
	s_waitcnt lgkmcnt(8)
	v_pk_add_f32 v[72:73], v[74:75], v[58:59]
	s_waitcnt lgkmcnt(5)
	v_pk_add_f32 v[82:83], v[60:61], v[82:83]
	s_waitcnt lgkmcnt(4)
	v_pk_add_f32 v[74:75], v[76:77], v[136:137]
	ds_read_b64_tr_b16 v[68:69], v50 offset:50176
	s_waitcnt lgkmcnt(2)
	v_pk_add_f32 v[136:137], v[62:63], v[200:201]
	s_waitcnt lgkmcnt(1)
	v_pk_add_f32 v[76:77], v[78:79], v[202:203]
	ds_read_b64_tr_b16 v[70:71], v50 offset:50688
	ds_read_b64_tr_b16 v[60:61], v50 offset:51200
	ds_read_b64_tr_b16 v[62:63], v50 offset:51712
	ds_read_b64_tr_b16 v[52:53], v50 offset:52224
	ds_read_b64_tr_b16 v[64:65], v50 offset:54272
	ds_read_b64_tr_b16 v[66:67], v50 offset:54784
	ds_read_b64_tr_b16 v[56:57], v50 offset:55296
	ds_read_b64_tr_b16 v[54:55], v50 offset:52736
	ds_read_b64_tr_b16 v[58:59], v50 offset:55808
	ds_read_b64_tr_b16 v[48:49], v50 offset:56320
	ds_read_b64_tr_b16 v[50:51], v50 offset:56832
	v_max3_f32 v78, v128, s30, v129
	v_max3_f32 v78, v78, v130, v131
	v_max3_f32 v78, v78, v132, v133
	v_max3_f32 v78, v78, v134, v135
	v_max3_f32 v78, v78, v126, v127
	v_max3_f32 v78, v78, v72, v73
	v_max_f32_e32 v79, 0xff800000, v82
	v_max3_f32 v78, v78, v74, v75
	v_max3_f32 v79, v79, v83, v136
	v_max3_f32 v78, v78, v76, v77
	v_max3_f32 v78, v79, v137, v78
	v_mov_b32_e32 v79, v78
	s_nop 1
	v_permlane32_swap_b32_e32 v78, v79
	v_max_f32_e32 v78, v78, v79
	v_cmp_lt_f32_e32 vcc, s48, v78
	s_cbranch_vccz .LBB0_1023
	v_max_f32_e32 v32, v78, v78
	v_max_f32_e32 v32, 0, v32
	v_cmp_lt_f32_e32 vcc, s49, v32
	s_nop 1
	v_cndmask_b32_e32 v33, 0, v173, vcc
	v_sub_f32_e32 v33, v33, v32
	v_exp_f32_e32 v33, v33
	v_cndmask_b32_e32 v34, 0, v174, vcc
	v_ldexp_f32 v33, v33, v34
	s_and_saveexec_b64 s[46:47], s[4:5]
	ds_write_b32 v176, v33
	s_or_b64 exec, exec, s[46:47]
	v_pk_mul_f32 v[44:45], v[124:125], v[32:33]
	v_pk_add_f32 v[82:83], v[82:83], v[32:33] op_sel_hi:[1,0] neg_lo:[0,1] neg_hi:[0,1]
	v_add_u32_e32 v44, s83, v155
	v_pk_add_f32 v[136:137], v[136:137], v[32:33] op_sel_hi:[1,0] neg_lo:[0,1] neg_hi:[0,1]
	v_sub_f32_e32 v128, v128, v32
	v_sub_f32_e32 v129, v129, v32
	v_sub_f32_e32 v130, v130, v32
	v_sub_f32_e32 v131, v131, v32
	v_sub_f32_e32 v132, v132, v32
	v_sub_f32_e32 v133, v133, v32
	v_sub_f32_e32 v134, v134, v32
	v_sub_f32_e32 v135, v135, v32
	v_sub_f32_e32 v126, v126, v32
	v_sub_f32_e32 v127, v127, v32
	v_sub_f32_e32 v72, v72, v32
	v_sub_f32_e32 v73, v73, v32
	v_sub_f32_e32 v74, v74, v32
	v_sub_f32_e32 v75, v75, v32
	v_sub_f32_e32 v76, v76, v32
	v_sub_f32_e32 v77, v77, v32
	v_pk_add_f32 v[78:79], v[124:125], v[32:33]
	ds_read_b128 v[32:35], v44 offset:64
	ds_read_b128 v[36:39], v44 offset:96
	ds_read_b128 v[40:43], v44
	ds_read_b128 v[200:203], v44 offset:32
	v_mov_b32_e32 v79, v45
	v_pk_add_f32 v[46:47], v[78:79], 0 neg_lo:[1,1] neg_hi:[1,1]
	s_waitcnt lgkmcnt(2)
	v_pk_mul_f32 v[28:29], v[28:29], v[36:37]
	v_pk_mul_f32 v[24:25], v[24:25], v[32:33]
	s_waitcnt lgkmcnt(0)
	v_pk_mul_f32 v[20:21], v[20:21], v[200:201]
	v_pk_mul_f32 v[16:17], v[16:17], v[40:41]
	v_pk_mul_f32 v[12:13], v[12:13], v[36:37]
	v_pk_mul_f32 v[8:9], v[8:9], v[32:33]
	v_pk_mul_f32 v[4:5], v[4:5], v[200:201]
	v_pk_mul_f32 v[30:31], v[30:31], v[38:39]
	v_pk_mul_f32 v[26:27], v[26:27], v[34:35]
	v_pk_mul_f32 v[22:23], v[22:23], v[202:203]
	v_pk_mul_f32 v[18:19], v[18:19], v[42:43]
	v_pk_mul_f32 v[14:15], v[14:15], v[38:39]
	v_pk_mul_f32 v[10:11], v[10:11], v[34:35]
	v_pk_mul_f32 v[6:7], v[6:7], v[202:203]
	v_pk_mul_f32 v[2:3], v[2:3], v[42:43]
	v_pk_mul_f32 v[0:1], v[0:1], v[40:41]
	v_mov_b32_e32 v47, v46
	v_mov_b32_e32 v45, v46
	v_mov_b32_e32 v44, v46
	v_mov_b32_e32 v43, v46
	v_mov_b32_e32 v42, v46
	v_mov_b32_e32 v41, v46
	v_mov_b32_e32 v40, v46
	v_mov_b32_e32 v39, v46
	v_mov_b32_e32 v38, v46
	v_mov_b32_e32 v37, v46
	v_mov_b32_e32 v36, v46
	v_mov_b32_e32 v35, v46
	v_mov_b32_e32 v34, v46
	v_mov_b32_e32 v33, v46
	v_mov_b32_e32 v32, v46
	v_mov_b64_e32 v[124:125], v[78:79]

.LBB0_1057:
	s_add_i32 s40, s18, s6
	s_cmp_gt_i32 s47, 5
	s_cselect_b32 s41, s33, 0xa000
	s_add_i32 s40, s40, s41
	v_add_u32_e32 v130, s40, v153
	ds_read_b128 v[64:67], v130
	ds_read_b128 v[122:125], v130 offset:512
	s_waitcnt lgkmcnt(1)
	v_mfma_f32_32x32x16_bf16 v[48:63], v[64:67], v[82:85], v[32:47]
	v_mov_b64_e32 v[78:79], v[46:47]
	v_mov_b64_e32 v[76:77], v[44:45]
	v_mov_b64_e32 v[74:75], v[42:43]
	v_mov_b64_e32 v[72:73], v[40:41]
	v_mov_b64_e32 v[70:71], v[38:39]
	v_mov_b64_e32 v[68:69], v[36:37]
	v_mov_b64_e32 v[66:67], v[34:35]
	v_mov_b64_e32 v[64:65], v[32:33]
	s_waitcnt lgkmcnt(0)
	s_nop 0
	v_mfma_f32_32x32x16_bf16 v[64:79], v[122:125], v[82:85], v[64:79]
	ds_read_b128 v[122:125], v130 offset:2048
	ds_read_b128 v[126:129], v130 offset:2560
	s_waitcnt lgkmcnt(1)
	v_mfma_f32_32x32x16_bf16 v[48:63], v[122:125], v[86:89], v[48:63]
	s_waitcnt lgkmcnt(0)
	v_mfma_f32_32x32x16_bf16 v[64:79], v[126:129], v[86:89], v[64:79]
	ds_read_b128 v[122:125], v130 offset:4096
	ds_read_b128 v[126:129], v130 offset:4608
	s_waitcnt lgkmcnt(1)
	v_mfma_f32_32x32x16_bf16 v[48:63], v[122:125], v[90:93], v[48:63]
	s_waitcnt lgkmcnt(0)
	v_mfma_f32_32x32x16_bf16 v[64:79], v[126:129], v[90:93], v[64:79]
	ds_read_b128 v[122:125], v130 offset:6144
	ds_read_b128 v[126:129], v130 offset:6656
	s_waitcnt lgkmcnt(1)
	v_mfma_f32_32x32x16_bf16 v[48:63], v[122:125], v[94:97], v[48:63]
	s_waitcnt lgkmcnt(0)
	v_mfma_f32_32x32x16_bf16 v[64:79], v[126:129], v[94:97], v[64:79]
	s_nop 11
	v_add_u32_e32 v68, s73, v194
	v_add_u32_e32 v69, s73, v189
	v_add_u32_e32 v71, s73, v188
	v_add_u32_e32 v72, s73, v187
	v_add_u32_e32 v75, s73, v185
	v_add_u32_e32 v77, s73, v184
	v_add_u32_e32 v73, s73, v186
	v_add_u32_e32 v78, s73, v183
	ds_read_b32 v68, v68
	ds_read_b32 v70, v69
	ds_read_b32 v69, v71
	ds_read_b32 v71, v72
	ds_read_b32 v74, v73
	ds_read_b32 v76, v75
	ds_read_b32 v75, v77
	ds_read_b32 v77, v78
	v_add_u32_e32 v72, s73, v182
	v_add_u32_e32 v122, s73, v180
	v_add_u32_e32 v123, s73, v179
	v_add_u32_e32 v73, s73, v181
	v_add_u32_e32 v124, s73, v178
	v_add_u32_e32 v125, s73, v177
	v_add_u32_e32 v126, s73, v176
	v_add_u32_e32 v127, s73, v175
	ds_read_b32 v78, v72
	ds_read_b32 v79, v73
	ds_read_b32 v122, v122
	ds_read_b32 v123, v123
	ds_read_b32 v128, v124
	ds_read_b32 v129, v125
	ds_read_b32 v196, v126
	ds_read_b32 v197, v127
	v_add_u32_e32 v72, s73, v137
	v_add_u32_e32 v73, s73, v136
	v_add_u32_e32 v124, s73, v135
	v_add_u32_e32 v125, s73, v117
	ds_read_b32 v198, v72
	ds_read_b32 v199, v73
	ds_read_b32 v200, v124
	ds_read_b32 v201, v125
	s_waitcnt lgkmcnt(14)
	v_pk_add_f32 v[124:125], v[48:49], v[68:69]
	s_waitcnt lgkmcnt(13)
	v_pk_add_f32 v[126:127], v[50:51], v[74:75]
	v_add_u32_e32 v50, s40, v154
	v_pk_add_f32 v[72:73], v[64:65], v[70:71]
	s_waitcnt lgkmcnt(12)
	v_pk_add_f32 v[74:75], v[66:67], v[76:77]
	s_waitcnt lgkmcnt(10)
	v_pk_add_f32 v[130:131], v[52:53], v[78:79]
	s_waitcnt lgkmcnt(8)
	v_pk_add_f32 v[132:133], v[54:55], v[122:123]
	s_waitcnt lgkmcnt(6)
	v_pk_add_f32 v[128:129], v[56:57], v[128:129]
	s_waitcnt lgkmcnt(4)
	v_pk_add_f32 v[76:77], v[58:59], v[196:197]
	ds_read_b64_tr_b16 v[68:69], v50 offset:49152
	s_waitcnt lgkmcnt(3)
	v_pk_add_f32 v[122:123], v[60:61], v[198:199]
	s_waitcnt lgkmcnt(1)
	v_pk_add_f32 v[78:79], v[62:63], v[200:201]
	ds_read_b64_tr_b16 v[70:71], v50 offset:49664
	ds_read_b64_tr_b16 v[56:57], v50 offset:50176
	ds_read_b64_tr_b16 v[58:59], v50 offset:50688
	ds_read_b64_tr_b16 v[52:53], v50 offset:51200
	ds_read_b64_tr_b16 v[64:65], v50 offset:53248
	ds_read_b64_tr_b16 v[66:67], v50 offset:53760
	ds_read_b64_tr_b16 v[60:61], v50 offset:54272
	ds_read_b64_tr_b16 v[54:55], v50 offset:51712
	ds_read_b64_tr_b16 v[62:63], v50 offset:54784
	ds_read_b64_tr_b16 v[48:49], v50 offset:55296
	ds_read_b64_tr_b16 v[50:51], v50 offset:55808
	v_max_f32_e32 v195, 0xff800000, v124
	v_max3_f32 v195, v195, v125, v126
	v_max3_f32 v195, v195, v127, v130
	v_max3_f32 v195, v195, v131, v132
	v_max3_f32 v195, v195, v133, v128
	v_max3_f32 v195, v195, v129, v76
	v_max3_f32 v196, v72, s30, v73
	v_max3_f32 v195, v195, v77, v122
	v_max3_f32 v196, v196, v74, v75
	v_max3_f32 v195, v195, v123, v78
	v_max3_f32 v195, v195, v79, v196
	v_mov_b32_e32 v196, v195
	s_nop 1
	v_permlane32_swap_b32_e32 v195, v196
	v_max_f32_e32 v195, v195, v196
	v_cmp_lt_f32_e32 vcc, s48, v195
	s_cbranch_vccz .LBB0_1061
	v_max_f32_e32 v32, v195, v195
	v_max_f32_e32 v32, 0, v32
	v_cmp_lt_f32_e32 vcc, s49, v32
	s_nop 1
	v_cndmask_b32_e32 v33, 0, v173, vcc
	v_sub_f32_e32 v33, v33, v32
	v_exp_f32_e32 v33, v33
	v_cndmask_b32_e32 v34, 0, v174, vcc
	v_ldexp_f32 v33, v33, v34
	s_and_saveexec_b64 s[40:41], s[4:5]
	ds_write_b32 v134, v33
	s_or_b64 exec, exec, s[40:41]
	v_pk_mul_f32 v[44:45], v[120:121], v[32:33]
	v_pk_add_f32 v[72:73], v[72:73], v[32:33] op_sel_hi:[1,0] neg_lo:[0,1] neg_hi:[0,1]
	v_add_u32_e32 v44, s46, v155
	v_pk_add_f32 v[74:75], v[74:75], v[32:33] op_sel_hi:[1,0] neg_lo:[0,1] neg_hi:[0,1]
	v_sub_f32_e32 v124, v124, v32
	v_sub_f32_e32 v125, v125, v32
	v_sub_f32_e32 v126, v126, v32
	v_sub_f32_e32 v127, v127, v32
	v_sub_f32_e32 v130, v130, v32
	v_sub_f32_e32 v131, v131, v32
	v_sub_f32_e32 v132, v132, v32
	v_sub_f32_e32 v133, v133, v32
	v_sub_f32_e32 v128, v128, v32
	v_sub_f32_e32 v129, v129, v32
	v_sub_f32_e32 v76, v76, v32
	v_sub_f32_e32 v77, v77, v32
	v_sub_f32_e32 v122, v122, v32
	v_sub_f32_e32 v123, v123, v32
	v_sub_f32_e32 v78, v78, v32
	v_sub_f32_e32 v79, v79, v32
	v_pk_add_f32 v[200:201], v[120:121], v[32:33]
	ds_read_b128 v[32:35], v44 offset:64
	ds_read_b128 v[36:39], v44 offset:96
	ds_read_b128 v[40:43], v44
	ds_read_b128 v[196:199], v44 offset:32
	v_mov_b32_e32 v201, v45
	v_pk_add_f32 v[46:47], v[200:201], 0 neg_lo:[1,1] neg_hi:[1,1]
	s_waitcnt lgkmcnt(2)
	v_pk_mul_f32 v[28:29], v[28:29], v[36:37]
	v_pk_mul_f32 v[24:25], v[24:25], v[32:33]
	s_waitcnt lgkmcnt(0)
	v_pk_mul_f32 v[20:21], v[20:21], v[196:197]
	v_pk_mul_f32 v[16:17], v[16:17], v[40:41]
	v_pk_mul_f32 v[12:13], v[12:13], v[36:37]
	v_pk_mul_f32 v[8:9], v[8:9], v[32:33]
	v_pk_mul_f32 v[4:5], v[4:5], v[196:197]
	v_pk_mul_f32 v[30:31], v[30:31], v[38:39]
	v_pk_mul_f32 v[26:27], v[26:27], v[34:35]
	v_pk_mul_f32 v[22:23], v[22:23], v[198:199]
	v_pk_mul_f32 v[18:19], v[18:19], v[42:43]
	v_pk_mul_f32 v[14:15], v[14:15], v[38:39]
	v_pk_mul_f32 v[10:11], v[10:11], v[34:35]
	v_pk_mul_f32 v[6:7], v[6:7], v[198:199]
	v_pk_mul_f32 v[2:3], v[2:3], v[42:43]
	v_pk_mul_f32 v[0:1], v[0:1], v[40:41]
	v_mov_b32_e32 v47, v46
	v_mov_b32_e32 v45, v46
	v_mov_b32_e32 v44, v46
	v_mov_b32_e32 v43, v46
	v_mov_b32_e32 v42, v46
	v_mov_b32_e32 v41, v46
	v_mov_b32_e32 v40, v46
	v_mov_b32_e32 v39, v46
	v_mov_b32_e32 v38, v46
	v_mov_b32_e32 v37, v46
	v_mov_b32_e32 v36, v46
	v_mov_b32_e32 v35, v46
	v_mov_b32_e32 v34, v46
	v_mov_b32_e32 v33, v46
	v_mov_b32_e32 v32, v46
	v_mov_b64_e32 v[120:121], v[200:201]
